# MFMA order: k order flipped in every second accumulator chain so every consecutive MFMA pair shares one operand register set (C inside a chain, A or B across chains); on top of v62
# speedup vs baseline: 1.0014x; 1.0014x over previous
; #define PG8_STAGEX(rs, bufoff, soff, voff) do { _Pragma("unroll") for (int _i = 0; _i < 2; ++_i) \
;         __builtin_amdgcn_raw_ptr_buffer_load_lds(rs, (LAS unsigned*)(lds + (bufoff) + ldsw + _i * 8192), 16, (voff)[_i], (soff), 0, 0); } while (0)
; #define PG8_LDA(dst, b, h) do { _Pragma("unroll") for (int m = 0; m < 4; ++m) _Pragma("unroll") for (int k = 0; k < 2; ++k) dst[m][k] = *(const LAS bf16x8*)(lds + PG8_SA(b, h) + aoff + m * 2048 + k * 1024); } while (0)
; #define PG8_LDB(dst, b, h) do { _Pragma("unroll") for (int n = 0; n < 2; ++n) _Pragma("unroll") for (int k = 0; k < 2; ++k) dst[n][k] = *(const LAS bf16x8*)(lds + PG8_SB(b, h) + boff + n * 2048 + k * 1024); } while (0)
; #define PG8_WAIT_V(n) asm volatile("s_waitcnt vmcnt(" #n ")" ::: "memory")
; #define PG8_WAIT_L(n) asm volatile("s_waitcnt lgkmcnt(" #n ")" ::: "memory")
; #define PG8_BAR __builtin_amdgcn_s_barrier()
; #define PG8_SCHED __builtin_amdgcn_sched_barrier(0)
;     ...
;             const unsigned a1 = cA + (unsigned)(t + 1) * kstep;
;             const unsigned a2 = last ? nA : cA + (unsigned)(t + 2) * kstep, b2 = last ? nB : cB + (unsigned)(t + 2) * kstep;
;             const unsigned a3 = a2 + kstep, b3 = b2 + kstep;
;             PG8_LDB(B0, 0, 0); PG8_LDB(B1, 0, 1); PG8_SCHED; PG8_LDA(At, 0, 0); PG8_STAGEX(rsA, PG8_SA(1, 1), a1 + hstepA, voffA);
;             PG8_WAIT_V(8); PG8_WAIT_L(0); PG8_BAR; PG8_MMA(0, 0, At, B0); PG8_MMA(0, 1, At, B1); PG8_BAR; PG8_SCHED;
;             PG8_LDA(At, 0, 1); PG8_STAGEX(rsB, PG8_SB(0, 0), b2, voffB); PG8_STAGEX(rsB, PG8_SB(0, 1), b2 + hstepB, voffB); PG8_STAGEX(rsA, PG8_SA(0, 0), a2, voffA);
;             PG8_WAIT_V(8); PG8_WAIT_L(0); PG8_BAR; PG8_MMA(1, 0, At, B0); PG8_MMA(1, 1, At, B1); PG8_BAR; PG8_SCHED;
.LBB0_223:
	v_add_u32_e32 v102, 0x10000, v172
	v_add_u32_e32 v146, 0x14000, v172
	ds_read_b128 v[82:85], v102
	ds_read_b128 v[86:89], v102 offset:1024
	ds_read_b128 v[98:101], v102 offset:2048
	ds_read_b128 v[102:105], v102 offset:3072
	ds_read_b128 v[150:153], v146
	ds_read_b128 v[154:157], v146 offset:1024
	ds_read_b128 v[182:185], v146 offset:2048
	ds_read_b128 v[186:189], v146 offset:3072
	s_add_i32 s42, s50, 0xfff80080
	s_cmp_eq_u32 s52, 28
	s_cselect_b32 s55, s30, s42
	s_cselect_b32 s54, s31, s51
	s_or_b32 s53, s55, 0x80
	s_mov_b32 m0, s22
	ds_read_b128 v[190:193], v173
	ds_read_b128 v[194:197], v173 offset:1024
	ds_read_b128 v[198:201], v173 offset:2048
	ds_read_b128 v[202:205], v173 offset:3072
	ds_read_b128 v[206:209], v173 offset:4096
	ds_read_b128 v[210:213], v173 offset:5120
	ds_read_b128 v[214:217], v173 offset:6144
	ds_read_b128 v[218:221], v173 offset:7168
	buffer_load_dwordx4 v159, s[76:79], s50 offen lds
	s_mov_b32 m0, s23
	s_nop 0
	buffer_load_dwordx4 v163, s[76:79], s50 offen lds
	s_waitcnt vmcnt(8)
	s_waitcnt lgkmcnt(0)
	s_setprio 1
	s_barrier
	v_mfma_f32_16x16x32_bf16 v[142:145], v[82:85], v[190:193], v[142:145]
	v_mfma_f32_16x16x32_bf16 v[142:145], v[86:89], v[194:197], v[142:145]
	v_mfma_f32_16x16x32_bf16 v[134:137], v[102:105], v[194:197], v[134:137]
	v_mfma_f32_16x16x32_bf16 v[134:137], v[98:101], v[190:193], v[134:137]
	v_mfma_f32_16x16x32_bf16 v[118:121], v[98:101], v[198:201], v[118:121]
	v_mfma_f32_16x16x32_bf16 v[118:121], v[102:105], v[202:205], v[118:121]
	v_mfma_f32_16x16x32_bf16 v[126:129], v[86:89], v[202:205], v[126:129]
	v_mfma_f32_16x16x32_bf16 v[126:129], v[82:85], v[198:201], v[126:129]
	v_mfma_f32_16x16x32_bf16 v[110:113], v[82:85], v[206:209], v[110:113]
	v_mfma_f32_16x16x32_bf16 v[110:113], v[86:89], v[210:213], v[110:113]
	v_mfma_f32_16x16x32_bf16 v[94:97], v[102:105], v[210:213], v[94:97]
	v_mfma_f32_16x16x32_bf16 v[94:97], v[98:101], v[206:209], v[94:97]
	v_mfma_f32_16x16x32_bf16 v[70:73], v[98:101], v[214:217], v[70:73]
	v_mfma_f32_16x16x32_bf16 v[70:73], v[102:105], v[218:221], v[70:73]
	v_mfma_f32_16x16x32_bf16 v[78:81], v[86:89], v[218:221], v[78:81]
	v_mfma_f32_16x16x32_bf16 v[78:81], v[82:85], v[214:217], v[78:81]
	v_mfma_f32_16x16x32_bf16 v[138:141], v[150:153], v[190:193], v[138:141]
	v_mfma_f32_16x16x32_bf16 v[138:141], v[154:157], v[194:197], v[138:141]
	v_mfma_f32_16x16x32_bf16 v[130:133], v[186:189], v[194:197], v[130:133]
	v_mfma_f32_16x16x32_bf16 v[130:133], v[182:185], v[190:193], v[130:133]
	v_mfma_f32_16x16x32_bf16 v[114:117], v[182:185], v[198:201], v[114:117]
	v_mfma_f32_16x16x32_bf16 v[114:117], v[186:189], v[202:205], v[114:117]
	v_mfma_f32_16x16x32_bf16 v[122:125], v[154:157], v[202:205], v[122:125]
	v_mfma_f32_16x16x32_bf16 v[122:125], v[150:153], v[198:201], v[122:125]
	v_mfma_f32_16x16x32_bf16 v[106:109], v[150:153], v[206:209], v[106:109]
	v_mfma_f32_16x16x32_bf16 v[106:109], v[154:157], v[210:213], v[106:109]
	v_mfma_f32_16x16x32_bf16 v[90:93], v[186:189], v[210:213], v[90:93]
	v_mfma_f32_16x16x32_bf16 v[90:93], v[182:185], v[206:209], v[90:93]
	v_mfma_f32_16x16x32_bf16 v[66:69], v[182:185], v[214:217], v[66:69]
	v_mfma_f32_16x16x32_bf16 v[66:69], v[186:189], v[218:221], v[66:69]
	v_mfma_f32_16x16x32_bf16 v[74:77], v[154:157], v[218:221], v[74:77]
	v_mfma_f32_16x16x32_bf16 v[74:77], v[150:153], v[214:217], v[74:77]
	s_barrier
	s_setprio 0
	s_mov_b32 m0, s9
	s_mov_b32 s42, s78
	s_mov_b32 s43, s79
	ds_read_b128 v[190:193], v173 offset:16384
	ds_read_b128 v[194:197], v173 offset:17408
	ds_read_b128 v[198:201], v173 offset:18432
	ds_read_b128 v[202:205], v173 offset:19456
	ds_read_b128 v[206:209], v173 offset:20480
	ds_read_b128 v[210:213], v173 offset:21504
	ds_read_b128 v[214:217], v173 offset:22528
	ds_read_b128 v[218:221], v173 offset:23552
	buffer_load_dwordx4 v161, s[40:43], s54 offen lds
	s_mov_b32 m0, s10
	s_add_i32 s56, s54, 0x80000
	buffer_load_dwordx4 v165, s[40:43], s54 offen lds
	s_mov_b32 m0, s11
	s_nop 0
	buffer_load_dwordx4 v161, s[40:43], s56 offen lds
	s_mov_b32 m0, s12
	s_nop 0
	buffer_load_dwordx4 v165, s[40:43], s56 offen lds
	s_mov_b32 m0, s8
	s_nop 0
	buffer_load_dwordx4 v159, s[76:79], s55 offen lds
	s_mov_b32 m0, s13
	s_nop 0
	buffer_load_dwordx4 v163, s[76:79], s55 offen lds
	s_waitcnt vmcnt(8)
	s_waitcnt lgkmcnt(0)
	s_setprio 1
	s_barrier
	v_mfma_f32_16x16x32_bf16 v[62:65], v[82:85], v[190:193], v[62:65]
	v_mfma_f32_16x16x32_bf16 v[62:65], v[86:89], v[194:197], v[62:65]
	v_mfma_f32_16x16x32_bf16 v[54:57], v[102:105], v[194:197], v[54:57]
	v_mfma_f32_16x16x32_bf16 v[54:57], v[98:101], v[190:193], v[54:57]
	v_mfma_f32_16x16x32_bf16 v[38:41], v[98:101], v[198:201], v[38:41]
	v_mfma_f32_16x16x32_bf16 v[38:41], v[102:105], v[202:205], v[38:41]
	v_mfma_f32_16x16x32_bf16 v[46:49], v[86:89], v[202:205], v[46:49]
	v_mfma_f32_16x16x32_bf16 v[46:49], v[82:85], v[198:201], v[46:49]
	v_mfma_f32_16x16x32_bf16 v[30:33], v[82:85], v[206:209], v[30:33]
	v_mfma_f32_16x16x32_bf16 v[30:33], v[86:89], v[210:213], v[30:33]
	v_mfma_f32_16x16x32_bf16 v[22:25], v[102:105], v[210:213], v[22:25]
	v_mfma_f32_16x16x32_bf16 v[22:25], v[98:101], v[206:209], v[22:25]
	v_mfma_f32_16x16x32_bf16 v[6:9], v[98:101], v[214:217], v[6:9]
	v_mfma_f32_16x16x32_bf16 v[6:9], v[102:105], v[218:221], v[6:9]
	v_mfma_f32_16x16x32_bf16 v[14:17], v[86:89], v[218:221], v[14:17]
	v_mfma_f32_16x16x32_bf16 v[14:17], v[82:85], v[214:217], v[14:17]
	v_mfma_f32_16x16x32_bf16 v[58:61], v[150:153], v[190:193], v[58:61]
	v_mfma_f32_16x16x32_bf16 v[58:61], v[154:157], v[194:197], v[58:61]
	v_mfma_f32_16x16x32_bf16 v[50:53], v[186:189], v[194:197], v[50:53]
	v_mfma_f32_16x16x32_bf16 v[50:53], v[182:185], v[190:193], v[50:53]
	v_mfma_f32_16x16x32_bf16 v[34:37], v[182:185], v[198:201], v[34:37]
	v_mfma_f32_16x16x32_bf16 v[34:37], v[186:189], v[202:205], v[34:37]
	v_mfma_f32_16x16x32_bf16 v[42:45], v[154:157], v[202:205], v[42:45]
	v_mfma_f32_16x16x32_bf16 v[42:45], v[150:153], v[198:201], v[42:45]
	v_mfma_f32_16x16x32_bf16 v[26:29], v[150:153], v[206:209], v[26:29]
	v_mfma_f32_16x16x32_bf16 v[26:29], v[154:157], v[210:213], v[26:29]
	v_mfma_f32_16x16x32_bf16 v[18:21], v[186:189], v[210:213], v[18:21]
	v_mfma_f32_16x16x32_bf16 v[18:21], v[182:185], v[206:209], v[18:21]
	v_mfma_f32_16x16x32_bf16 v[2:5], v[182:185], v[214:217], v[2:5]
	v_mfma_f32_16x16x32_bf16 v[2:5], v[186:189], v[218:221], v[2:5]
	v_mfma_f32_16x16x32_bf16 v[10:13], v[154:157], v[218:221], v[10:13]
	v_mfma_f32_16x16x32_bf16 v[10:13], v[150:153], v[214:217], v[10:13]
	s_barrier
; #define PG8_STAGEX(rs, bufoff, soff, voff) do { _Pragma("unroll") for (int _i = 0; _i < 2; ++_i) \
;         __builtin_amdgcn_raw_ptr_buffer_load_lds(rs, (LAS unsigned*)(lds + (bufoff) + ldsw + _i * 8192), 16, (voff)[_i], (soff), 0, 0); } while (0)
; #define PG8_LDA(dst, b, h) do { _Pragma("unroll") for (int m = 0; m < 4; ++m) _Pragma("unroll") for (int k = 0; k < 2; ++k) dst[m][k] = *(const LAS bf16x8*)(lds + PG8_SA(b, h) + aoff + m * 2048 + k * 1024); } while (0)
; #define PG8_LDB(dst, b, h) do { _Pragma("unroll") for (int n = 0; n < 2; ++n) _Pragma("unroll") for (int k = 0; k < 2; ++k) dst[n][k] = *(const LAS bf16x8*)(lds + PG8_SB(b, h) + boff + n * 2048 + k * 1024); } while (0)
; #define PG8_WAIT_V(n) asm volatile("s_waitcnt vmcnt(" #n ")" ::: "memory")
; #define PG8_WAIT_L(n) asm volatile("s_waitcnt lgkmcnt(" #n ")" ::: "memory")
; #define PG8_BAR __builtin_amdgcn_s_barrier()
; #define PG8_SCHED __builtin_amdgcn_sched_barrier(0)
;     ...
;             PG8_LDB(B0, 1, 0); PG8_LDB(B1, 1, 1); PG8_SCHED; PG8_LDA(At, 1, 0); PG8_STAGEX(rsA, PG8_SA(0, 1), a2 + hstepA, voffA);
;             PG8_WAIT_V(8); PG8_WAIT_L(0); PG8_BAR; PG8_MMA(0, 0, At, B0); PG8_MMA(0, 1, At, B1); PG8_BAR; PG8_SCHED;
;             PG8_LDA(At, 1, 1); PG8_STAGEX(rsB, PG8_SB(1, 0), b3, voffB); PG8_STAGEX(rsB, PG8_SB(1, 1), b3 + hstepB, voffB); PG8_STAGEX(rsA, PG8_SA(1, 0), a3, voffA);
;             PG8_WAIT_V(8); PG8_WAIT_L(0); PG8_BAR; PG8_MMA(1, 0, At, B0); PG8_MMA(1, 1, At, B1); PG8_BAR; PG8_SCHED;
;         }
;     ...
;         if (wr == 0) PG8_BAR;
	s_setprio 0
	v_add_u32_e32 v102, 0x18000, v172
	v_add_u32_e32 v146, 0x1c000, v172
	ds_read_b128 v[82:85], v102
	ds_read_b128 v[86:89], v102 offset:1024
	ds_read_b128 v[98:101], v102 offset:2048
	ds_read_b128 v[102:105], v102 offset:3072
	ds_read_b128 v[150:153], v146
	ds_read_b128 v[154:157], v146 offset:1024
	ds_read_b128 v[182:185], v146 offset:2048
	ds_read_b128 v[186:189], v146 offset:3072
	s_add_i32 s55, s55, 0x80000
	s_mov_b32 m0, s14
	ds_read_b128 v[190:193], v173 offset:32768
	ds_read_b128 v[194:197], v173 offset:33792
	ds_read_b128 v[198:201], v173 offset:34816
	ds_read_b128 v[202:205], v173 offset:35840
	ds_read_b128 v[206:209], v173 offset:36864
	ds_read_b128 v[210:213], v173 offset:37888
	ds_read_b128 v[214:217], v173 offset:38912
	ds_read_b128 v[218:221], v173 offset:39936
	buffer_load_dwordx4 v159, s[76:79], s55 offen lds
	s_mov_b32 m0, s15
	s_nop 0
	buffer_load_dwordx4 v163, s[76:79], s55 offen lds
	s_waitcnt vmcnt(8)
	s_waitcnt lgkmcnt(0)
	s_setprio 1
	s_barrier
	v_mfma_f32_16x16x32_bf16 v[142:145], v[82:85], v[190:193], v[142:145]
	v_mfma_f32_16x16x32_bf16 v[142:145], v[86:89], v[194:197], v[142:145]
	v_mfma_f32_16x16x32_bf16 v[134:137], v[102:105], v[194:197], v[134:137]
	v_mfma_f32_16x16x32_bf16 v[134:137], v[98:101], v[190:193], v[134:137]
	v_mfma_f32_16x16x32_bf16 v[118:121], v[98:101], v[198:201], v[118:121]
	v_mfma_f32_16x16x32_bf16 v[118:121], v[102:105], v[202:205], v[118:121]
	v_mfma_f32_16x16x32_bf16 v[126:129], v[86:89], v[202:205], v[126:129]
	v_mfma_f32_16x16x32_bf16 v[126:129], v[82:85], v[198:201], v[126:129]
	v_mfma_f32_16x16x32_bf16 v[110:113], v[82:85], v[206:209], v[110:113]
	v_mfma_f32_16x16x32_bf16 v[110:113], v[86:89], v[210:213], v[110:113]
	v_mfma_f32_16x16x32_bf16 v[94:97], v[102:105], v[210:213], v[94:97]
	v_mfma_f32_16x16x32_bf16 v[94:97], v[98:101], v[206:209], v[94:97]
	v_mfma_f32_16x16x32_bf16 v[70:73], v[98:101], v[214:217], v[70:73]
	v_mfma_f32_16x16x32_bf16 v[70:73], v[102:105], v[218:221], v[70:73]
	v_mfma_f32_16x16x32_bf16 v[78:81], v[86:89], v[218:221], v[78:81]
	v_mfma_f32_16x16x32_bf16 v[78:81], v[82:85], v[214:217], v[78:81]
	v_mfma_f32_16x16x32_bf16 v[138:141], v[150:153], v[190:193], v[138:141]
	v_mfma_f32_16x16x32_bf16 v[138:141], v[154:157], v[194:197], v[138:141]
	v_mfma_f32_16x16x32_bf16 v[130:133], v[186:189], v[194:197], v[130:133]
	v_mfma_f32_16x16x32_bf16 v[130:133], v[182:185], v[190:193], v[130:133]
	v_mfma_f32_16x16x32_bf16 v[114:117], v[182:185], v[198:201], v[114:117]
	v_mfma_f32_16x16x32_bf16 v[114:117], v[186:189], v[202:205], v[114:117]
	v_mfma_f32_16x16x32_bf16 v[122:125], v[154:157], v[202:205], v[122:125]
	v_mfma_f32_16x16x32_bf16 v[122:125], v[150:153], v[198:201], v[122:125]
	v_mfma_f32_16x16x32_bf16 v[106:109], v[150:153], v[206:209], v[106:109]
	v_mfma_f32_16x16x32_bf16 v[106:109], v[154:157], v[210:213], v[106:109]
	v_mfma_f32_16x16x32_bf16 v[90:93], v[186:189], v[210:213], v[90:93]
	v_mfma_f32_16x16x32_bf16 v[90:93], v[182:185], v[206:209], v[90:93]
	v_mfma_f32_16x16x32_bf16 v[66:69], v[182:185], v[214:217], v[66:69]
	v_mfma_f32_16x16x32_bf16 v[66:69], v[186:189], v[218:221], v[66:69]
	v_mfma_f32_16x16x32_bf16 v[74:77], v[154:157], v[218:221], v[74:77]
	v_mfma_f32_16x16x32_bf16 v[74:77], v[150:153], v[214:217], v[74:77]
	s_barrier
	s_setprio 0
	s_mov_b32 m0, s16
	s_or_b32 s55, s54, 0x80
	ds_read_b128 v[190:193], v173 offset:49152
	ds_read_b128 v[194:197], v173 offset:50176
	ds_read_b128 v[198:201], v173 offset:51200
	ds_read_b128 v[202:205], v173 offset:52224
	ds_read_b128 v[206:209], v173 offset:53248
	ds_read_b128 v[210:213], v173 offset:54272
	ds_read_b128 v[214:217], v173 offset:55296
	ds_read_b128 v[218:221], v173 offset:56320
	buffer_load_dwordx4 v161, s[40:43], s55 offen lds
	s_mov_b32 m0, s17
	s_add_i32 s54, s54, 0x80080
	buffer_load_dwordx4 v165, s[40:43], s55 offen lds
	s_mov_b32 m0, s20
	s_nop 0
	buffer_load_dwordx4 v161, s[40:43], s54 offen lds
	s_mov_b32 m0, s21
	s_nop 0
	buffer_load_dwordx4 v165, s[40:43], s54 offen lds
	s_mov_b32 m0, s18
	s_nop 0
	buffer_load_dwordx4 v159, s[76:79], s53 offen lds
	s_mov_b32 m0, s19
	s_nop 0
	buffer_load_dwordx4 v163, s[76:79], s53 offen lds
	s_waitcnt vmcnt(8)
	s_waitcnt lgkmcnt(0)
	s_setprio 1
	s_barrier
	v_mfma_f32_16x16x32_bf16 v[62:65], v[82:85], v[190:193], v[62:65]
	v_mfma_f32_16x16x32_bf16 v[62:65], v[86:89], v[194:197], v[62:65]
	v_mfma_f32_16x16x32_bf16 v[54:57], v[102:105], v[194:197], v[54:57]
	v_mfma_f32_16x16x32_bf16 v[54:57], v[98:101], v[190:193], v[54:57]
	v_mfma_f32_16x16x32_bf16 v[38:41], v[98:101], v[198:201], v[38:41]
	v_mfma_f32_16x16x32_bf16 v[38:41], v[102:105], v[202:205], v[38:41]
	v_mfma_f32_16x16x32_bf16 v[46:49], v[86:89], v[202:205], v[46:49]
	v_mfma_f32_16x16x32_bf16 v[46:49], v[82:85], v[198:201], v[46:49]
	v_mfma_f32_16x16x32_bf16 v[30:33], v[82:85], v[206:209], v[30:33]
	v_mfma_f32_16x16x32_bf16 v[30:33], v[86:89], v[210:213], v[30:33]
	v_mfma_f32_16x16x32_bf16 v[22:25], v[102:105], v[210:213], v[22:25]
	v_mfma_f32_16x16x32_bf16 v[22:25], v[98:101], v[206:209], v[22:25]
	v_mfma_f32_16x16x32_bf16 v[6:9], v[98:101], v[214:217], v[6:9]
	v_mfma_f32_16x16x32_bf16 v[6:9], v[102:105], v[218:221], v[6:9]
	v_mfma_f32_16x16x32_bf16 v[14:17], v[86:89], v[218:221], v[14:17]
	v_mfma_f32_16x16x32_bf16 v[14:17], v[82:85], v[214:217], v[14:17]
	v_mfma_f32_16x16x32_bf16 v[58:61], v[150:153], v[190:193], v[58:61]
	v_mfma_f32_16x16x32_bf16 v[58:61], v[154:157], v[194:197], v[58:61]
	v_mfma_f32_16x16x32_bf16 v[50:53], v[186:189], v[194:197], v[50:53]
	v_mfma_f32_16x16x32_bf16 v[50:53], v[182:185], v[190:193], v[50:53]
	v_mfma_f32_16x16x32_bf16 v[34:37], v[182:185], v[198:201], v[34:37]
	v_mfma_f32_16x16x32_bf16 v[34:37], v[186:189], v[202:205], v[34:37]
	v_mfma_f32_16x16x32_bf16 v[42:45], v[154:157], v[202:205], v[42:45]
	v_mfma_f32_16x16x32_bf16 v[42:45], v[150:153], v[198:201], v[42:45]
	v_mfma_f32_16x16x32_bf16 v[26:29], v[150:153], v[206:209], v[26:29]
	v_mfma_f32_16x16x32_bf16 v[26:29], v[154:157], v[210:213], v[26:29]
	v_mfma_f32_16x16x32_bf16 v[18:21], v[186:189], v[210:213], v[18:21]
	v_mfma_f32_16x16x32_bf16 v[18:21], v[182:185], v[206:209], v[18:21]
	v_mfma_f32_16x16x32_bf16 v[2:5], v[182:185], v[214:217], v[2:5]
	v_mfma_f32_16x16x32_bf16 v[2:5], v[186:189], v[218:221], v[2:5]
	v_mfma_f32_16x16x32_bf16 v[10:13], v[154:157], v[218:221], v[10:13]
	v_mfma_f32_16x16x32_bf16 v[10:13], v[150:153], v[214:217], v[10:13]
	s_barrier
	s_setprio 0
	s_add_i32 s52, s52, 2
	s_addk_i32 s50, 0x100
	s_addk_i32 s51, 0x100
	s_cmp_gt_u32 s52, 29
	s_cbranch_scc0 .LBB0_223
	s_and_b64 vcc, exec, s[46:47]
	s_cbranch_vccz .LBB0_226
	s_barrier

; #define PG8_STAGEX(rs, bufoff, soff, voff) do { _Pragma("unroll") for (int _i = 0; _i < 2; ++_i) \
;         __builtin_amdgcn_raw_ptr_buffer_load_lds(rs, (LAS unsigned*)(lds + (bufoff) + ldsw + _i * 8192), 16, (voff)[_i], (soff), 0, 0); } while (0)
; #define PG8_LDA(dst, b, h) do { _Pragma("unroll") for (int m = 0; m < 4; ++m) _Pragma("unroll") for (int k = 0; k < 2; ++k) dst[m][k] = *(const LAS bf16x8*)(lds + PG8_SA(b, h) + aoff + m * 2048 + k * 1024); } while (0)
; #define PG8_LDB(dst, b, h) do { _Pragma("unroll") for (int n = 0; n < 2; ++n) _Pragma("unroll") for (int k = 0; k < 2; ++k) dst[n][k] = *(const LAS bf16x8*)(lds + PG8_SB(b, h) + boff + n * 2048 + k * 1024); } while (0)
; #define PG8_WAIT_V(n) asm volatile("s_waitcnt vmcnt(" #n ")" ::: "memory")
; #define PG8_WAIT_L(n) asm volatile("s_waitcnt lgkmcnt(" #n ")" ::: "memory")
; #define PG8_BAR __builtin_amdgcn_s_barrier()
; #define PG8_SCHED __builtin_amdgcn_sched_barrier(0)
;     ...
;             for (int t = 0; t < nt; t += 2) {
;                 const bool last = (t == nt - 2);
;                 const unsigned a1 = cA + (unsigned)(t + 1) * kstep;
;                 const unsigned a2 = last ? nA : cA + (unsigned)(t + 2) * kstep, b2 = last ? nB : cB + (unsigned)(t + 2) * kstep;
;                 const unsigned a3 = a2 + kstep, b3 = b2 + kstep;
;                 if (w0) { PG8_LDB(B0, 0, 0); PG8_LDB(B1, 0, 1); PG8_SCHED; PG8_LDA(At, 0, 0); }
;                 PG8_WAIT_L(0); PG8_BAR; if (w0) { PG8_MMA(0, 0, At, B0); PG8_MMA(0, 1, At, B1); } PG8_BAR; PG8_SCHED;
;                 PG8_STAGEX(rsB, PG8_SB(0, 0), b2, voffB); PG8_STAGEX(rsB, PG8_SB(0, 1), b2 + hstepB, voffB); PG8_STAGEX(rsA, PG8_SA(0, 0), a2, voffA);
;                 PG8_WAIT_V(6); PG8_BAR; PG8_BAR; PG8_SCHED;
.LBB0_240:
	v_add_u32_e32 v86, 0x10000, v72
	v_add_u32_e32 v102, 0x14000, v72
	ds_read_b128 v[74:77], v86
	ds_read_b128 v[78:81], v86 offset:1024
	ds_read_b128 v[82:85], v86 offset:2048
	ds_read_b128 v[86:89], v86 offset:3072
	ds_read_b128 v[90:93], v102
	ds_read_b128 v[94:97], v102 offset:1024
	ds_read_b128 v[98:101], v102 offset:2048
	ds_read_b128 v[102:105], v102 offset:3072
	s_cmp_lg_u32 s27, 28
	s_cselect_b32 s28, s26, 0
	s_add_i32 s29, s28, s17
	s_or_b32 s30, s29, 0x80
	s_add_i32 s28, s28, s11
	ds_read_b128 v[106:109], v73
	ds_read_b128 v[110:113], v73 offset:1024
	ds_read_b128 v[114:117], v73 offset:2048
	ds_read_b128 v[118:121], v73 offset:3072
	ds_read_b128 v[122:125], v73 offset:4096
	ds_read_b128 v[126:129], v73 offset:5120
	ds_read_b128 v[130:133], v73 offset:6144
	ds_read_b128 v[134:137], v73 offset:7168
	s_waitcnt lgkmcnt(0)
	s_setprio 1
	s_barrier
	v_mfma_f32_16x16x32_bf16 v[62:65], v[74:77], v[106:109], v[62:65]
	v_mfma_f32_16x16x32_bf16 v[62:65], v[78:81], v[110:113], v[62:65]
	v_mfma_f32_16x16x32_bf16 v[58:61], v[86:89], v[110:113], v[58:61]
	v_mfma_f32_16x16x32_bf16 v[58:61], v[82:85], v[106:109], v[58:61]
	v_mfma_f32_16x16x32_bf16 v[38:41], v[82:85], v[114:117], v[38:41]
	v_mfma_f32_16x16x32_bf16 v[38:41], v[86:89], v[118:121], v[38:41]
	v_mfma_f32_16x16x32_bf16 v[54:57], v[78:81], v[118:121], v[54:57]
	v_mfma_f32_16x16x32_bf16 v[54:57], v[74:77], v[114:117], v[54:57]
	v_mfma_f32_16x16x32_bf16 v[30:33], v[74:77], v[122:125], v[30:33]
	v_mfma_f32_16x16x32_bf16 v[30:33], v[78:81], v[126:129], v[30:33]
	v_mfma_f32_16x16x32_bf16 v[22:25], v[86:89], v[126:129], v[22:25]
	v_mfma_f32_16x16x32_bf16 v[22:25], v[82:85], v[122:125], v[22:25]
	v_mfma_f32_16x16x32_bf16 v[6:9], v[82:85], v[130:133], v[6:9]
	v_mfma_f32_16x16x32_bf16 v[6:9], v[86:89], v[134:137], v[6:9]
	v_mfma_f32_16x16x32_bf16 v[14:17], v[78:81], v[134:137], v[14:17]
	v_mfma_f32_16x16x32_bf16 v[14:17], v[74:77], v[130:133], v[14:17]
	v_mfma_f32_16x16x32_bf16 v[50:53], v[90:93], v[106:109], v[50:53]
	v_mfma_f32_16x16x32_bf16 v[50:53], v[94:97], v[110:113], v[50:53]
	v_mfma_f32_16x16x32_bf16 v[46:49], v[102:105], v[110:113], v[46:49]
	v_mfma_f32_16x16x32_bf16 v[46:49], v[98:101], v[106:109], v[46:49]
	v_mfma_f32_16x16x32_bf16 v[34:37], v[98:101], v[114:117], v[34:37]
	v_mfma_f32_16x16x32_bf16 v[34:37], v[102:105], v[118:121], v[34:37]
	v_mfma_f32_16x16x32_bf16 v[42:45], v[94:97], v[118:121], v[42:45]
	v_mfma_f32_16x16x32_bf16 v[42:45], v[90:93], v[114:117], v[42:45]
	v_mfma_f32_16x16x32_bf16 v[26:29], v[90:93], v[122:125], v[26:29]
	v_mfma_f32_16x16x32_bf16 v[26:29], v[94:97], v[126:129], v[26:29]
	v_mfma_f32_16x16x32_bf16 v[18:21], v[102:105], v[126:129], v[18:21]
	v_mfma_f32_16x16x32_bf16 v[18:21], v[98:101], v[122:125], v[18:21]
	v_mfma_f32_16x16x32_bf16 v[2:5], v[98:101], v[130:133], v[2:5]
	v_mfma_f32_16x16x32_bf16 v[2:5], v[102:105], v[134:137], v[2:5]
	v_mfma_f32_16x16x32_bf16 v[10:13], v[94:97], v[134:137], v[10:13]
	v_mfma_f32_16x16x32_bf16 v[10:13], v[90:93], v[130:133], v[10:13]
	s_barrier
	s_setprio 0
	s_mov_b32 m0, s13
	s_mov_b32 s42, s78
	s_mov_b32 s43, s79
	buffer_load_dwordx4 v67, s[40:43], s28 offen lds
	s_mov_b32 m0, s14
	s_add_i32 s31, s28, 0x80000
	buffer_load_dwordx4 v69, s[40:43], s28 offen lds
	s_mov_b32 m0, s15
	s_nop 0
	buffer_load_dwordx4 v67, s[40:43], s31 offen lds
	s_mov_b32 m0, s16
	s_nop 0
	buffer_load_dwordx4 v69, s[40:43], s31 offen lds
	s_mov_b32 m0, s12
	s_nop 0
	buffer_load_dwordx4 v66, s[76:79], s29 offen lds
	s_mov_b32 m0, s18
	s_nop 0
	buffer_load_dwordx4 v68, s[76:79], s29 offen lds
	s_waitcnt vmcnt(6)
	s_barrier
	s_barrier
; #define PG8_STAGEX(rs, bufoff, soff, voff) do { _Pragma("unroll") for (int _i = 0; _i < 2; ++_i) \
;         __builtin_amdgcn_raw_ptr_buffer_load_lds(rs, (LAS unsigned*)(lds + (bufoff) + ldsw + _i * 8192), 16, (voff)[_i], (soff), 0, 0); } while (0)
; #define PG8_LDA(dst, b, h) do { _Pragma("unroll") for (int m = 0; m < 4; ++m) _Pragma("unroll") for (int k = 0; k < 2; ++k) dst[m][k] = *(const LAS bf16x8*)(lds + PG8_SA(b, h) + aoff + m * 2048 + k * 1024); } while (0)
; #define PG8_LDB(dst, b, h) do { _Pragma("unroll") for (int n = 0; n < 2; ++n) _Pragma("unroll") for (int k = 0; k < 2; ++k) dst[n][k] = *(const LAS bf16x8*)(lds + PG8_SB(b, h) + boff + n * 2048 + k * 1024); } while (0)
; #define PG8_WAIT_V(n) asm volatile("s_waitcnt vmcnt(" #n ")" ::: "memory")
; #define PG8_WAIT_L(n) asm volatile("s_waitcnt lgkmcnt(" #n ")" ::: "memory")
; #define PG8_BAR __builtin_amdgcn_s_barrier()
; #define PG8_SCHED __builtin_amdgcn_sched_barrier(0)
;     ...
;                 if (w0) { PG8_LDB(B0, 1, 0); PG8_LDB(B1, 1, 1); PG8_SCHED; PG8_LDA(At, 1, 0); }
;                 PG8_WAIT_L(0); PG8_BAR; if (w0) { PG8_MMA(0, 0, At, B0); PG8_MMA(0, 1, At, B1); } PG8_BAR; PG8_SCHED;
;                 PG8_STAGEX(rsB, PG8_SB(1, 0), b3, voffB); PG8_STAGEX(rsB, PG8_SB(1, 1), b3 + hstepB, voffB); PG8_STAGEX(rsA, PG8_SA(1, 0), a3, voffA);
;                 PG8_WAIT_V(6); PG8_BAR; PG8_BAR; PG8_SCHED;
;             }
;         }
;         if (wr == 0) PG8_BAR;
	v_add_u32_e32 v86, 0x18000, v72
	v_add_u32_e32 v102, 0x1c000, v72
	ds_read_b128 v[74:77], v86
	ds_read_b128 v[78:81], v86 offset:1024
	ds_read_b128 v[82:85], v86 offset:2048
	ds_read_b128 v[86:89], v86 offset:3072
	ds_read_b128 v[90:93], v102
	ds_read_b128 v[94:97], v102 offset:1024
	ds_read_b128 v[98:101], v102 offset:2048
	ds_read_b128 v[102:105], v102 offset:3072
	ds_read_b128 v[106:109], v73 offset:32768
	ds_read_b128 v[110:113], v73 offset:33792
	ds_read_b128 v[114:117], v73 offset:34816
	ds_read_b128 v[118:121], v73 offset:35840
	ds_read_b128 v[122:125], v73 offset:36864
	ds_read_b128 v[126:129], v73 offset:37888
	ds_read_b128 v[130:133], v73 offset:38912
	ds_read_b128 v[134:137], v73 offset:39936
	s_waitcnt lgkmcnt(0)
	s_setprio 1
	s_barrier
	v_mfma_f32_16x16x32_bf16 v[62:65], v[74:77], v[106:109], v[62:65]
	v_mfma_f32_16x16x32_bf16 v[58:61], v[82:85], v[106:109], v[58:61]
	v_mfma_f32_16x16x32_bf16 v[54:57], v[74:77], v[114:117], v[54:57]
	v_mfma_f32_16x16x32_bf16 v[38:41], v[82:85], v[114:117], v[38:41]
	v_mfma_f32_16x16x32_bf16 v[30:33], v[74:77], v[122:125], v[30:33]
	v_mfma_f32_16x16x32_bf16 v[22:25], v[82:85], v[122:125], v[22:25]
	v_mfma_f32_16x16x32_bf16 v[14:17], v[74:77], v[130:133], v[14:17]
	v_mfma_f32_16x16x32_bf16 v[6:9], v[82:85], v[130:133], v[6:9]
	v_mfma_f32_16x16x32_bf16 v[62:65], v[78:81], v[110:113], v[62:65]
	v_mfma_f32_16x16x32_bf16 v[58:61], v[86:89], v[110:113], v[58:61]
	v_mfma_f32_16x16x32_bf16 v[54:57], v[78:81], v[118:121], v[54:57]
	v_mfma_f32_16x16x32_bf16 v[38:41], v[86:89], v[118:121], v[38:41]
	v_mfma_f32_16x16x32_bf16 v[30:33], v[78:81], v[126:129], v[30:33]
	v_mfma_f32_16x16x32_bf16 v[22:25], v[86:89], v[126:129], v[22:25]
	v_mfma_f32_16x16x32_bf16 v[14:17], v[78:81], v[134:137], v[14:17]
	v_mfma_f32_16x16x32_bf16 v[6:9], v[86:89], v[134:137], v[6:9]
	v_mfma_f32_16x16x32_bf16 v[50:53], v[90:93], v[106:109], v[50:53]
	s_or_b32 s29, s28, 0x80
	v_mfma_f32_16x16x32_bf16 v[46:49], v[98:101], v[106:109], v[46:49]
	v_mfma_f32_16x16x32_bf16 v[42:45], v[90:93], v[114:117], v[42:45]
	v_mfma_f32_16x16x32_bf16 v[34:37], v[98:101], v[114:117], v[34:37]
	v_mfma_f32_16x16x32_bf16 v[26:29], v[90:93], v[122:125], v[26:29]
	v_mfma_f32_16x16x32_bf16 v[18:21], v[98:101], v[122:125], v[18:21]
	v_mfma_f32_16x16x32_bf16 v[10:13], v[90:93], v[130:133], v[10:13]
	v_mfma_f32_16x16x32_bf16 v[2:5], v[98:101], v[130:133], v[2:5]
	v_mfma_f32_16x16x32_bf16 v[50:53], v[94:97], v[110:113], v[50:53]
	v_mfma_f32_16x16x32_bf16 v[46:49], v[102:105], v[110:113], v[46:49]
	v_mfma_f32_16x16x32_bf16 v[42:45], v[94:97], v[118:121], v[42:45]
	v_mfma_f32_16x16x32_bf16 v[34:37], v[102:105], v[118:121], v[34:37]
	v_mfma_f32_16x16x32_bf16 v[26:29], v[94:97], v[126:129], v[26:29]
	v_mfma_f32_16x16x32_bf16 v[18:21], v[102:105], v[126:129], v[18:21]
	v_mfma_f32_16x16x32_bf16 v[10:13], v[94:97], v[134:137], v[10:13]
	v_mfma_f32_16x16x32_bf16 v[2:5], v[102:105], v[134:137], v[2:5]
	s_barrier
	s_setprio 0
	s_mov_b32 m0, s20
	s_add_i32 s28, s28, 0x80080
	buffer_load_dwordx4 v67, s[40:43], s29 offen lds
	s_mov_b32 m0, s21
	s_nop 0
	buffer_load_dwordx4 v69, s[40:43], s29 offen lds
	s_mov_b32 m0, s24
	s_nop 0
	buffer_load_dwordx4 v67, s[40:43], s28 offen lds
	s_mov_b32 m0, s25
	s_nop 0
	buffer_load_dwordx4 v69, s[40:43], s28 offen lds
	s_mov_b32 m0, s22
	s_nop 0
	buffer_load_dwordx4 v66, s[76:79], s30 offen lds
	s_mov_b32 m0, s23
	s_nop 0
	buffer_load_dwordx4 v68, s[76:79], s30 offen lds
	s_waitcnt vmcnt(6)
	s_barrier
	s_barrier
	s_addk_i32 s26, 0x100
	s_add_i32 s27, s27, 2
	s_cmp_gt_u32 s27, 29
	s_cbranch_scc0 .LBB0_240
	s_cmpk_lt_u32 s8, 0x100
	s_cbranch_scc0 .LBB0_243
	s_barrier

; #define PG8_STAGEX(rs, bufoff, soff, voff) do { _Pragma("unroll") for (int _i = 0; _i < 2; ++_i) \
;         __builtin_amdgcn_raw_ptr_buffer_load_lds(rs, (LAS unsigned*)(lds + (bufoff) + ldsw + _i * 8192), 16, (voff)[_i], (soff), 0, 0); } while (0)
; #define PG8_LDA(dst, b, h) do { _Pragma("unroll") for (int m = 0; m < 4; ++m) _Pragma("unroll") for (int k = 0; k < 2; ++k) dst[m][k] = *(const LAS bf16x8*)(lds + PG8_SA(b, h) + aoff + m * 2048 + k * 1024); } while (0)
; #define PG8_LDB(dst, b, h) do { _Pragma("unroll") for (int n = 0; n < 2; ++n) _Pragma("unroll") for (int k = 0; k < 2; ++k) dst[n][k] = *(const LAS bf16x8*)(lds + PG8_SB(b, h) + boff + n * 2048 + k * 1024); } while (0)
; #define PG8_WAIT_V(n) asm volatile("s_waitcnt vmcnt(" #n ")" ::: "memory")
; #define PG8_WAIT_L(n) asm volatile("s_waitcnt lgkmcnt(" #n ")" ::: "memory")
; #define PG8_BAR __builtin_amdgcn_s_barrier()
; #define PG8_SCHED __builtin_amdgcn_sched_barrier(0)
;     ...
;             const unsigned a1 = cA + (unsigned)(t + 1) * kstep;
;             const unsigned a2 = last ? nA : cA + (unsigned)(t + 2) * kstep, b2 = last ? nB : cB + (unsigned)(t + 2) * kstep;
;             const unsigned a3 = a2 + kstep, b3 = b2 + kstep;
;             PG8_LDB(B0, 0, 0); PG8_LDB(B1, 0, 1); PG8_SCHED; PG8_LDA(At, 0, 0); PG8_STAGEX(rsA, PG8_SA(1, 1), a1 + hstepA, voffA);
;             PG8_WAIT_V(8); PG8_WAIT_L(0); PG8_BAR; PG8_MMA(0, 0, At, B0); PG8_MMA(0, 1, At, B1); PG8_BAR; PG8_SCHED;
;             PG8_LDA(At, 0, 1); PG8_STAGEX(rsB, PG8_SB(0, 0), b2, voffB); PG8_STAGEX(rsB, PG8_SB(0, 1), b2 + hstepB, voffB); PG8_STAGEX(rsA, PG8_SA(0, 0), a2, voffA);
;             PG8_WAIT_V(8); PG8_WAIT_L(0); PG8_BAR; PG8_MMA(1, 0, At, B0); PG8_MMA(1, 1, At, B1); PG8_BAR; PG8_SCHED;
.LBB0_323:
	v_add_u32_e32 v118, 0x10000, v210
	v_add_u32_e32 v160, 0x14000, v210
	ds_read_b128 v[106:109], v118
	ds_read_b128 v[110:113], v118 offset:1024
	ds_read_b128 v[114:117], v118 offset:2048
	ds_read_b128 v[118:121], v118 offset:3072
	ds_read_b128 v[122:125], v160
	ds_read_b128 v[134:137], v160 offset:1024
	ds_read_b128 v[156:159], v160 offset:2048
	ds_read_b128 v[160:163], v160 offset:3072
	s_add_i32 s42, s51, 0xffea8080
	s_cmpk_eq_i32 s58, 0x52
	s_cselect_b32 s61, s30, s42
	s_cselect_b32 s60, s31, s57
	s_or_b32 s59, s61, 0x80
	s_mov_b32 m0, s68
	ds_read_b128 v[164:167], v211
	ds_read_b128 v[168:171], v211 offset:1024
	ds_read_b128 v[182:185], v211 offset:2048
	ds_read_b128 v[186:189], v211 offset:3072
	ds_read_b128 v[190:193], v211 offset:4096
	ds_read_b128 v[194:197], v211 offset:5120
	ds_read_b128 v[198:201], v211 offset:6144
	ds_read_b128 v[202:205], v211 offset:7168
	buffer_load_dwordx4 v178, s[76:79], s51 offen lds
	s_mov_b32 m0, s69
	s_nop 0
	buffer_load_dwordx4 v206, s[76:79], s51 offen lds
	s_waitcnt vmcnt(8)
	s_waitcnt lgkmcnt(0)
	s_setprio 1
	s_barrier
	v_mfma_f32_16x16x32_bf16 v[150:153], v[106:109], v[164:167], v[150:153]
	v_mfma_f32_16x16x32_bf16 v[150:153], v[110:113], v[168:171], v[150:153]
	v_mfma_f32_16x16x32_bf16 v[146:149], v[118:121], v[168:171], v[146:149]
	v_mfma_f32_16x16x32_bf16 v[146:149], v[114:117], v[164:167], v[146:149]
	v_mfma_f32_16x16x32_bf16 v[138:141], v[114:117], v[182:185], v[138:141]
	v_mfma_f32_16x16x32_bf16 v[138:141], v[118:121], v[186:189], v[138:141]
	v_mfma_f32_16x16x32_bf16 v[142:145], v[110:113], v[186:189], v[142:145]
	v_mfma_f32_16x16x32_bf16 v[142:145], v[106:109], v[182:185], v[142:145]
	v_mfma_f32_16x16x32_bf16 v[130:133], v[106:109], v[190:193], v[130:133]
	v_mfma_f32_16x16x32_bf16 v[130:133], v[110:113], v[194:197], v[130:133]
	v_mfma_f32_16x16x32_bf16 v[126:129], v[118:121], v[194:197], v[126:129]
	v_mfma_f32_16x16x32_bf16 v[126:129], v[114:117], v[190:193], v[126:129]
	v_mfma_f32_16x16x32_bf16 v[98:101], v[114:117], v[198:201], v[98:101]
	v_mfma_f32_16x16x32_bf16 v[98:101], v[118:121], v[202:205], v[98:101]
	v_mfma_f32_16x16x32_bf16 v[102:105], v[110:113], v[202:205], v[102:105]
	v_mfma_f32_16x16x32_bf16 v[102:105], v[106:109], v[198:201], v[102:105]
	v_mfma_f32_16x16x32_bf16 v[62:65], v[122:125], v[164:167], v[62:65]
	v_mfma_f32_16x16x32_bf16 v[62:65], v[134:137], v[168:171], v[62:65]
	v_mfma_f32_16x16x32_bf16 v[58:61], v[160:163], v[168:171], v[58:61]
	v_mfma_f32_16x16x32_bf16 v[58:61], v[156:159], v[164:167], v[58:61]
	v_mfma_f32_16x16x32_bf16 v[50:53], v[156:159], v[182:185], v[50:53]
	v_mfma_f32_16x16x32_bf16 v[50:53], v[160:163], v[186:189], v[50:53]
	v_mfma_f32_16x16x32_bf16 v[54:57], v[134:137], v[186:189], v[54:57]
	v_mfma_f32_16x16x32_bf16 v[54:57], v[122:125], v[182:185], v[54:57]
	v_mfma_f32_16x16x32_bf16 v[46:49], v[122:125], v[190:193], v[46:49]
	v_mfma_f32_16x16x32_bf16 v[46:49], v[134:137], v[194:197], v[46:49]
	v_mfma_f32_16x16x32_bf16 v[42:45], v[160:163], v[194:197], v[42:45]
	v_mfma_f32_16x16x32_bf16 v[42:45], v[156:159], v[190:193], v[42:45]
	v_mfma_f32_16x16x32_bf16 v[34:37], v[156:159], v[198:201], v[34:37]
	v_mfma_f32_16x16x32_bf16 v[34:37], v[160:163], v[202:205], v[34:37]
	v_mfma_f32_16x16x32_bf16 v[38:41], v[134:137], v[202:205], v[38:41]
	v_mfma_f32_16x16x32_bf16 v[38:41], v[122:125], v[198:201], v[38:41]
	s_barrier
	s_setprio 0
	s_mov_b32 m0, s15
	s_mov_b32 s42, s78
	s_mov_b32 s43, s79
	ds_read_b128 v[164:167], v211 offset:16384
	ds_read_b128 v[168:171], v211 offset:17408
	ds_read_b128 v[182:185], v211 offset:18432
	ds_read_b128 v[186:189], v211 offset:19456
	ds_read_b128 v[190:193], v211 offset:20480
	ds_read_b128 v[194:197], v211 offset:21504
	ds_read_b128 v[198:201], v211 offset:22528
	ds_read_b128 v[202:205], v211 offset:23552
	buffer_load_dwordx4 v179, s[40:43], s60 offen lds
	s_mov_b32 m0, s16
	s_add_i32 s62, s60, 0x158000
	buffer_load_dwordx4 v207, s[40:43], s60 offen lds
	s_mov_b32 m0, s17
	s_nop 0
	buffer_load_dwordx4 v179, s[40:43], s62 offen lds
	s_mov_b32 m0, s18
	s_nop 0
	buffer_load_dwordx4 v207, s[40:43], s62 offen lds
	s_mov_b32 m0, s14
	s_nop 0
	buffer_load_dwordx4 v178, s[76:79], s61 offen lds
	s_mov_b32 m0, s19
	s_nop 0
	buffer_load_dwordx4 v206, s[76:79], s61 offen lds
	s_waitcnt vmcnt(8)
	s_waitcnt lgkmcnt(0)
	s_setprio 1
	s_barrier
	v_mfma_f32_16x16x32_bf16 v[94:97], v[106:109], v[164:167], v[94:97]
	v_mfma_f32_16x16x32_bf16 v[94:97], v[110:113], v[168:171], v[94:97]
	v_mfma_f32_16x16x32_bf16 v[90:93], v[118:121], v[168:171], v[90:93]
	v_mfma_f32_16x16x32_bf16 v[90:93], v[114:117], v[164:167], v[90:93]
	v_mfma_f32_16x16x32_bf16 v[82:85], v[114:117], v[182:185], v[82:85]
	v_mfma_f32_16x16x32_bf16 v[82:85], v[118:121], v[186:189], v[82:85]
	v_mfma_f32_16x16x32_bf16 v[86:89], v[110:113], v[186:189], v[86:89]
	v_mfma_f32_16x16x32_bf16 v[86:89], v[106:109], v[182:185], v[86:89]
	v_mfma_f32_16x16x32_bf16 v[78:81], v[106:109], v[190:193], v[78:81]
	v_mfma_f32_16x16x32_bf16 v[78:81], v[110:113], v[194:197], v[78:81]
	v_mfma_f32_16x16x32_bf16 v[74:77], v[118:121], v[194:197], v[74:77]
	v_mfma_f32_16x16x32_bf16 v[74:77], v[114:117], v[190:193], v[74:77]
	v_mfma_f32_16x16x32_bf16 v[66:69], v[114:117], v[198:201], v[66:69]
	v_mfma_f32_16x16x32_bf16 v[66:69], v[118:121], v[202:205], v[66:69]
	v_mfma_f32_16x16x32_bf16 v[70:73], v[110:113], v[202:205], v[70:73]
	v_mfma_f32_16x16x32_bf16 v[70:73], v[106:109], v[198:201], v[70:73]
	v_mfma_f32_16x16x32_bf16 v[30:33], v[122:125], v[164:167], v[30:33]
	v_mfma_f32_16x16x32_bf16 v[30:33], v[134:137], v[168:171], v[30:33]
	v_mfma_f32_16x16x32_bf16 v[26:29], v[160:163], v[168:171], v[26:29]
	v_mfma_f32_16x16x32_bf16 v[26:29], v[156:159], v[164:167], v[26:29]
	v_mfma_f32_16x16x32_bf16 v[18:21], v[156:159], v[182:185], v[18:21]
	v_mfma_f32_16x16x32_bf16 v[18:21], v[160:163], v[186:189], v[18:21]
	v_mfma_f32_16x16x32_bf16 v[22:25], v[134:137], v[186:189], v[22:25]
	v_mfma_f32_16x16x32_bf16 v[22:25], v[122:125], v[182:185], v[22:25]
	v_mfma_f32_16x16x32_bf16 v[14:17], v[122:125], v[190:193], v[14:17]
	v_mfma_f32_16x16x32_bf16 v[14:17], v[134:137], v[194:197], v[14:17]
	v_mfma_f32_16x16x32_bf16 v[10:13], v[160:163], v[194:197], v[10:13]
	v_mfma_f32_16x16x32_bf16 v[10:13], v[156:159], v[190:193], v[10:13]
	v_mfma_f32_16x16x32_bf16 v[2:5], v[156:159], v[198:201], v[2:5]
	v_mfma_f32_16x16x32_bf16 v[2:5], v[160:163], v[202:205], v[2:5]
	v_mfma_f32_16x16x32_bf16 v[6:9], v[134:137], v[202:205], v[6:9]
	v_mfma_f32_16x16x32_bf16 v[6:9], v[122:125], v[198:201], v[6:9]
	s_barrier
; #define PG8_STAGEX(rs, bufoff, soff, voff) do { _Pragma("unroll") for (int _i = 0; _i < 2; ++_i) \
;         __builtin_amdgcn_raw_ptr_buffer_load_lds(rs, (LAS unsigned*)(lds + (bufoff) + ldsw + _i * 8192), 16, (voff)[_i], (soff), 0, 0); } while (0)
; #define PG8_LDA(dst, b, h) do { _Pragma("unroll") for (int m = 0; m < 4; ++m) _Pragma("unroll") for (int k = 0; k < 2; ++k) dst[m][k] = *(const LAS bf16x8*)(lds + PG8_SA(b, h) + aoff + m * 2048 + k * 1024); } while (0)
; #define PG8_LDB(dst, b, h) do { _Pragma("unroll") for (int n = 0; n < 2; ++n) _Pragma("unroll") for (int k = 0; k < 2; ++k) dst[n][k] = *(const LAS bf16x8*)(lds + PG8_SB(b, h) + boff + n * 2048 + k * 1024); } while (0)
; #define PG8_WAIT_V(n) asm volatile("s_waitcnt vmcnt(" #n ")" ::: "memory")
; #define PG8_WAIT_L(n) asm volatile("s_waitcnt lgkmcnt(" #n ")" ::: "memory")
; #define PG8_BAR __builtin_amdgcn_s_barrier()
; #define PG8_SCHED __builtin_amdgcn_sched_barrier(0)
;     ...
;             PG8_LDB(B0, 1, 0); PG8_LDB(B1, 1, 1); PG8_SCHED; PG8_LDA(At, 1, 0); PG8_STAGEX(rsA, PG8_SA(0, 1), a2 + hstepA, voffA);
;             PG8_WAIT_V(8); PG8_WAIT_L(0); PG8_BAR; PG8_MMA(0, 0, At, B0); PG8_MMA(0, 1, At, B1); PG8_BAR; PG8_SCHED;
;             PG8_LDA(At, 1, 1); PG8_STAGEX(rsB, PG8_SB(1, 0), b3, voffB); PG8_STAGEX(rsB, PG8_SB(1, 1), b3 + hstepB, voffB); PG8_STAGEX(rsA, PG8_SA(1, 0), a3, voffA);
;             PG8_WAIT_V(8); PG8_WAIT_L(0); PG8_BAR; PG8_MMA(1, 0, At, B0); PG8_MMA(1, 1, At, B1); PG8_BAR; PG8_SCHED;
;         }
;     ...
;         if (wr == 0) PG8_BAR;
	s_setprio 0
	v_add_u32_e32 v118, 0x18000, v210
	v_add_u32_e32 v160, 0x1c000, v210
	ds_read_b128 v[106:109], v118
	ds_read_b128 v[110:113], v118 offset:1024
	ds_read_b128 v[114:117], v118 offset:2048
	ds_read_b128 v[118:121], v118 offset:3072
	ds_read_b128 v[122:125], v160
	ds_read_b128 v[134:137], v160 offset:1024
	ds_read_b128 v[156:159], v160 offset:2048
	ds_read_b128 v[160:163], v160 offset:3072
	s_add_i32 s61, s61, 0x158000
	s_mov_b32 m0, s20
	ds_read_b128 v[164:167], v211 offset:32768
	ds_read_b128 v[168:171], v211 offset:33792
	ds_read_b128 v[182:185], v211 offset:34816
	ds_read_b128 v[186:189], v211 offset:35840
	ds_read_b128 v[190:193], v211 offset:36864
	ds_read_b128 v[194:197], v211 offset:37888
	ds_read_b128 v[198:201], v211 offset:38912
	ds_read_b128 v[202:205], v211 offset:39936
	buffer_load_dwordx4 v178, s[76:79], s61 offen lds
	s_mov_b32 m0, s21
	s_nop 0
	buffer_load_dwordx4 v206, s[76:79], s61 offen lds
	s_waitcnt vmcnt(8)
	s_waitcnt lgkmcnt(0)
	s_setprio 1
	s_barrier
	v_mfma_f32_16x16x32_bf16 v[150:153], v[106:109], v[164:167], v[150:153]
	v_mfma_f32_16x16x32_bf16 v[150:153], v[110:113], v[168:171], v[150:153]
	v_mfma_f32_16x16x32_bf16 v[146:149], v[118:121], v[168:171], v[146:149]
	v_mfma_f32_16x16x32_bf16 v[146:149], v[114:117], v[164:167], v[146:149]
	v_mfma_f32_16x16x32_bf16 v[138:141], v[114:117], v[182:185], v[138:141]
	v_mfma_f32_16x16x32_bf16 v[138:141], v[118:121], v[186:189], v[138:141]
	v_mfma_f32_16x16x32_bf16 v[142:145], v[110:113], v[186:189], v[142:145]
	v_mfma_f32_16x16x32_bf16 v[142:145], v[106:109], v[182:185], v[142:145]
	v_mfma_f32_16x16x32_bf16 v[130:133], v[106:109], v[190:193], v[130:133]
	v_mfma_f32_16x16x32_bf16 v[130:133], v[110:113], v[194:197], v[130:133]
	v_mfma_f32_16x16x32_bf16 v[126:129], v[118:121], v[194:197], v[126:129]
	v_mfma_f32_16x16x32_bf16 v[126:129], v[114:117], v[190:193], v[126:129]
	v_mfma_f32_16x16x32_bf16 v[98:101], v[114:117], v[198:201], v[98:101]
	v_mfma_f32_16x16x32_bf16 v[98:101], v[118:121], v[202:205], v[98:101]
	v_mfma_f32_16x16x32_bf16 v[102:105], v[110:113], v[202:205], v[102:105]
	v_mfma_f32_16x16x32_bf16 v[102:105], v[106:109], v[198:201], v[102:105]
	v_mfma_f32_16x16x32_bf16 v[62:65], v[122:125], v[164:167], v[62:65]
	v_mfma_f32_16x16x32_bf16 v[62:65], v[134:137], v[168:171], v[62:65]
	v_mfma_f32_16x16x32_bf16 v[58:61], v[160:163], v[168:171], v[58:61]
	v_mfma_f32_16x16x32_bf16 v[58:61], v[156:159], v[164:167], v[58:61]
	v_mfma_f32_16x16x32_bf16 v[50:53], v[156:159], v[182:185], v[50:53]
	v_mfma_f32_16x16x32_bf16 v[50:53], v[160:163], v[186:189], v[50:53]
	v_mfma_f32_16x16x32_bf16 v[54:57], v[134:137], v[186:189], v[54:57]
	v_mfma_f32_16x16x32_bf16 v[54:57], v[122:125], v[182:185], v[54:57]
	v_mfma_f32_16x16x32_bf16 v[46:49], v[122:125], v[190:193], v[46:49]
	v_mfma_f32_16x16x32_bf16 v[46:49], v[134:137], v[194:197], v[46:49]
	v_mfma_f32_16x16x32_bf16 v[42:45], v[160:163], v[194:197], v[42:45]
	v_mfma_f32_16x16x32_bf16 v[42:45], v[156:159], v[190:193], v[42:45]
	v_mfma_f32_16x16x32_bf16 v[34:37], v[156:159], v[198:201], v[34:37]
	v_mfma_f32_16x16x32_bf16 v[34:37], v[160:163], v[202:205], v[34:37]
	v_mfma_f32_16x16x32_bf16 v[38:41], v[134:137], v[202:205], v[38:41]
	v_mfma_f32_16x16x32_bf16 v[38:41], v[122:125], v[198:201], v[38:41]
	s_barrier
	s_setprio 0
	s_mov_b32 m0, s28
	s_or_b32 s61, s60, 0x80
	ds_read_b128 v[164:167], v211 offset:49152
	ds_read_b128 v[168:171], v211 offset:50176
	ds_read_b128 v[182:185], v211 offset:51200
	ds_read_b128 v[186:189], v211 offset:52224
	ds_read_b128 v[190:193], v211 offset:53248
	ds_read_b128 v[194:197], v211 offset:54272
	ds_read_b128 v[198:201], v211 offset:55296
	ds_read_b128 v[202:205], v211 offset:56320
	buffer_load_dwordx4 v179, s[40:43], s61 offen lds
	s_mov_b32 m0, s29
	s_add_i32 s60, s60, 0x158080
	buffer_load_dwordx4 v207, s[40:43], s61 offen lds
	s_mov_b32 m0, s66
	s_nop 0
	buffer_load_dwordx4 v179, s[40:43], s60 offen lds
	s_mov_b32 m0, s67
	s_nop 0
	buffer_load_dwordx4 v207, s[40:43], s60 offen lds
	s_mov_b32 m0, s54
	s_nop 0
	buffer_load_dwordx4 v178, s[76:79], s59 offen lds
	s_mov_b32 m0, s55
	s_nop 0
	buffer_load_dwordx4 v206, s[76:79], s59 offen lds
	s_waitcnt vmcnt(8)
	s_waitcnt lgkmcnt(0)
	s_setprio 1
	s_barrier
	v_mfma_f32_16x16x32_bf16 v[94:97], v[106:109], v[164:167], v[94:97]
	v_mfma_f32_16x16x32_bf16 v[94:97], v[110:113], v[168:171], v[94:97]
	v_mfma_f32_16x16x32_bf16 v[90:93], v[118:121], v[168:171], v[90:93]
	v_mfma_f32_16x16x32_bf16 v[90:93], v[114:117], v[164:167], v[90:93]
	v_mfma_f32_16x16x32_bf16 v[82:85], v[114:117], v[182:185], v[82:85]
	v_mfma_f32_16x16x32_bf16 v[82:85], v[118:121], v[186:189], v[82:85]
	v_mfma_f32_16x16x32_bf16 v[86:89], v[110:113], v[186:189], v[86:89]
	v_mfma_f32_16x16x32_bf16 v[86:89], v[106:109], v[182:185], v[86:89]
	v_mfma_f32_16x16x32_bf16 v[78:81], v[106:109], v[190:193], v[78:81]
	v_mfma_f32_16x16x32_bf16 v[78:81], v[110:113], v[194:197], v[78:81]
	v_mfma_f32_16x16x32_bf16 v[74:77], v[118:121], v[194:197], v[74:77]
	v_mfma_f32_16x16x32_bf16 v[74:77], v[114:117], v[190:193], v[74:77]
	v_mfma_f32_16x16x32_bf16 v[66:69], v[114:117], v[198:201], v[66:69]
	v_mfma_f32_16x16x32_bf16 v[66:69], v[118:121], v[202:205], v[66:69]
	v_mfma_f32_16x16x32_bf16 v[70:73], v[110:113], v[202:205], v[70:73]
	v_mfma_f32_16x16x32_bf16 v[70:73], v[106:109], v[198:201], v[70:73]
	v_mfma_f32_16x16x32_bf16 v[30:33], v[122:125], v[164:167], v[30:33]
	v_mfma_f32_16x16x32_bf16 v[30:33], v[134:137], v[168:171], v[30:33]
	v_mfma_f32_16x16x32_bf16 v[26:29], v[160:163], v[168:171], v[26:29]
	v_mfma_f32_16x16x32_bf16 v[26:29], v[156:159], v[164:167], v[26:29]
	v_mfma_f32_16x16x32_bf16 v[18:21], v[156:159], v[182:185], v[18:21]
	v_mfma_f32_16x16x32_bf16 v[18:21], v[160:163], v[186:189], v[18:21]
	v_mfma_f32_16x16x32_bf16 v[22:25], v[134:137], v[186:189], v[22:25]
	v_mfma_f32_16x16x32_bf16 v[22:25], v[122:125], v[182:185], v[22:25]
	v_mfma_f32_16x16x32_bf16 v[14:17], v[122:125], v[190:193], v[14:17]
	v_mfma_f32_16x16x32_bf16 v[14:17], v[134:137], v[194:197], v[14:17]
	v_mfma_f32_16x16x32_bf16 v[10:13], v[160:163], v[194:197], v[10:13]
	v_mfma_f32_16x16x32_bf16 v[10:13], v[156:159], v[190:193], v[10:13]
	v_mfma_f32_16x16x32_bf16 v[2:5], v[156:159], v[198:201], v[2:5]
	v_mfma_f32_16x16x32_bf16 v[2:5], v[160:163], v[202:205], v[2:5]
	v_mfma_f32_16x16x32_bf16 v[6:9], v[134:137], v[202:205], v[6:9]
	v_mfma_f32_16x16x32_bf16 v[6:9], v[122:125], v[198:201], v[6:9]
	s_barrier
	s_setprio 0
	s_add_i32 s58, s58, 2
	s_addk_i32 s51, 0x100
	s_addk_i32 s57, 0x100
	s_cmpk_gt_u32 s58, 0x53
	s_cbranch_scc0 .LBB0_323
	s_and_b64 vcc, exec, s[48:49]
	s_cbranch_vccz .LBB0_326
	s_barrier

; #define PG8_STAGEX(rs, bufoff, soff, voff) do { _Pragma("unroll") for (int _i = 0; _i < 2; ++_i) \
;         __builtin_amdgcn_raw_ptr_buffer_load_lds(rs, (LAS unsigned*)(lds + (bufoff) + ldsw + _i * 8192), 16, (voff)[_i], (soff), 0, 0); } while (0)
; #define PG8_LDA(dst, b, h) do { _Pragma("unroll") for (int m = 0; m < 4; ++m) _Pragma("unroll") for (int k = 0; k < 2; ++k) dst[m][k] = *(const LAS bf16x8*)(lds + PG8_SA(b, h) + aoff + m * 2048 + k * 1024); } while (0)
; #define PG8_LDB(dst, b, h) do { _Pragma("unroll") for (int n = 0; n < 2; ++n) _Pragma("unroll") for (int k = 0; k < 2; ++k) dst[n][k] = *(const LAS bf16x8*)(lds + PG8_SB(b, h) + boff + n * 2048 + k * 1024); } while (0)
; #define PG8_WAIT_V(n) asm volatile("s_waitcnt vmcnt(" #n ")" ::: "memory")
; #define PG8_WAIT_L(n) asm volatile("s_waitcnt lgkmcnt(" #n ")" ::: "memory")
; #define PG8_BAR __builtin_amdgcn_s_barrier()
; #define PG8_SCHED __builtin_amdgcn_sched_barrier(0)
;     ...
;                 PG8_WAIT_L(0); PG8_BAR; if (w0) { PG8_MMA(0, 0, At, B0); PG8_MMA(0, 1, At, B1); } PG8_BAR; PG8_SCHED;
;                 PG8_STAGEX(rsB, PG8_SB(0, 0), b2, voffB); PG8_STAGEX(rsB, PG8_SB(0, 1), b2 + hstepB, voffB); PG8_STAGEX(rsA, PG8_SA(0, 0), a2, voffA);
;                 PG8_WAIT_V(6); PG8_BAR; PG8_BAR; PG8_SCHED;
;                 if (w0) { PG8_LDB(B0, 1, 0); PG8_LDB(B1, 1, 1); PG8_SCHED; PG8_LDA(At, 1, 0); }
;                 PG8_WAIT_L(0); PG8_BAR; if (w0) { PG8_MMA(0, 0, At, B0); PG8_MMA(0, 1, At, B1); } PG8_BAR; PG8_SCHED;
.LBB0_355:
	s_waitcnt lgkmcnt(0)
	s_and_b64 vcc, exec, s[38:39]
	s_barrier
	s_cbranch_vccnz .LBB0_357
	s_setprio 1
	s_waitcnt lgkmcnt(7)
	v_mfma_f32_16x16x32_bf16 v[62:65], v[66:69], v[98:101], v[62:65]
	v_mfma_f32_16x16x32_bf16 v[62:65], v[70:73], v[102:105], v[62:65]
	v_mfma_f32_16x16x32_bf16 v[58:61], v[78:81], v[102:105], v[58:61]
	v_mfma_f32_16x16x32_bf16 v[58:61], v[74:77], v[98:101], v[58:61]
	v_mfma_f32_16x16x32_bf16 v[50:53], v[74:77], v[106:109], v[50:53]
	v_mfma_f32_16x16x32_bf16 v[50:53], v[78:81], v[110:113], v[50:53]
	v_mfma_f32_16x16x32_bf16 v[54:57], v[70:73], v[110:113], v[54:57]
	v_mfma_f32_16x16x32_bf16 v[54:57], v[66:69], v[106:109], v[54:57]
	v_mfma_f32_16x16x32_bf16 v[46:49], v[66:69], v[114:117], v[46:49]
	v_mfma_f32_16x16x32_bf16 v[46:49], v[70:73], v[118:121], v[46:49]
	v_mfma_f32_16x16x32_bf16 v[42:45], v[78:81], v[118:121], v[42:45]
	v_mfma_f32_16x16x32_bf16 v[42:45], v[74:77], v[114:117], v[42:45]
	v_mfma_f32_16x16x32_bf16 v[34:37], v[74:77], v[122:125], v[34:37]
	v_mfma_f32_16x16x32_bf16 v[34:37], v[78:81], v[126:129], v[34:37]
	v_mfma_f32_16x16x32_bf16 v[38:41], v[70:73], v[126:129], v[38:41]
	v_mfma_f32_16x16x32_bf16 v[38:41], v[66:69], v[122:125], v[38:41]
	v_mfma_f32_16x16x32_bf16 v[30:33], v[82:85], v[98:101], v[30:33]
	v_mfma_f32_16x16x32_bf16 v[30:33], v[86:89], v[102:105], v[30:33]
	v_mfma_f32_16x16x32_bf16 v[26:29], v[94:97], v[102:105], v[26:29]
	v_mfma_f32_16x16x32_bf16 v[26:29], v[90:93], v[98:101], v[26:29]
	v_mfma_f32_16x16x32_bf16 v[18:21], v[90:93], v[106:109], v[18:21]
	v_mfma_f32_16x16x32_bf16 v[18:21], v[94:97], v[110:113], v[18:21]
	v_mfma_f32_16x16x32_bf16 v[22:25], v[86:89], v[110:113], v[22:25]
	v_mfma_f32_16x16x32_bf16 v[22:25], v[82:85], v[106:109], v[22:25]
	v_mfma_f32_16x16x32_bf16 v[14:17], v[82:85], v[114:117], v[14:17]
	v_mfma_f32_16x16x32_bf16 v[14:17], v[86:89], v[118:121], v[14:17]
	v_mfma_f32_16x16x32_bf16 v[10:13], v[94:97], v[118:121], v[10:13]
	v_mfma_f32_16x16x32_bf16 v[10:13], v[90:93], v[114:117], v[10:13]
	v_mfma_f32_16x16x32_bf16 v[2:5], v[90:93], v[122:125], v[2:5]
	v_mfma_f32_16x16x32_bf16 v[2:5], v[94:97], v[126:129], v[2:5]
	v_mfma_f32_16x16x32_bf16 v[6:9], v[86:89], v[126:129], v[6:9]
	v_mfma_f32_16x16x32_bf16 v[6:9], v[82:85], v[122:125], v[6:9]
	s_setprio 0

; #define PG8_STAGEX(rs, bufoff, soff, voff) do { _Pragma("unroll") for (int _i = 0; _i < 2; ++_i) \
;         __builtin_amdgcn_raw_ptr_buffer_load_lds(rs, (LAS unsigned*)(lds + (bufoff) + ldsw + _i * 8192), 16, (voff)[_i], (soff), 0, 0); } while (0)
; #define PG8_LDA(dst, b, h) do { _Pragma("unroll") for (int m = 0; m < 4; ++m) _Pragma("unroll") for (int k = 0; k < 2; ++k) dst[m][k] = *(const LAS bf16x8*)(lds + PG8_SA(b, h) + aoff + m * 2048 + k * 1024); } while (0)
; #define PG8_LDB(dst, b, h) do { _Pragma("unroll") for (int n = 0; n < 2; ++n) _Pragma("unroll") for (int k = 0; k < 2; ++k) dst[n][k] = *(const LAS bf16x8*)(lds + PG8_SB(b, h) + boff + n * 2048 + k * 1024); } while (0)
; #define PG8_WAIT_V(n) asm volatile("s_waitcnt vmcnt(" #n ")" ::: "memory")
; #define PG8_WAIT_L(n) asm volatile("s_waitcnt lgkmcnt(" #n ")" ::: "memory")
; #define PG8_BAR __builtin_amdgcn_s_barrier()
; #define PG8_SCHED __builtin_amdgcn_sched_barrier(0)
;     ...
;                 if (w0) { PG8_LDB(B0, 1, 0); PG8_LDB(B1, 1, 1); PG8_SCHED; PG8_LDA(At, 1, 0); }
;                 PG8_WAIT_L(0); PG8_BAR; if (w0) { PG8_MMA(0, 0, At, B0); PG8_MMA(0, 1, At, B1); } PG8_BAR; PG8_SCHED;
;                 PG8_STAGEX(rsB, PG8_SB(1, 0), b3, voffB); PG8_STAGEX(rsB, PG8_SB(1, 1), b3 + hstepB, voffB); PG8_STAGEX(rsA, PG8_SA(1, 0), a3, voffA);
;                 PG8_WAIT_V(6); PG8_BAR; PG8_BAR; PG8_SCHED;
.LBB0_359:
	s_waitcnt lgkmcnt(0)
	s_and_b64 vcc, exec, s[38:39]
	s_barrier
	s_cbranch_vccnz .LBB0_352
	s_setprio 1
	s_waitcnt lgkmcnt(7)
	v_mfma_f32_16x16x32_bf16 v[62:65], v[66:69], v[98:101], v[62:65]
	v_mfma_f32_16x16x32_bf16 v[62:65], v[70:73], v[102:105], v[62:65]
	v_mfma_f32_16x16x32_bf16 v[58:61], v[78:81], v[102:105], v[58:61]
	v_mfma_f32_16x16x32_bf16 v[58:61], v[74:77], v[98:101], v[58:61]
	v_mfma_f32_16x16x32_bf16 v[50:53], v[74:77], v[106:109], v[50:53]
	v_mfma_f32_16x16x32_bf16 v[50:53], v[78:81], v[110:113], v[50:53]
	v_mfma_f32_16x16x32_bf16 v[54:57], v[70:73], v[110:113], v[54:57]
	v_mfma_f32_16x16x32_bf16 v[54:57], v[66:69], v[106:109], v[54:57]
	v_mfma_f32_16x16x32_bf16 v[46:49], v[66:69], v[114:117], v[46:49]
	v_mfma_f32_16x16x32_bf16 v[46:49], v[70:73], v[118:121], v[46:49]
	v_mfma_f32_16x16x32_bf16 v[42:45], v[78:81], v[118:121], v[42:45]
	v_mfma_f32_16x16x32_bf16 v[42:45], v[74:77], v[114:117], v[42:45]
	v_mfma_f32_16x16x32_bf16 v[34:37], v[74:77], v[122:125], v[34:37]
	v_mfma_f32_16x16x32_bf16 v[34:37], v[78:81], v[126:129], v[34:37]
	v_mfma_f32_16x16x32_bf16 v[38:41], v[70:73], v[126:129], v[38:41]
	v_mfma_f32_16x16x32_bf16 v[38:41], v[66:69], v[122:125], v[38:41]
	v_mfma_f32_16x16x32_bf16 v[30:33], v[82:85], v[98:101], v[30:33]
	v_mfma_f32_16x16x32_bf16 v[30:33], v[86:89], v[102:105], v[30:33]
	v_mfma_f32_16x16x32_bf16 v[26:29], v[94:97], v[102:105], v[26:29]
	v_mfma_f32_16x16x32_bf16 v[26:29], v[90:93], v[98:101], v[26:29]
	v_mfma_f32_16x16x32_bf16 v[18:21], v[90:93], v[106:109], v[18:21]
	v_mfma_f32_16x16x32_bf16 v[18:21], v[94:97], v[110:113], v[18:21]
	v_mfma_f32_16x16x32_bf16 v[22:25], v[86:89], v[110:113], v[22:25]
	v_mfma_f32_16x16x32_bf16 v[22:25], v[82:85], v[106:109], v[22:25]
	v_mfma_f32_16x16x32_bf16 v[14:17], v[82:85], v[114:117], v[14:17]
	v_mfma_f32_16x16x32_bf16 v[14:17], v[86:89], v[118:121], v[14:17]
	v_mfma_f32_16x16x32_bf16 v[10:13], v[94:97], v[118:121], v[10:13]
	v_mfma_f32_16x16x32_bf16 v[10:13], v[90:93], v[114:117], v[10:13]
	v_mfma_f32_16x16x32_bf16 v[2:5], v[90:93], v[122:125], v[2:5]
	v_mfma_f32_16x16x32_bf16 v[2:5], v[94:97], v[126:129], v[2:5]
	v_mfma_f32_16x16x32_bf16 v[6:9], v[86:89], v[126:129], v[6:9]
	v_mfma_f32_16x16x32_bf16 v[6:9], v[82:85], v[122:125], v[6:9]
	s_setprio 0
	s_branch .LBB0_352

; #define PG8_STAGEX(rs, bufoff, soff, voff) do { _Pragma("unroll") for (int _i = 0; _i < 2; ++_i) \
;         __builtin_amdgcn_raw_ptr_buffer_load_lds(rs, (LAS unsigned*)(lds + (bufoff) + ldsw + _i * 8192), 16, (voff)[_i], (soff), 0, 0); } while (0)
; #define PG8_LDA(dst, b, h) do { _Pragma("unroll") for (int m = 0; m < 4; ++m) _Pragma("unroll") for (int k = 0; k < 2; ++k) dst[m][k] = *(const LAS bf16x8*)(lds + PG8_SA(b, h) + aoff + m * 2048 + k * 1024); } while (0)
; #define PG8_LDB(dst, b, h) do { _Pragma("unroll") for (int n = 0; n < 2; ++n) _Pragma("unroll") for (int k = 0; k < 2; ++k) dst[n][k] = *(const LAS bf16x8*)(lds + PG8_SB(b, h) + boff + n * 2048 + k * 1024); } while (0)
; #define PG8_WAIT_V(n) asm volatile("s_waitcnt vmcnt(" #n ")" ::: "memory")
; #define PG8_WAIT_L(n) asm volatile("s_waitcnt lgkmcnt(" #n ")" ::: "memory")
; #define PG8_BAR __builtin_amdgcn_s_barrier()
; #define PG8_SCHED __builtin_amdgcn_sched_barrier(0)
;     ...
;             const unsigned a1 = cA + (unsigned)(t + 1) * kstep;
;             const unsigned a2 = last ? nA : cA + (unsigned)(t + 2) * kstep, b2 = last ? nB : cB + (unsigned)(t + 2) * kstep;
;             const unsigned a3 = a2 + kstep, b3 = b2 + kstep;
;             PG8_LDB(B0, 0, 0); PG8_LDB(B1, 0, 1); PG8_SCHED; PG8_LDA(At, 0, 0); PG8_STAGEX(rsA, PG8_SA(1, 1), a1 + hstepA, voffA);
;             PG8_WAIT_V(8); PG8_WAIT_L(0); PG8_BAR; PG8_MMA(0, 0, At, B0); PG8_MMA(0, 1, At, B1); PG8_BAR; PG8_SCHED;
;             PG8_LDA(At, 0, 1); PG8_STAGEX(rsB, PG8_SB(0, 0), b2, voffB); PG8_STAGEX(rsB, PG8_SB(0, 1), b2 + hstepB, voffB); PG8_STAGEX(rsA, PG8_SA(0, 0), a2, voffA);
;             PG8_WAIT_V(8); PG8_WAIT_L(0); PG8_BAR; PG8_MMA(1, 0, At, B0); PG8_MMA(1, 1, At, B1); PG8_BAR; PG8_SCHED;
.LBB0_437:
	v_add_u32_e32 v142, 0x10000, v220
	v_add_u32_e32 v158, 0x14000, v220
	ds_read_b128 v[130:133], v142
	ds_read_b128 v[134:137], v142 offset:1024
	ds_read_b128 v[138:141], v142 offset:2048
	ds_read_b128 v[142:145], v142 offset:3072
	ds_read_b128 v[146:149], v158
	ds_read_b128 v[150:153], v158 offset:1024
	ds_read_b128 v[154:157], v158 offset:2048
	ds_read_b128 v[158:161], v158 offset:3072
	s_add_i32 s30, s7, 0xfff80080
	s_cmp_eq_u32 s29, 28
	s_cselect_b32 s50, s2, s30
	s_cselect_b32 s31, s5, s28
	s_or_b32 s30, s50, 0x80
	s_mov_b32 m0, s20
	ds_read_b128 v[162:165], v221
	ds_read_b128 v[170:173], v221 offset:1024
	ds_read_b128 v[182:185], v221 offset:2048
	ds_read_b128 v[186:189], v221 offset:3072
	ds_read_b128 v[190:193], v221 offset:4096
	ds_read_b128 v[194:197], v221 offset:5120
	ds_read_b128 v[198:201], v221 offset:6144
	ds_read_b128 v[202:205], v221 offset:7168
	buffer_load_dwordx4 v178, s[76:79], s7 offen lds
	s_mov_b32 m0, s22
	s_nop 0
	buffer_load_dwordx4 v210, s[76:79], s7 offen lds
	s_waitcnt vmcnt(8)
	s_waitcnt lgkmcnt(0)
	s_setprio 1
	s_barrier
	v_mfma_f32_16x16x32_bf16 v[126:129], v[130:133], v[162:165], v[126:129]
	v_mfma_f32_16x16x32_bf16 v[126:129], v[134:137], v[170:173], v[126:129]
	v_mfma_f32_16x16x32_bf16 v[110:113], v[142:145], v[170:173], v[110:113]
	v_mfma_f32_16x16x32_bf16 v[110:113], v[138:141], v[162:165], v[110:113]
	v_mfma_f32_16x16x32_bf16 v[102:105], v[138:141], v[182:185], v[102:105]
	v_mfma_f32_16x16x32_bf16 v[102:105], v[142:145], v[186:189], v[102:105]
	v_mfma_f32_16x16x32_bf16 v[118:121], v[134:137], v[186:189], v[118:121]
	v_mfma_f32_16x16x32_bf16 v[118:121], v[130:133], v[182:185], v[118:121]
	v_mfma_f32_16x16x32_bf16 v[114:117], v[130:133], v[190:193], v[114:117]
	v_mfma_f32_16x16x32_bf16 v[114:117], v[134:137], v[194:197], v[114:117]
	v_mfma_f32_16x16x32_bf16 v[98:101], v[142:145], v[194:197], v[98:101]
	v_mfma_f32_16x16x32_bf16 v[98:101], v[138:141], v[190:193], v[98:101]
	v_mfma_f32_16x16x32_bf16 v[106:109], v[138:141], v[198:201], v[106:109]
	v_mfma_f32_16x16x32_bf16 v[106:109], v[142:145], v[202:205], v[106:109]
	v_mfma_f32_16x16x32_bf16 v[122:125], v[134:137], v[202:205], v[122:125]
	v_mfma_f32_16x16x32_bf16 v[122:125], v[130:133], v[198:201], v[122:125]
	v_mfma_f32_16x16x32_bf16 v[62:65], v[146:149], v[162:165], v[62:65]
	v_mfma_f32_16x16x32_bf16 v[62:65], v[150:153], v[170:173], v[62:65]
	v_mfma_f32_16x16x32_bf16 v[46:49], v[158:161], v[170:173], v[46:49]
	v_mfma_f32_16x16x32_bf16 v[46:49], v[154:157], v[162:165], v[46:49]
	v_mfma_f32_16x16x32_bf16 v[38:41], v[154:157], v[182:185], v[38:41]
	v_mfma_f32_16x16x32_bf16 v[38:41], v[158:161], v[186:189], v[38:41]
	v_mfma_f32_16x16x32_bf16 v[54:57], v[150:153], v[186:189], v[54:57]
	v_mfma_f32_16x16x32_bf16 v[54:57], v[146:149], v[182:185], v[54:57]
	v_mfma_f32_16x16x32_bf16 v[50:53], v[146:149], v[190:193], v[50:53]
	v_mfma_f32_16x16x32_bf16 v[50:53], v[150:153], v[194:197], v[50:53]
	v_mfma_f32_16x16x32_bf16 v[34:37], v[158:161], v[194:197], v[34:37]
	v_mfma_f32_16x16x32_bf16 v[34:37], v[154:157], v[190:193], v[34:37]
	v_mfma_f32_16x16x32_bf16 v[42:45], v[154:157], v[198:201], v[42:45]
	v_mfma_f32_16x16x32_bf16 v[42:45], v[158:161], v[202:205], v[42:45]
	v_mfma_f32_16x16x32_bf16 v[58:61], v[150:153], v[202:205], v[58:61]
	v_mfma_f32_16x16x32_bf16 v[58:61], v[146:149], v[198:201], v[58:61]
	s_barrier
	s_setprio 0
	s_mov_b32 m0, s90
	s_mov_b32 s58, s78
	s_mov_b32 s59, s79
	ds_read_b128 v[162:165], v221 offset:16384
	ds_read_b128 v[170:173], v221 offset:17408
	ds_read_b128 v[182:185], v221 offset:18432
	ds_read_b128 v[186:189], v221 offset:19456
	ds_read_b128 v[190:193], v221 offset:20480
	ds_read_b128 v[194:197], v221 offset:21504
	ds_read_b128 v[198:201], v221 offset:22528
	ds_read_b128 v[202:205], v221 offset:23552
	buffer_load_dwordx4 v179, s[56:59], s31 offen lds
	s_mov_b32 m0, s91
	s_add_i32 s51, s31, 0x80000
	buffer_load_dwordx4 v211, s[56:59], s31 offen lds
	s_mov_b32 m0, s9
	s_nop 0
	buffer_load_dwordx4 v179, s[56:59], s51 offen lds
	s_mov_b32 m0, s10
	s_nop 0
	buffer_load_dwordx4 v211, s[56:59], s51 offen lds
	s_mov_b32 m0, s89
	s_nop 0
	buffer_load_dwordx4 v178, s[76:79], s50 offen lds
	s_mov_b32 m0, s11
	s_nop 0
	buffer_load_dwordx4 v210, s[76:79], s50 offen lds
	s_waitcnt vmcnt(8)
	s_waitcnt lgkmcnt(0)
	s_setprio 1
	s_barrier
	v_mfma_f32_16x16x32_bf16 v[94:97], v[130:133], v[162:165], v[94:97]
	v_mfma_f32_16x16x32_bf16 v[94:97], v[134:137], v[170:173], v[94:97]
	v_mfma_f32_16x16x32_bf16 v[78:81], v[142:145], v[170:173], v[78:81]
	v_mfma_f32_16x16x32_bf16 v[78:81], v[138:141], v[162:165], v[78:81]
	v_mfma_f32_16x16x32_bf16 v[70:73], v[138:141], v[182:185], v[70:73]
	v_mfma_f32_16x16x32_bf16 v[70:73], v[142:145], v[186:189], v[70:73]
	v_mfma_f32_16x16x32_bf16 v[86:89], v[134:137], v[186:189], v[86:89]
	v_mfma_f32_16x16x32_bf16 v[86:89], v[130:133], v[182:185], v[86:89]
	v_mfma_f32_16x16x32_bf16 v[82:85], v[130:133], v[190:193], v[82:85]
	v_mfma_f32_16x16x32_bf16 v[82:85], v[134:137], v[194:197], v[82:85]
	v_mfma_f32_16x16x32_bf16 v[66:69], v[142:145], v[194:197], v[66:69]
	v_mfma_f32_16x16x32_bf16 v[66:69], v[138:141], v[190:193], v[66:69]
	v_mfma_f32_16x16x32_bf16 v[74:77], v[138:141], v[198:201], v[74:77]
	v_mfma_f32_16x16x32_bf16 v[74:77], v[142:145], v[202:205], v[74:77]
	v_mfma_f32_16x16x32_bf16 v[90:93], v[134:137], v[202:205], v[90:93]
	v_mfma_f32_16x16x32_bf16 v[90:93], v[130:133], v[198:201], v[90:93]
	v_mfma_f32_16x16x32_bf16 v[30:33], v[146:149], v[162:165], v[30:33]
	v_mfma_f32_16x16x32_bf16 v[30:33], v[150:153], v[170:173], v[30:33]
	v_mfma_f32_16x16x32_bf16 v[14:17], v[158:161], v[170:173], v[14:17]
	v_mfma_f32_16x16x32_bf16 v[14:17], v[154:157], v[162:165], v[14:17]
	v_mfma_f32_16x16x32_bf16 v[10:13], v[154:157], v[182:185], v[10:13]
	v_mfma_f32_16x16x32_bf16 v[10:13], v[158:161], v[186:189], v[10:13]
	v_mfma_f32_16x16x32_bf16 v[22:25], v[150:153], v[186:189], v[22:25]
	v_mfma_f32_16x16x32_bf16 v[22:25], v[146:149], v[182:185], v[22:25]
	v_mfma_f32_16x16x32_bf16 v[18:21], v[146:149], v[190:193], v[18:21]
	v_mfma_f32_16x16x32_bf16 v[18:21], v[150:153], v[194:197], v[18:21]
	v_mfma_f32_16x16x32_bf16 v[2:5], v[158:161], v[194:197], v[2:5]
	v_mfma_f32_16x16x32_bf16 v[2:5], v[154:157], v[190:193], v[2:5]
	v_mfma_f32_16x16x32_bf16 v[6:9], v[154:157], v[198:201], v[6:9]
	v_mfma_f32_16x16x32_bf16 v[6:9], v[158:161], v[202:205], v[6:9]
	v_mfma_f32_16x16x32_bf16 v[26:29], v[150:153], v[202:205], v[26:29]
	v_mfma_f32_16x16x32_bf16 v[26:29], v[146:149], v[198:201], v[26:29]
	s_barrier
; #define PG8_STAGEX(rs, bufoff, soff, voff) do { _Pragma("unroll") for (int _i = 0; _i < 2; ++_i) \
;         __builtin_amdgcn_raw_ptr_buffer_load_lds(rs, (LAS unsigned*)(lds + (bufoff) + ldsw + _i * 8192), 16, (voff)[_i], (soff), 0, 0); } while (0)
; #define PG8_LDA(dst, b, h) do { _Pragma("unroll") for (int m = 0; m < 4; ++m) _Pragma("unroll") for (int k = 0; k < 2; ++k) dst[m][k] = *(const LAS bf16x8*)(lds + PG8_SA(b, h) + aoff + m * 2048 + k * 1024); } while (0)
; #define PG8_LDB(dst, b, h) do { _Pragma("unroll") for (int n = 0; n < 2; ++n) _Pragma("unroll") for (int k = 0; k < 2; ++k) dst[n][k] = *(const LAS bf16x8*)(lds + PG8_SB(b, h) + boff + n * 2048 + k * 1024); } while (0)
; #define PG8_WAIT_V(n) asm volatile("s_waitcnt vmcnt(" #n ")" ::: "memory")
; #define PG8_WAIT_L(n) asm volatile("s_waitcnt lgkmcnt(" #n ")" ::: "memory")
; #define PG8_BAR __builtin_amdgcn_s_barrier()
; #define PG8_SCHED __builtin_amdgcn_sched_barrier(0)
;     ...
;             PG8_LDB(B0, 1, 0); PG8_LDB(B1, 1, 1); PG8_SCHED; PG8_LDA(At, 1, 0); PG8_STAGEX(rsA, PG8_SA(0, 1), a2 + hstepA, voffA);
;             PG8_WAIT_V(8); PG8_WAIT_L(0); PG8_BAR; PG8_MMA(0, 0, At, B0); PG8_MMA(0, 1, At, B1); PG8_BAR; PG8_SCHED;
;             PG8_LDA(At, 1, 1); PG8_STAGEX(rsB, PG8_SB(1, 0), b3, voffB); PG8_STAGEX(rsB, PG8_SB(1, 1), b3 + hstepB, voffB); PG8_STAGEX(rsA, PG8_SA(1, 0), a3, voffA);
;             PG8_WAIT_V(8); PG8_WAIT_L(0); PG8_BAR; PG8_MMA(1, 0, At, B0); PG8_MMA(1, 1, At, B1); PG8_BAR; PG8_SCHED;
;         }
;     ...
;         if (wr == 0) PG8_BAR;
	s_setprio 0
	v_add_u32_e32 v142, 0x18000, v220
	v_add_u32_e32 v158, 0x1c000, v220
	ds_read_b128 v[130:133], v142
	ds_read_b128 v[134:137], v142 offset:1024
	ds_read_b128 v[138:141], v142 offset:2048
	ds_read_b128 v[142:145], v142 offset:3072
	ds_read_b128 v[146:149], v158
	ds_read_b128 v[150:153], v158 offset:1024
	ds_read_b128 v[154:157], v158 offset:2048
	ds_read_b128 v[158:161], v158 offset:3072
	s_add_i32 s50, s50, 0x80000
	s_mov_b32 m0, s74
	ds_read_b128 v[162:165], v221 offset:32768
	ds_read_b128 v[170:173], v221 offset:33792
	ds_read_b128 v[182:185], v221 offset:34816
	ds_read_b128 v[186:189], v221 offset:35840
	ds_read_b128 v[190:193], v221 offset:36864
	ds_read_b128 v[194:197], v221 offset:37888
	ds_read_b128 v[198:201], v221 offset:38912
	ds_read_b128 v[202:205], v221 offset:39936
	buffer_load_dwordx4 v178, s[76:79], s50 offen lds
	s_mov_b32 m0, s12
	s_nop 0
	buffer_load_dwordx4 v210, s[76:79], s50 offen lds
	s_waitcnt vmcnt(8)
	s_waitcnt lgkmcnt(0)
	s_setprio 1
	s_barrier
	v_mfma_f32_16x16x32_bf16 v[126:129], v[130:133], v[162:165], v[126:129]
	v_mfma_f32_16x16x32_bf16 v[126:129], v[134:137], v[170:173], v[126:129]
	v_mfma_f32_16x16x32_bf16 v[110:113], v[142:145], v[170:173], v[110:113]
	v_mfma_f32_16x16x32_bf16 v[110:113], v[138:141], v[162:165], v[110:113]
	v_mfma_f32_16x16x32_bf16 v[102:105], v[138:141], v[182:185], v[102:105]
	v_mfma_f32_16x16x32_bf16 v[102:105], v[142:145], v[186:189], v[102:105]
	v_mfma_f32_16x16x32_bf16 v[118:121], v[134:137], v[186:189], v[118:121]
	v_mfma_f32_16x16x32_bf16 v[118:121], v[130:133], v[182:185], v[118:121]
	v_mfma_f32_16x16x32_bf16 v[114:117], v[130:133], v[190:193], v[114:117]
	v_mfma_f32_16x16x32_bf16 v[114:117], v[134:137], v[194:197], v[114:117]
	v_mfma_f32_16x16x32_bf16 v[98:101], v[142:145], v[194:197], v[98:101]
	v_mfma_f32_16x16x32_bf16 v[98:101], v[138:141], v[190:193], v[98:101]
	v_mfma_f32_16x16x32_bf16 v[106:109], v[138:141], v[198:201], v[106:109]
	v_mfma_f32_16x16x32_bf16 v[106:109], v[142:145], v[202:205], v[106:109]
	v_mfma_f32_16x16x32_bf16 v[122:125], v[134:137], v[202:205], v[122:125]
	v_mfma_f32_16x16x32_bf16 v[122:125], v[130:133], v[198:201], v[122:125]
	v_mfma_f32_16x16x32_bf16 v[62:65], v[146:149], v[162:165], v[62:65]
	v_mfma_f32_16x16x32_bf16 v[62:65], v[150:153], v[170:173], v[62:65]
	v_mfma_f32_16x16x32_bf16 v[46:49], v[158:161], v[170:173], v[46:49]
	v_mfma_f32_16x16x32_bf16 v[46:49], v[154:157], v[162:165], v[46:49]
	v_mfma_f32_16x16x32_bf16 v[38:41], v[154:157], v[182:185], v[38:41]
	v_mfma_f32_16x16x32_bf16 v[38:41], v[158:161], v[186:189], v[38:41]
	v_mfma_f32_16x16x32_bf16 v[54:57], v[150:153], v[186:189], v[54:57]
	v_mfma_f32_16x16x32_bf16 v[54:57], v[146:149], v[182:185], v[54:57]
	v_mfma_f32_16x16x32_bf16 v[50:53], v[146:149], v[190:193], v[50:53]
	v_mfma_f32_16x16x32_bf16 v[50:53], v[150:153], v[194:197], v[50:53]
	v_mfma_f32_16x16x32_bf16 v[34:37], v[158:161], v[194:197], v[34:37]
	v_mfma_f32_16x16x32_bf16 v[34:37], v[154:157], v[190:193], v[34:37]
	v_mfma_f32_16x16x32_bf16 v[42:45], v[154:157], v[198:201], v[42:45]
	v_mfma_f32_16x16x32_bf16 v[42:45], v[158:161], v[202:205], v[42:45]
	v_mfma_f32_16x16x32_bf16 v[58:61], v[150:153], v[202:205], v[58:61]
	v_mfma_f32_16x16x32_bf16 v[58:61], v[146:149], v[198:201], v[58:61]
	s_barrier
	s_setprio 0
	s_mov_b32 m0, s13
	s_or_b32 s50, s31, 0x80
	ds_read_b128 v[162:165], v221 offset:49152
	ds_read_b128 v[170:173], v221 offset:50176
	ds_read_b128 v[182:185], v221 offset:51200
	ds_read_b128 v[186:189], v221 offset:52224
	ds_read_b128 v[190:193], v221 offset:53248
	ds_read_b128 v[194:197], v221 offset:54272
	ds_read_b128 v[198:201], v221 offset:55296
	ds_read_b128 v[202:205], v221 offset:56320
	buffer_load_dwordx4 v179, s[56:59], s50 offen lds
	s_mov_b32 m0, s14
	s_add_i32 s31, s31, 0x80080
	buffer_load_dwordx4 v211, s[56:59], s50 offen lds
	s_mov_b32 m0, s17
	s_nop 0
	buffer_load_dwordx4 v179, s[56:59], s31 offen lds
	s_mov_b32 m0, s18
	s_nop 0
	buffer_load_dwordx4 v211, s[56:59], s31 offen lds
	s_mov_b32 m0, s15
	s_nop 0
	buffer_load_dwordx4 v178, s[76:79], s30 offen lds
	s_mov_b32 m0, s16
	s_nop 0
	buffer_load_dwordx4 v210, s[76:79], s30 offen lds
	s_waitcnt vmcnt(8)
	s_waitcnt lgkmcnt(0)
	s_setprio 1
	s_barrier
	v_mfma_f32_16x16x32_bf16 v[94:97], v[130:133], v[162:165], v[94:97]
	v_mfma_f32_16x16x32_bf16 v[94:97], v[134:137], v[170:173], v[94:97]
	v_mfma_f32_16x16x32_bf16 v[78:81], v[142:145], v[170:173], v[78:81]
	v_mfma_f32_16x16x32_bf16 v[78:81], v[138:141], v[162:165], v[78:81]
	v_mfma_f32_16x16x32_bf16 v[70:73], v[138:141], v[182:185], v[70:73]
	v_mfma_f32_16x16x32_bf16 v[70:73], v[142:145], v[186:189], v[70:73]
	v_mfma_f32_16x16x32_bf16 v[86:89], v[134:137], v[186:189], v[86:89]
	v_mfma_f32_16x16x32_bf16 v[86:89], v[130:133], v[182:185], v[86:89]
	v_mfma_f32_16x16x32_bf16 v[82:85], v[130:133], v[190:193], v[82:85]
	v_mfma_f32_16x16x32_bf16 v[82:85], v[134:137], v[194:197], v[82:85]
	v_mfma_f32_16x16x32_bf16 v[66:69], v[142:145], v[194:197], v[66:69]
	v_mfma_f32_16x16x32_bf16 v[66:69], v[138:141], v[190:193], v[66:69]
	v_mfma_f32_16x16x32_bf16 v[74:77], v[138:141], v[198:201], v[74:77]
	v_mfma_f32_16x16x32_bf16 v[74:77], v[142:145], v[202:205], v[74:77]
	v_mfma_f32_16x16x32_bf16 v[90:93], v[134:137], v[202:205], v[90:93]
	v_mfma_f32_16x16x32_bf16 v[90:93], v[130:133], v[198:201], v[90:93]
	v_mfma_f32_16x16x32_bf16 v[30:33], v[146:149], v[162:165], v[30:33]
	v_mfma_f32_16x16x32_bf16 v[30:33], v[150:153], v[170:173], v[30:33]
	v_mfma_f32_16x16x32_bf16 v[14:17], v[158:161], v[170:173], v[14:17]
	v_mfma_f32_16x16x32_bf16 v[14:17], v[154:157], v[162:165], v[14:17]
	v_mfma_f32_16x16x32_bf16 v[10:13], v[154:157], v[182:185], v[10:13]
	v_mfma_f32_16x16x32_bf16 v[10:13], v[158:161], v[186:189], v[10:13]
	v_mfma_f32_16x16x32_bf16 v[22:25], v[150:153], v[186:189], v[22:25]
	v_mfma_f32_16x16x32_bf16 v[22:25], v[146:149], v[182:185], v[22:25]
	v_mfma_f32_16x16x32_bf16 v[18:21], v[146:149], v[190:193], v[18:21]
	v_mfma_f32_16x16x32_bf16 v[18:21], v[150:153], v[194:197], v[18:21]
	v_mfma_f32_16x16x32_bf16 v[2:5], v[158:161], v[194:197], v[2:5]
	v_mfma_f32_16x16x32_bf16 v[2:5], v[154:157], v[190:193], v[2:5]
	v_mfma_f32_16x16x32_bf16 v[6:9], v[154:157], v[198:201], v[6:9]
	v_mfma_f32_16x16x32_bf16 v[6:9], v[158:161], v[202:205], v[6:9]
	v_mfma_f32_16x16x32_bf16 v[26:29], v[150:153], v[202:205], v[26:29]
	v_mfma_f32_16x16x32_bf16 v[26:29], v[146:149], v[198:201], v[26:29]
	s_barrier
	s_setprio 0
	s_add_i32 s29, s29, 2
	s_addk_i32 s7, 0x100
	s_addk_i32 s28, 0x100
	s_cmp_gt_u32 s29, 29
	s_cbranch_scc0 .LBB0_437
	s_and_b64 vcc, exec, s[84:85]
	s_cbranch_vccz .LBB0_440
	s_barrier

; #define PG8_STAGEX(rs, bufoff, soff, voff) do { _Pragma("unroll") for (int _i = 0; _i < 2; ++_i) \
;         __builtin_amdgcn_raw_ptr_buffer_load_lds(rs, (LAS unsigned*)(lds + (bufoff) + ldsw + _i * 8192), 16, (voff)[_i], (soff), 0, 0); } while (0)
; #define PG8_LDA(dst, b, h) do { _Pragma("unroll") for (int m = 0; m < 4; ++m) _Pragma("unroll") for (int k = 0; k < 2; ++k) dst[m][k] = *(const LAS bf16x8*)(lds + PG8_SA(b, h) + aoff + m * 2048 + k * 1024); } while (0)
; #define PG8_LDB(dst, b, h) do { _Pragma("unroll") for (int n = 0; n < 2; ++n) _Pragma("unroll") for (int k = 0; k < 2; ++k) dst[n][k] = *(const LAS bf16x8*)(lds + PG8_SB(b, h) + boff + n * 2048 + k * 1024); } while (0)
; #define PG8_WAIT_V(n) asm volatile("s_waitcnt vmcnt(" #n ")" ::: "memory")
; #define PG8_WAIT_L(n) asm volatile("s_waitcnt lgkmcnt(" #n ")" ::: "memory")
; #define PG8_BAR __builtin_amdgcn_s_barrier()
; #define PG8_SCHED __builtin_amdgcn_sched_barrier(0)
;     ...
;             for (int t = 0; t < nt; t += 2) {
;                 const bool last = (t == nt - 2);
;                 const unsigned a1 = cA + (unsigned)(t + 1) * kstep;
;                 const unsigned a2 = last ? nA : cA + (unsigned)(t + 2) * kstep, b2 = last ? nB : cB + (unsigned)(t + 2) * kstep;
;                 const unsigned a3 = a2 + kstep, b3 = b2 + kstep;
;                 if (w0) { PG8_LDB(B0, 0, 0); PG8_LDB(B1, 0, 1); PG8_SCHED; PG8_LDA(At, 0, 0); }
;                 PG8_WAIT_L(0); PG8_BAR; if (w0) { PG8_MMA(0, 0, At, B0); PG8_MMA(0, 1, At, B1); } PG8_BAR; PG8_SCHED;
;                 PG8_STAGEX(rsB, PG8_SB(0, 0), b2, voffB); PG8_STAGEX(rsB, PG8_SB(0, 1), b2 + hstepB, voffB); PG8_STAGEX(rsA, PG8_SA(0, 0), a2, voffA);
;                 PG8_WAIT_V(6); PG8_BAR; PG8_BAR; PG8_SCHED;
.LBB0_542:
	v_add_u32_e32 v73, 0x10000, v71
	ds_read_b128 v[74:77], v73
	ds_read_b128 v[78:81], v73 offset:1024
	ds_read_b128 v[82:85], v73 offset:2048
	ds_read_b128 v[86:89], v73 offset:3072
	v_add_u32_e32 v73, 0x14000, v71
	ds_read_b128 v[90:93], v73
	ds_read_b128 v[94:97], v73 offset:1024
	ds_read_b128 v[98:101], v73 offset:2048
	ds_read_b128 v[110:113], v73 offset:3072
	s_cmp_lg_u32 s26, 28
	s_cselect_b32 s27, s25, 0
	s_add_i32 s28, s27, s17
	s_or_b32 s29, s28, 0x80
	s_add_i32 s27, s27, s10
	ds_read_b128 v[114:117], v72
	ds_read_b128 v[118:121], v72 offset:1024
	ds_read_b128 v[122:125], v72 offset:2048
	ds_read_b128 v[126:129], v72 offset:3072
	ds_read_b128 v[130:133], v72 offset:4096
	ds_read_b128 v[134:137], v72 offset:5120
	ds_read_b128 v[138:141], v72 offset:6144
	ds_read_b128 v[142:145], v72 offset:7168
	s_waitcnt lgkmcnt(0)
	s_setprio 1
	s_barrier
	v_mfma_f32_16x16x32_bf16 v[62:65], v[74:77], v[114:117], v[62:65]
	v_mfma_f32_16x16x32_bf16 v[62:65], v[78:81], v[118:121], v[62:65]
	v_mfma_f32_16x16x32_bf16 v[46:49], v[86:89], v[118:121], v[46:49]
	v_mfma_f32_16x16x32_bf16 v[46:49], v[82:85], v[114:117], v[46:49]
	v_mfma_f32_16x16x32_bf16 v[38:41], v[82:85], v[122:125], v[38:41]
	v_mfma_f32_16x16x32_bf16 v[38:41], v[86:89], v[126:129], v[38:41]
	v_mfma_f32_16x16x32_bf16 v[54:57], v[78:81], v[126:129], v[54:57]
	v_mfma_f32_16x16x32_bf16 v[54:57], v[74:77], v[122:125], v[54:57]
	v_mfma_f32_16x16x32_bf16 v[50:53], v[74:77], v[130:133], v[50:53]
	v_mfma_f32_16x16x32_bf16 v[50:53], v[78:81], v[134:137], v[50:53]
	v_mfma_f32_16x16x32_bf16 v[34:37], v[86:89], v[134:137], v[34:37]
	v_mfma_f32_16x16x32_bf16 v[34:37], v[82:85], v[130:133], v[34:37]
	v_mfma_f32_16x16x32_bf16 v[42:45], v[82:85], v[138:141], v[42:45]
	v_mfma_f32_16x16x32_bf16 v[42:45], v[86:89], v[142:145], v[42:45]
	v_mfma_f32_16x16x32_bf16 v[58:61], v[78:81], v[142:145], v[58:61]
	v_mfma_f32_16x16x32_bf16 v[58:61], v[74:77], v[138:141], v[58:61]
	v_mfma_f32_16x16x32_bf16 v[30:33], v[90:93], v[114:117], v[30:33]
	v_mfma_f32_16x16x32_bf16 v[30:33], v[94:97], v[118:121], v[30:33]
	v_mfma_f32_16x16x32_bf16 v[14:17], v[110:113], v[118:121], v[14:17]
	v_mfma_f32_16x16x32_bf16 v[14:17], v[98:101], v[114:117], v[14:17]
	v_mfma_f32_16x16x32_bf16 v[10:13], v[98:101], v[122:125], v[10:13]
	v_mfma_f32_16x16x32_bf16 v[10:13], v[110:113], v[126:129], v[10:13]
	v_mfma_f32_16x16x32_bf16 v[22:25], v[94:97], v[126:129], v[22:25]
	v_mfma_f32_16x16x32_bf16 v[22:25], v[90:93], v[122:125], v[22:25]
	v_mfma_f32_16x16x32_bf16 v[18:21], v[90:93], v[130:133], v[18:21]
	v_mfma_f32_16x16x32_bf16 v[18:21], v[94:97], v[134:137], v[18:21]
	v_mfma_f32_16x16x32_bf16 v[2:5], v[110:113], v[134:137], v[2:5]
	v_mfma_f32_16x16x32_bf16 v[2:5], v[98:101], v[130:133], v[2:5]
	v_mfma_f32_16x16x32_bf16 v[6:9], v[98:101], v[138:141], v[6:9]
	v_mfma_f32_16x16x32_bf16 v[6:9], v[110:113], v[142:145], v[6:9]
	v_mfma_f32_16x16x32_bf16 v[26:29], v[94:97], v[142:145], v[26:29]
	v_mfma_f32_16x16x32_bf16 v[26:29], v[90:93], v[138:141], v[26:29]
	s_barrier
	s_setprio 0
	s_mov_b32 m0, s12
	s_mov_b32 s58, s78
	s_mov_b32 s59, s79
	buffer_load_dwordx4 v67, s[56:59], s27 offen lds
	s_mov_b32 m0, s13
	s_add_i32 s30, s27, 0x80000
	buffer_load_dwordx4 v69, s[56:59], s27 offen lds
	s_mov_b32 m0, s14
	s_nop 0
	buffer_load_dwordx4 v67, s[56:59], s30 offen lds
	s_mov_b32 m0, s15
	s_nop 0
	buffer_load_dwordx4 v69, s[56:59], s30 offen lds
	s_mov_b32 m0, s11
	s_nop 0
	buffer_load_dwordx4 v66, s[76:79], s28 offen lds
	s_mov_b32 m0, s18
	s_nop 0
	buffer_load_dwordx4 v68, s[76:79], s28 offen lds
	s_waitcnt vmcnt(6)
	s_barrier
	s_barrier
; #define PG8_STAGEX(rs, bufoff, soff, voff) do { _Pragma("unroll") for (int _i = 0; _i < 2; ++_i) \
;         __builtin_amdgcn_raw_ptr_buffer_load_lds(rs, (LAS unsigned*)(lds + (bufoff) + ldsw + _i * 8192), 16, (voff)[_i], (soff), 0, 0); } while (0)
; #define PG8_LDA(dst, b, h) do { _Pragma("unroll") for (int m = 0; m < 4; ++m) _Pragma("unroll") for (int k = 0; k < 2; ++k) dst[m][k] = *(const LAS bf16x8*)(lds + PG8_SA(b, h) + aoff + m * 2048 + k * 1024); } while (0)
; #define PG8_LDB(dst, b, h) do { _Pragma("unroll") for (int n = 0; n < 2; ++n) _Pragma("unroll") for (int k = 0; k < 2; ++k) dst[n][k] = *(const LAS bf16x8*)(lds + PG8_SB(b, h) + boff + n * 2048 + k * 1024); } while (0)
; #define PG8_WAIT_V(n) asm volatile("s_waitcnt vmcnt(" #n ")" ::: "memory")
; #define PG8_WAIT_L(n) asm volatile("s_waitcnt lgkmcnt(" #n ")" ::: "memory")
; #define PG8_BAR __builtin_amdgcn_s_barrier()
; #define PG8_SCHED __builtin_amdgcn_sched_barrier(0)
;     ...
;                 if (w0) { PG8_LDB(B0, 1, 0); PG8_LDB(B1, 1, 1); PG8_SCHED; PG8_LDA(At, 1, 0); }
;                 PG8_WAIT_L(0); PG8_BAR; if (w0) { PG8_MMA(0, 0, At, B0); PG8_MMA(0, 1, At, B1); } PG8_BAR; PG8_SCHED;
;                 PG8_STAGEX(rsB, PG8_SB(1, 0), b3, voffB); PG8_STAGEX(rsB, PG8_SB(1, 1), b3 + hstepB, voffB); PG8_STAGEX(rsA, PG8_SA(1, 0), a3, voffA);
;                 PG8_WAIT_V(6); PG8_BAR; PG8_BAR; PG8_SCHED;
;             }
;         }
;         if (wr == 0) PG8_BAR;
	v_add_u32_e32 v73, 0x18000, v71
	ds_read_b128 v[74:77], v73
	ds_read_b128 v[78:81], v73 offset:1024
	ds_read_b128 v[82:85], v73 offset:2048
	ds_read_b128 v[86:89], v73 offset:3072
	v_add_u32_e32 v73, 0x1c000, v71
	ds_read_b128 v[90:93], v73
	ds_read_b128 v[94:97], v73 offset:1024
	ds_read_b128 v[98:101], v73 offset:2048
	ds_read_b128 v[110:113], v73 offset:3072
	ds_read_b128 v[114:117], v72 offset:32768
	ds_read_b128 v[118:121], v72 offset:33792
	ds_read_b128 v[122:125], v72 offset:34816
	ds_read_b128 v[126:129], v72 offset:35840
	ds_read_b128 v[130:133], v72 offset:36864
	ds_read_b128 v[134:137], v72 offset:37888
	ds_read_b128 v[138:141], v72 offset:38912
	ds_read_b128 v[142:145], v72 offset:39936
	s_waitcnt lgkmcnt(0)
	s_setprio 1
	s_barrier
	v_mfma_f32_16x16x32_bf16 v[62:65], v[74:77], v[114:117], v[62:65]
	v_mfma_f32_16x16x32_bf16 v[46:49], v[82:85], v[114:117], v[46:49]
	v_mfma_f32_16x16x32_bf16 v[54:57], v[74:77], v[122:125], v[54:57]
	v_mfma_f32_16x16x32_bf16 v[38:41], v[82:85], v[122:125], v[38:41]
	v_mfma_f32_16x16x32_bf16 v[50:53], v[74:77], v[130:133], v[50:53]
	v_mfma_f32_16x16x32_bf16 v[34:37], v[82:85], v[130:133], v[34:37]
	v_mfma_f32_16x16x32_bf16 v[58:61], v[74:77], v[138:141], v[58:61]
	v_mfma_f32_16x16x32_bf16 v[42:45], v[82:85], v[138:141], v[42:45]
	v_mfma_f32_16x16x32_bf16 v[62:65], v[78:81], v[118:121], v[62:65]
	v_mfma_f32_16x16x32_bf16 v[46:49], v[86:89], v[118:121], v[46:49]
	v_mfma_f32_16x16x32_bf16 v[54:57], v[78:81], v[126:129], v[54:57]
	v_mfma_f32_16x16x32_bf16 v[38:41], v[86:89], v[126:129], v[38:41]
	v_mfma_f32_16x16x32_bf16 v[50:53], v[78:81], v[134:137], v[50:53]
	v_mfma_f32_16x16x32_bf16 v[34:37], v[86:89], v[134:137], v[34:37]
	v_mfma_f32_16x16x32_bf16 v[58:61], v[78:81], v[142:145], v[58:61]
	v_mfma_f32_16x16x32_bf16 v[42:45], v[86:89], v[142:145], v[42:45]
	v_mfma_f32_16x16x32_bf16 v[30:33], v[90:93], v[114:117], v[30:33]
	s_or_b32 s28, s27, 0x80
	v_mfma_f32_16x16x32_bf16 v[14:17], v[98:101], v[114:117], v[14:17]
	v_mfma_f32_16x16x32_bf16 v[22:25], v[90:93], v[122:125], v[22:25]
	v_mfma_f32_16x16x32_bf16 v[10:13], v[98:101], v[122:125], v[10:13]
	v_mfma_f32_16x16x32_bf16 v[18:21], v[90:93], v[130:133], v[18:21]
	v_mfma_f32_16x16x32_bf16 v[2:5], v[98:101], v[130:133], v[2:5]
	v_mfma_f32_16x16x32_bf16 v[26:29], v[90:93], v[138:141], v[26:29]
	v_mfma_f32_16x16x32_bf16 v[6:9], v[98:101], v[138:141], v[6:9]
	v_mfma_f32_16x16x32_bf16 v[30:33], v[94:97], v[118:121], v[30:33]
	v_mfma_f32_16x16x32_bf16 v[14:17], v[110:113], v[118:121], v[14:17]
	v_mfma_f32_16x16x32_bf16 v[22:25], v[94:97], v[126:129], v[22:25]
	v_mfma_f32_16x16x32_bf16 v[10:13], v[110:113], v[126:129], v[10:13]
	v_mfma_f32_16x16x32_bf16 v[18:21], v[94:97], v[134:137], v[18:21]
	v_mfma_f32_16x16x32_bf16 v[2:5], v[110:113], v[134:137], v[2:5]
	v_mfma_f32_16x16x32_bf16 v[26:29], v[94:97], v[142:145], v[26:29]
	v_mfma_f32_16x16x32_bf16 v[6:9], v[110:113], v[142:145], v[6:9]
	s_barrier
	s_setprio 0
	s_mov_b32 m0, s19
	s_add_i32 s27, s27, 0x80080
	buffer_load_dwordx4 v67, s[56:59], s28 offen lds
	s_mov_b32 m0, s20
	s_nop 0
	buffer_load_dwordx4 v69, s[56:59], s28 offen lds
	s_mov_b32 m0, s23
	s_nop 0
	buffer_load_dwordx4 v67, s[56:59], s27 offen lds
	s_mov_b32 m0, s24
	s_nop 0
	buffer_load_dwordx4 v69, s[56:59], s27 offen lds
	s_mov_b32 m0, s21
	s_nop 0
	buffer_load_dwordx4 v66, s[76:79], s29 offen lds
	s_mov_b32 m0, s22
	s_nop 0
	buffer_load_dwordx4 v68, s[76:79], s29 offen lds
	s_waitcnt vmcnt(6)
	s_barrier
	s_barrier
	s_addk_i32 s25, 0x100
	s_add_i32 s26, s26, 2
	s_cmp_gt_u32 s26, 29
	s_cbranch_scc0 .LBB0_542
	s_cmpk_lt_u32 s1, 0x100
	s_cbranch_scc0 .LBB0_545
	s_barrier

; #define PG8_STAGEX(rs, bufoff, soff, voff) do { _Pragma("unroll") for (int _i = 0; _i < 2; ++_i) \
;         __builtin_amdgcn_raw_ptr_buffer_load_lds(rs, (LAS unsigned*)(lds + (bufoff) + ldsw + _i * 8192), 16, (voff)[_i], (soff), 0, 0); } while (0)
; #define PG8_LDA(dst, b, h) do { _Pragma("unroll") for (int m = 0; m < 4; ++m) _Pragma("unroll") for (int k = 0; k < 2; ++k) dst[m][k] = *(const LAS bf16x8*)(lds + PG8_SA(b, h) + aoff + m * 2048 + k * 1024); } while (0)
; #define PG8_LDB(dst, b, h) do { _Pragma("unroll") for (int n = 0; n < 2; ++n) _Pragma("unroll") for (int k = 0; k < 2; ++k) dst[n][k] = *(const LAS bf16x8*)(lds + PG8_SB(b, h) + boff + n * 2048 + k * 1024); } while (0)
; #define PG8_WAIT_V(n) asm volatile("s_waitcnt vmcnt(" #n ")" ::: "memory")
; #define PG8_WAIT_L(n) asm volatile("s_waitcnt lgkmcnt(" #n ")" ::: "memory")
; #define PG8_BAR __builtin_amdgcn_s_barrier()
; #define PG8_SCHED __builtin_amdgcn_sched_barrier(0)
;     ...
;             const unsigned a1 = cA + (unsigned)(t + 1) * kstep;
;             const unsigned a2 = last ? nA : cA + (unsigned)(t + 2) * kstep, b2 = last ? nB : cB + (unsigned)(t + 2) * kstep;
;             const unsigned a3 = a2 + kstep, b3 = b2 + kstep;
;             PG8_LDB(B0, 0, 0); PG8_LDB(B1, 0, 1); PG8_SCHED; PG8_LDA(At, 0, 0); PG8_STAGEX(rsA, PG8_SA(1, 1), a1 + hstepA, voffA);
;             PG8_WAIT_V(8); PG8_WAIT_L(0); PG8_BAR; PG8_MMA(0, 0, At, B0); PG8_MMA(0, 1, At, B1); PG8_BAR; PG8_SCHED;
;             PG8_LDA(At, 0, 1); PG8_STAGEX(rsB, PG8_SB(0, 0), b2, voffB); PG8_STAGEX(rsB, PG8_SB(0, 1), b2 + hstepB, voffB); PG8_STAGEX(rsA, PG8_SA(0, 0), a2, voffA);
;             PG8_WAIT_V(8); PG8_WAIT_L(0); PG8_BAR; PG8_MMA(1, 0, At, B0); PG8_MMA(1, 1, At, B1); PG8_BAR; PG8_SCHED;
.LBB0_788:
	v_add_u32_e32 v150, 0x10000, v153
	ds_read_b128 v[138:141], v150
	ds_read_b128 v[142:145], v150 offset:1024
	ds_read_b128 v[146:149], v150 offset:2048
	ds_read_b128 v[156:159], v150 offset:3072
	v_add_u32_e32 v150, 0x14000, v153
	ds_read_b128 v[160:163], v150
	ds_read_b128 v[164:167], v150 offset:1024
	ds_read_b128 v[182:185], v150 offset:2048
	ds_read_b128 v[186:189], v150 offset:3072
	s_add_i32 s48, s31, 0xfffc0080
	s_cmp_eq_u32 s55, s47
	s_cselect_b32 s50, s7, s48
	s_cselect_b32 s49, s30, s46
	s_add_i32 s48, s50, 0x80
	s_mov_b32 m0, s35
	ds_read_b128 v[190:193], v154
	ds_read_b128 v[194:197], v154 offset:1024
	ds_read_b128 v[198:201], v154 offset:2048
	ds_read_b128 v[202:205], v154 offset:3072
	ds_read_b128 v[206:209], v154 offset:4096
	ds_read_b128 v[210:213], v154 offset:5120
	ds_read_b128 v[214:217], v154 offset:6144
	ds_read_b128 v[218:221], v154 offset:7168
	buffer_load_dwordx4 v130, s[76:79], s31 offen lds
	s_mov_b32 m0, s82
	s_nop 0
	buffer_load_dwordx4 v134, s[76:79], s31 offen lds
	s_waitcnt vmcnt(8)
	s_waitcnt lgkmcnt(0)
	s_setprio 1
	s_barrier
	v_mfma_f32_16x16x32_bf16 v[126:129], v[190:193], v[138:141], v[126:129]
	v_mfma_f32_16x16x32_bf16 v[126:129], v[194:197], v[142:145], v[126:129]
	v_mfma_f32_16x16x32_bf16 v[62:65], v[194:197], v[156:159], v[62:65]
	v_mfma_f32_16x16x32_bf16 v[62:65], v[190:193], v[146:149], v[62:65]
	v_mfma_f32_16x16x32_bf16 v[54:57], v[198:201], v[146:149], v[54:57]
	v_mfma_f32_16x16x32_bf16 v[54:57], v[202:205], v[156:159], v[54:57]
	v_mfma_f32_16x16x32_bf16 v[118:121], v[202:205], v[142:145], v[118:121]
	v_mfma_f32_16x16x32_bf16 v[118:121], v[198:201], v[138:141], v[118:121]
	v_mfma_f32_16x16x32_bf16 v[110:113], v[206:209], v[138:141], v[110:113]
	v_mfma_f32_16x16x32_bf16 v[110:113], v[210:213], v[142:145], v[110:113]
	v_mfma_f32_16x16x32_bf16 v[46:49], v[210:213], v[156:159], v[46:49]
	v_mfma_f32_16x16x32_bf16 v[46:49], v[206:209], v[146:149], v[46:49]
	v_mfma_f32_16x16x32_bf16 v[38:41], v[214:217], v[146:149], v[38:41]
	v_mfma_f32_16x16x32_bf16 v[38:41], v[218:221], v[156:159], v[38:41]
	v_mfma_f32_16x16x32_bf16 v[102:105], v[218:221], v[142:145], v[102:105]
	v_mfma_f32_16x16x32_bf16 v[102:105], v[214:217], v[138:141], v[102:105]
	v_mfma_f32_16x16x32_bf16 v[122:125], v[190:193], v[160:163], v[122:125]
	v_mfma_f32_16x16x32_bf16 v[122:125], v[194:197], v[164:167], v[122:125]
	v_mfma_f32_16x16x32_bf16 v[58:61], v[194:197], v[186:189], v[58:61]
	v_mfma_f32_16x16x32_bf16 v[58:61], v[190:193], v[182:185], v[58:61]
	v_mfma_f32_16x16x32_bf16 v[50:53], v[198:201], v[182:185], v[50:53]
	v_mfma_f32_16x16x32_bf16 v[50:53], v[202:205], v[186:189], v[50:53]
	v_mfma_f32_16x16x32_bf16 v[114:117], v[202:205], v[164:167], v[114:117]
	v_mfma_f32_16x16x32_bf16 v[114:117], v[198:201], v[160:163], v[114:117]
	v_mfma_f32_16x16x32_bf16 v[106:109], v[206:209], v[160:163], v[106:109]
	v_mfma_f32_16x16x32_bf16 v[106:109], v[210:213], v[164:167], v[106:109]
	v_mfma_f32_16x16x32_bf16 v[42:45], v[210:213], v[186:189], v[42:45]
	v_mfma_f32_16x16x32_bf16 v[42:45], v[206:209], v[182:185], v[42:45]
	v_mfma_f32_16x16x32_bf16 v[34:37], v[214:217], v[182:185], v[34:37]
	v_mfma_f32_16x16x32_bf16 v[34:37], v[218:221], v[186:189], v[34:37]
	v_mfma_f32_16x16x32_bf16 v[98:101], v[218:221], v[164:167], v[98:101]
	v_mfma_f32_16x16x32_bf16 v[98:101], v[214:217], v[160:163], v[98:101]
	s_barrier
	s_setprio 0
	s_mov_b32 m0, s15
	s_mov_b32 s86, s78
	s_mov_b32 s87, s79
	ds_read_b128 v[190:193], v154 offset:16384
	ds_read_b128 v[194:197], v154 offset:17408
	ds_read_b128 v[198:201], v154 offset:18432
	ds_read_b128 v[202:205], v154 offset:19456
	ds_read_b128 v[206:209], v154 offset:20480
	ds_read_b128 v[210:213], v154 offset:21504
	ds_read_b128 v[214:217], v154 offset:22528
	ds_read_b128 v[218:221], v154 offset:23552
	buffer_load_dwordx4 v132, s[84:87], s49 offen lds
	s_mov_b32 m0, s16
	s_add_i32 s51, s49, 0x8000
	buffer_load_dwordx4 v136, s[84:87], s49 offen lds
	s_mov_b32 m0, s17
	s_nop 0
	buffer_load_dwordx4 v132, s[84:87], s51 offen lds
	s_mov_b32 m0, s18
	s_nop 0
	buffer_load_dwordx4 v136, s[84:87], s51 offen lds
	s_mov_b32 m0, s14
	s_nop 0
	buffer_load_dwordx4 v130, s[76:79], s50 offen lds
	s_mov_b32 m0, s19
	s_nop 0
	buffer_load_dwordx4 v134, s[76:79], s50 offen lds
	s_waitcnt vmcnt(8)
	s_waitcnt lgkmcnt(0)
	s_setprio 1
	s_barrier
	v_mfma_f32_16x16x32_bf16 v[94:97], v[190:193], v[138:141], v[94:97]
	v_mfma_f32_16x16x32_bf16 v[94:97], v[194:197], v[142:145], v[94:97]
	v_mfma_f32_16x16x32_bf16 v[30:33], v[194:197], v[156:159], v[30:33]
	v_mfma_f32_16x16x32_bf16 v[30:33], v[190:193], v[146:149], v[30:33]
	v_mfma_f32_16x16x32_bf16 v[22:25], v[198:201], v[146:149], v[22:25]
	v_mfma_f32_16x16x32_bf16 v[22:25], v[202:205], v[156:159], v[22:25]
	v_mfma_f32_16x16x32_bf16 v[86:89], v[202:205], v[142:145], v[86:89]
	v_mfma_f32_16x16x32_bf16 v[86:89], v[198:201], v[138:141], v[86:89]
	v_mfma_f32_16x16x32_bf16 v[78:81], v[206:209], v[138:141], v[78:81]
	v_mfma_f32_16x16x32_bf16 v[78:81], v[210:213], v[142:145], v[78:81]
	v_mfma_f32_16x16x32_bf16 v[14:17], v[210:213], v[156:159], v[14:17]
	v_mfma_f32_16x16x32_bf16 v[14:17], v[206:209], v[146:149], v[14:17]
	v_mfma_f32_16x16x32_bf16 v[6:9], v[214:217], v[146:149], v[6:9]
	v_mfma_f32_16x16x32_bf16 v[6:9], v[218:221], v[156:159], v[6:9]
	v_mfma_f32_16x16x32_bf16 v[70:73], v[218:221], v[142:145], v[70:73]
	v_mfma_f32_16x16x32_bf16 v[70:73], v[214:217], v[138:141], v[70:73]
	v_mfma_f32_16x16x32_bf16 v[90:93], v[190:193], v[160:163], v[90:93]
	v_mfma_f32_16x16x32_bf16 v[90:93], v[194:197], v[164:167], v[90:93]
	v_mfma_f32_16x16x32_bf16 v[26:29], v[194:197], v[186:189], v[26:29]
	v_mfma_f32_16x16x32_bf16 v[26:29], v[190:193], v[182:185], v[26:29]
	v_mfma_f32_16x16x32_bf16 v[18:21], v[198:201], v[182:185], v[18:21]
	v_mfma_f32_16x16x32_bf16 v[18:21], v[202:205], v[186:189], v[18:21]
	v_mfma_f32_16x16x32_bf16 v[82:85], v[202:205], v[164:167], v[82:85]
	v_mfma_f32_16x16x32_bf16 v[82:85], v[198:201], v[160:163], v[82:85]
	v_mfma_f32_16x16x32_bf16 v[74:77], v[206:209], v[160:163], v[74:77]
	v_mfma_f32_16x16x32_bf16 v[74:77], v[210:213], v[164:167], v[74:77]
	v_mfma_f32_16x16x32_bf16 v[10:13], v[210:213], v[186:189], v[10:13]
	v_mfma_f32_16x16x32_bf16 v[10:13], v[206:209], v[182:185], v[10:13]
	v_mfma_f32_16x16x32_bf16 v[2:5], v[214:217], v[182:185], v[2:5]
	v_mfma_f32_16x16x32_bf16 v[2:5], v[218:221], v[186:189], v[2:5]
	v_mfma_f32_16x16x32_bf16 v[66:69], v[218:221], v[164:167], v[66:69]
	v_mfma_f32_16x16x32_bf16 v[66:69], v[214:217], v[160:163], v[66:69]
	s_barrier
; #define PG8_STAGEX(rs, bufoff, soff, voff) do { _Pragma("unroll") for (int _i = 0; _i < 2; ++_i) \
;         __builtin_amdgcn_raw_ptr_buffer_load_lds(rs, (LAS unsigned*)(lds + (bufoff) + ldsw + _i * 8192), 16, (voff)[_i], (soff), 0, 0); } while (0)
; #define PG8_LDA(dst, b, h) do { _Pragma("unroll") for (int m = 0; m < 4; ++m) _Pragma("unroll") for (int k = 0; k < 2; ++k) dst[m][k] = *(const LAS bf16x8*)(lds + PG8_SA(b, h) + aoff + m * 2048 + k * 1024); } while (0)
; #define PG8_LDB(dst, b, h) do { _Pragma("unroll") for (int n = 0; n < 2; ++n) _Pragma("unroll") for (int k = 0; k < 2; ++k) dst[n][k] = *(const LAS bf16x8*)(lds + PG8_SB(b, h) + boff + n * 2048 + k * 1024); } while (0)
; #define PG8_WAIT_V(n) asm volatile("s_waitcnt vmcnt(" #n ")" ::: "memory")
; #define PG8_WAIT_L(n) asm volatile("s_waitcnt lgkmcnt(" #n ")" ::: "memory")
; #define PG8_BAR __builtin_amdgcn_s_barrier()
; #define PG8_SCHED __builtin_amdgcn_sched_barrier(0)
;     ...
;             PG8_LDB(B0, 1, 0); PG8_LDB(B1, 1, 1); PG8_SCHED; PG8_LDA(At, 1, 0); PG8_STAGEX(rsA, PG8_SA(0, 1), a2 + hstepA, voffA);
;             PG8_WAIT_V(8); PG8_WAIT_L(0); PG8_BAR; PG8_MMA(0, 0, At, B0); PG8_MMA(0, 1, At, B1); PG8_BAR; PG8_SCHED;
;             PG8_LDA(At, 1, 1); PG8_STAGEX(rsB, PG8_SB(1, 0), b3, voffB); PG8_STAGEX(rsB, PG8_SB(1, 1), b3 + hstepB, voffB); PG8_STAGEX(rsA, PG8_SA(1, 0), a3, voffA);
;             PG8_WAIT_V(8); PG8_WAIT_L(0); PG8_BAR; PG8_MMA(1, 0, At, B0); PG8_MMA(1, 1, At, B1); PG8_BAR; PG8_SCHED;
;     ...
;         }
;         if (wr == 0) PG8_BAR;
	s_setprio 0
	v_add_u32_e32 v150, 0x18000, v153
	ds_read_b128 v[138:141], v150
	ds_read_b128 v[142:145], v150 offset:1024
	ds_read_b128 v[146:149], v150 offset:2048
	ds_read_b128 v[156:159], v150 offset:3072
	v_add_u32_e32 v150, 0x1c000, v153
	ds_read_b128 v[160:163], v150
	ds_read_b128 v[164:167], v150 offset:1024
	ds_read_b128 v[182:185], v150 offset:2048
	ds_read_b128 v[186:189], v150 offset:3072
	s_add_i32 s50, s50, 0x40000
	s_mov_b32 m0, s20
	ds_read_b128 v[190:193], v154 offset:32768
	ds_read_b128 v[194:197], v154 offset:33792
	ds_read_b128 v[198:201], v154 offset:34816
	ds_read_b128 v[202:205], v154 offset:35840
	ds_read_b128 v[206:209], v154 offset:36864
	ds_read_b128 v[210:213], v154 offset:37888
	ds_read_b128 v[214:217], v154 offset:38912
	ds_read_b128 v[218:221], v154 offset:39936
	buffer_load_dwordx4 v130, s[76:79], s50 offen lds
	s_mov_b32 m0, s21
	s_nop 0
	buffer_load_dwordx4 v134, s[76:79], s50 offen lds
	s_waitcnt vmcnt(8)
	s_waitcnt lgkmcnt(0)
	s_setprio 1
	s_barrier
	v_mfma_f32_16x16x32_bf16 v[126:129], v[190:193], v[138:141], v[126:129]
	v_mfma_f32_16x16x32_bf16 v[126:129], v[194:197], v[142:145], v[126:129]
	v_mfma_f32_16x16x32_bf16 v[62:65], v[194:197], v[156:159], v[62:65]
	v_mfma_f32_16x16x32_bf16 v[62:65], v[190:193], v[146:149], v[62:65]
	v_mfma_f32_16x16x32_bf16 v[54:57], v[198:201], v[146:149], v[54:57]
	v_mfma_f32_16x16x32_bf16 v[54:57], v[202:205], v[156:159], v[54:57]
	v_mfma_f32_16x16x32_bf16 v[118:121], v[202:205], v[142:145], v[118:121]
	v_mfma_f32_16x16x32_bf16 v[118:121], v[198:201], v[138:141], v[118:121]
	v_mfma_f32_16x16x32_bf16 v[110:113], v[206:209], v[138:141], v[110:113]
	v_mfma_f32_16x16x32_bf16 v[110:113], v[210:213], v[142:145], v[110:113]
	v_mfma_f32_16x16x32_bf16 v[46:49], v[210:213], v[156:159], v[46:49]
	v_mfma_f32_16x16x32_bf16 v[46:49], v[206:209], v[146:149], v[46:49]
	v_mfma_f32_16x16x32_bf16 v[38:41], v[214:217], v[146:149], v[38:41]
	v_mfma_f32_16x16x32_bf16 v[38:41], v[218:221], v[156:159], v[38:41]
	v_mfma_f32_16x16x32_bf16 v[102:105], v[218:221], v[142:145], v[102:105]
	v_mfma_f32_16x16x32_bf16 v[102:105], v[214:217], v[138:141], v[102:105]
	v_mfma_f32_16x16x32_bf16 v[122:125], v[190:193], v[160:163], v[122:125]
	v_mfma_f32_16x16x32_bf16 v[122:125], v[194:197], v[164:167], v[122:125]
	v_mfma_f32_16x16x32_bf16 v[58:61], v[194:197], v[186:189], v[58:61]
	v_mfma_f32_16x16x32_bf16 v[58:61], v[190:193], v[182:185], v[58:61]
	v_mfma_f32_16x16x32_bf16 v[50:53], v[198:201], v[182:185], v[50:53]
	v_mfma_f32_16x16x32_bf16 v[50:53], v[202:205], v[186:189], v[50:53]
	v_mfma_f32_16x16x32_bf16 v[114:117], v[202:205], v[164:167], v[114:117]
	v_mfma_f32_16x16x32_bf16 v[114:117], v[198:201], v[160:163], v[114:117]
	v_mfma_f32_16x16x32_bf16 v[106:109], v[206:209], v[160:163], v[106:109]
	v_mfma_f32_16x16x32_bf16 v[106:109], v[210:213], v[164:167], v[106:109]
	v_mfma_f32_16x16x32_bf16 v[42:45], v[210:213], v[186:189], v[42:45]
	v_mfma_f32_16x16x32_bf16 v[42:45], v[206:209], v[182:185], v[42:45]
	v_mfma_f32_16x16x32_bf16 v[34:37], v[214:217], v[182:185], v[34:37]
	v_mfma_f32_16x16x32_bf16 v[34:37], v[218:221], v[186:189], v[34:37]
	v_mfma_f32_16x16x32_bf16 v[98:101], v[218:221], v[164:167], v[98:101]
	v_mfma_f32_16x16x32_bf16 v[98:101], v[214:217], v[160:163], v[98:101]
	s_barrier
	s_setprio 0
	s_mov_b32 m0, s93
	s_or_b32 s50, s49, 0x80
	ds_read_b128 v[190:193], v154 offset:49152
	ds_read_b128 v[194:197], v154 offset:50176
	ds_read_b128 v[198:201], v154 offset:51200
	ds_read_b128 v[202:205], v154 offset:52224
	ds_read_b128 v[206:209], v154 offset:53248
	ds_read_b128 v[210:213], v154 offset:54272
	ds_read_b128 v[214:217], v154 offset:55296
	ds_read_b128 v[218:221], v154 offset:56320
	buffer_load_dwordx4 v132, s[84:87], s50 offen lds
	s_mov_b32 m0, s94
	s_add_i32 s49, s49, 0x8080
	buffer_load_dwordx4 v136, s[84:87], s50 offen lds
	s_mov_b32 m0, s9
	s_nop 0
	buffer_load_dwordx4 v132, s[84:87], s49 offen lds
	s_mov_b32 m0, s54
	s_nop 0
	buffer_load_dwordx4 v136, s[84:87], s49 offen lds
	s_mov_b32 m0, s95
	s_nop 0
	buffer_load_dwordx4 v130, s[76:79], s48 offen lds
	s_mov_b32 m0, s97
	s_nop 0
	buffer_load_dwordx4 v134, s[76:79], s48 offen lds
	s_waitcnt vmcnt(8)
	s_waitcnt lgkmcnt(0)
	s_setprio 1
	s_barrier
	v_mfma_f32_16x16x32_bf16 v[94:97], v[190:193], v[138:141], v[94:97]
	v_mfma_f32_16x16x32_bf16 v[94:97], v[194:197], v[142:145], v[94:97]
	v_mfma_f32_16x16x32_bf16 v[30:33], v[194:197], v[156:159], v[30:33]
	v_mfma_f32_16x16x32_bf16 v[30:33], v[190:193], v[146:149], v[30:33]
	v_mfma_f32_16x16x32_bf16 v[22:25], v[198:201], v[146:149], v[22:25]
	v_mfma_f32_16x16x32_bf16 v[22:25], v[202:205], v[156:159], v[22:25]
	v_mfma_f32_16x16x32_bf16 v[86:89], v[202:205], v[142:145], v[86:89]
	v_mfma_f32_16x16x32_bf16 v[86:89], v[198:201], v[138:141], v[86:89]
	v_mfma_f32_16x16x32_bf16 v[78:81], v[206:209], v[138:141], v[78:81]
	v_mfma_f32_16x16x32_bf16 v[78:81], v[210:213], v[142:145], v[78:81]
	v_mfma_f32_16x16x32_bf16 v[14:17], v[210:213], v[156:159], v[14:17]
	v_mfma_f32_16x16x32_bf16 v[14:17], v[206:209], v[146:149], v[14:17]
	v_mfma_f32_16x16x32_bf16 v[6:9], v[214:217], v[146:149], v[6:9]
	v_mfma_f32_16x16x32_bf16 v[6:9], v[218:221], v[156:159], v[6:9]
	v_mfma_f32_16x16x32_bf16 v[70:73], v[218:221], v[142:145], v[70:73]
	v_mfma_f32_16x16x32_bf16 v[70:73], v[214:217], v[138:141], v[70:73]
	v_mfma_f32_16x16x32_bf16 v[90:93], v[190:193], v[160:163], v[90:93]
	v_mfma_f32_16x16x32_bf16 v[90:93], v[194:197], v[164:167], v[90:93]
	v_mfma_f32_16x16x32_bf16 v[26:29], v[194:197], v[186:189], v[26:29]
	v_mfma_f32_16x16x32_bf16 v[26:29], v[190:193], v[182:185], v[26:29]
	v_mfma_f32_16x16x32_bf16 v[18:21], v[198:201], v[182:185], v[18:21]
	v_mfma_f32_16x16x32_bf16 v[18:21], v[202:205], v[186:189], v[18:21]
	v_mfma_f32_16x16x32_bf16 v[82:85], v[202:205], v[164:167], v[82:85]
	v_mfma_f32_16x16x32_bf16 v[82:85], v[198:201], v[160:163], v[82:85]
	v_mfma_f32_16x16x32_bf16 v[74:77], v[206:209], v[160:163], v[74:77]
	v_mfma_f32_16x16x32_bf16 v[74:77], v[210:213], v[164:167], v[74:77]
	v_mfma_f32_16x16x32_bf16 v[10:13], v[210:213], v[186:189], v[10:13]
	v_mfma_f32_16x16x32_bf16 v[10:13], v[206:209], v[182:185], v[10:13]
	v_mfma_f32_16x16x32_bf16 v[2:5], v[214:217], v[182:185], v[2:5]
	v_mfma_f32_16x16x32_bf16 v[2:5], v[218:221], v[186:189], v[2:5]
	v_mfma_f32_16x16x32_bf16 v[66:69], v[218:221], v[164:167], v[66:69]
	v_mfma_f32_16x16x32_bf16 v[66:69], v[214:217], v[160:163], v[66:69]
	s_barrier
	s_setprio 0
	s_add_i32 s47, s47, 2
	s_addk_i32 s31, 0x100
	s_addk_i32 s46, 0x100
	s_cmp_ge_i32 s47, s34
	s_cbranch_scc0 .LBB0_788
	s_mov_b32 s61, s96
	s_and_b64 vcc, exec, s[62:63]
	s_cbranch_vccz .LBB0_791

; #define PG8_STAGEX(rs, bufoff, soff, voff) do { _Pragma("unroll") for (int _i = 0; _i < 2; ++_i) \
;         __builtin_amdgcn_raw_ptr_buffer_load_lds(rs, (LAS unsigned*)(lds + (bufoff) + ldsw + _i * 8192), 16, (voff)[_i], (soff), 0, 0); } while (0)
; #define PG8_LDA(dst, b, h) do { _Pragma("unroll") for (int m = 0; m < 4; ++m) _Pragma("unroll") for (int k = 0; k < 2; ++k) dst[m][k] = *(const LAS bf16x8*)(lds + PG8_SA(b, h) + aoff + m * 2048 + k * 1024); } while (0)
; #define PG8_LDB(dst, b, h) do { _Pragma("unroll") for (int n = 0; n < 2; ++n) _Pragma("unroll") for (int k = 0; k < 2; ++k) dst[n][k] = *(const LAS bf16x8*)(lds + PG8_SB(b, h) + boff + n * 2048 + k * 1024); } while (0)
; #define PG8_WAIT_V(n) asm volatile("s_waitcnt vmcnt(" #n ")" ::: "memory")
; #define PG8_WAIT_L(n) asm volatile("s_waitcnt lgkmcnt(" #n ")" ::: "memory")
; #define PG8_BAR __builtin_amdgcn_s_barrier()
; #define PG8_SCHED __builtin_amdgcn_sched_barrier(0)
;     ...
;             const unsigned a1 = cA + (unsigned)(t + 1) * kstep;
;             const unsigned a2 = last ? nA : cA + (unsigned)(t + 2) * kstep, b2 = last ? nB : cB + (unsigned)(t + 2) * kstep;
;             const unsigned a3 = a2 + kstep, b3 = b2 + kstep;
;             PG8_LDB(B0, 0, 0); PG8_LDB(B1, 0, 1); PG8_SCHED; PG8_LDA(At, 0, 0); PG8_STAGEX(rsA, PG8_SA(1, 1), a1 + hstepA, voffA);
;             PG8_WAIT_V(8); PG8_WAIT_L(0); PG8_BAR; PG8_MMA(0, 0, At, B0); PG8_MMA(0, 1, At, B1); PG8_BAR; PG8_SCHED;
;             PG8_LDA(At, 0, 1); PG8_STAGEX(rsB, PG8_SB(0, 0), b2, voffB); PG8_STAGEX(rsB, PG8_SB(0, 1), b2 + hstepB, voffB); PG8_STAGEX(rsA, PG8_SA(0, 0), a2, voffA);
;             PG8_WAIT_V(8); PG8_WAIT_L(0); PG8_BAR; PG8_MMA(1, 0, At, B0); PG8_MMA(1, 1, At, B1); PG8_BAR; PG8_SCHED;
.LBB0_1274:
	v_add_u32_e32 v142, 0x10000, v157
	v_add_u32_e32 v159, 0x14000, v157
	ds_read_b128 v[130:133], v142
	ds_read_b128 v[134:137], v142 offset:1024
	ds_read_b128 v[138:141], v142 offset:2048
	ds_read_b128 v[142:145], v142 offset:3072
	ds_read_b128 v[146:149], v159
	ds_read_b128 v[164:167], v159 offset:1024
	ds_read_b128 v[168:171], v159 offset:2048
	ds_read_b128 v[182:185], v159 offset:3072
	s_add_i32 s42, s62, 0xfff80080
	s_cmp_eq_u32 s67, 28
	s_cselect_b32 s70, s30, s42
	s_cselect_b32 s69, s31, s63
	s_or_b32 s68, s70, 0x80
	s_mov_b32 m0, s29
	ds_read_b128 v[186:189], v158
	ds_read_b128 v[190:193], v158 offset:1024
	ds_read_b128 v[194:197], v158 offset:2048
	ds_read_b128 v[198:201], v158 offset:3072
	ds_read_b128 v[202:205], v158 offset:4096
	ds_read_b128 v[206:209], v158 offset:5120
	ds_read_b128 v[210:213], v158 offset:6144
	ds_read_b128 v[214:217], v158 offset:7168
	buffer_load_dwordx4 v150, s[76:79], s62 offen lds
	s_mov_b32 m0, s35
	s_nop 0
	buffer_load_dwordx4 v152, s[76:79], s62 offen lds
	s_waitcnt vmcnt(8)
	s_waitcnt lgkmcnt(0)
	s_setprio 1
	s_barrier
	v_mfma_f32_16x16x32_bf16 v[126:129], v[130:133], v[186:189], v[126:129]
	v_mfma_f32_16x16x32_bf16 v[126:129], v[134:137], v[190:193], v[126:129]
	v_mfma_f32_16x16x32_bf16 v[122:125], v[142:145], v[190:193], v[122:125]
	v_mfma_f32_16x16x32_bf16 v[122:125], v[138:141], v[186:189], v[122:125]
	v_mfma_f32_16x16x32_bf16 v[114:117], v[138:141], v[194:197], v[114:117]
	v_mfma_f32_16x16x32_bf16 v[114:117], v[142:145], v[198:201], v[114:117]
	v_mfma_f32_16x16x32_bf16 v[118:121], v[134:137], v[198:201], v[118:121]
	v_mfma_f32_16x16x32_bf16 v[118:121], v[130:133], v[194:197], v[118:121]
	v_mfma_f32_16x16x32_bf16 v[110:113], v[130:133], v[202:205], v[110:113]
	v_mfma_f32_16x16x32_bf16 v[110:113], v[134:137], v[206:209], v[110:113]
	v_mfma_f32_16x16x32_bf16 v[106:109], v[142:145], v[206:209], v[106:109]
	v_mfma_f32_16x16x32_bf16 v[106:109], v[138:141], v[202:205], v[106:109]
	v_mfma_f32_16x16x32_bf16 v[98:101], v[138:141], v[210:213], v[98:101]
	v_mfma_f32_16x16x32_bf16 v[98:101], v[142:145], v[214:217], v[98:101]
	v_mfma_f32_16x16x32_bf16 v[102:105], v[134:137], v[214:217], v[102:105]
	v_mfma_f32_16x16x32_bf16 v[102:105], v[130:133], v[210:213], v[102:105]
	v_mfma_f32_16x16x32_bf16 v[62:65], v[146:149], v[186:189], v[62:65]
	v_mfma_f32_16x16x32_bf16 v[62:65], v[164:167], v[190:193], v[62:65]
	v_mfma_f32_16x16x32_bf16 v[58:61], v[182:185], v[190:193], v[58:61]
	v_mfma_f32_16x16x32_bf16 v[58:61], v[168:171], v[186:189], v[58:61]
	v_mfma_f32_16x16x32_bf16 v[50:53], v[168:171], v[194:197], v[50:53]
	v_mfma_f32_16x16x32_bf16 v[50:53], v[182:185], v[198:201], v[50:53]
	v_mfma_f32_16x16x32_bf16 v[54:57], v[164:167], v[198:201], v[54:57]
	v_mfma_f32_16x16x32_bf16 v[54:57], v[146:149], v[194:197], v[54:57]
	v_mfma_f32_16x16x32_bf16 v[46:49], v[146:149], v[202:205], v[46:49]
	v_mfma_f32_16x16x32_bf16 v[46:49], v[164:167], v[206:209], v[46:49]
	v_mfma_f32_16x16x32_bf16 v[42:45], v[182:185], v[206:209], v[42:45]
	v_mfma_f32_16x16x32_bf16 v[42:45], v[168:171], v[202:205], v[42:45]
	v_mfma_f32_16x16x32_bf16 v[34:37], v[168:171], v[210:213], v[34:37]
	v_mfma_f32_16x16x32_bf16 v[34:37], v[182:185], v[214:217], v[34:37]
	v_mfma_f32_16x16x32_bf16 v[38:41], v[164:167], v[214:217], v[38:41]
	v_mfma_f32_16x16x32_bf16 v[38:41], v[146:149], v[210:213], v[38:41]
	s_barrier
	s_setprio 0
	s_mov_b32 m0, s16
	s_mov_b32 s42, s78
	s_mov_b32 s43, s79
	ds_read_b128 v[186:189], v158 offset:16384
	ds_read_b128 v[190:193], v158 offset:17408
	ds_read_b128 v[194:197], v158 offset:18432
	ds_read_b128 v[198:201], v158 offset:19456
	ds_read_b128 v[202:205], v158 offset:20480
	ds_read_b128 v[206:209], v158 offset:21504
	ds_read_b128 v[210:213], v158 offset:22528
	ds_read_b128 v[214:217], v158 offset:23552
	buffer_load_dwordx4 v151, s[40:43], s69 offen lds
	s_mov_b32 m0, s17
	s_add_i32 s71, s69, 0x80000
	buffer_load_dwordx4 v153, s[40:43], s69 offen lds
	s_mov_b32 m0, s18
	s_nop 0
	buffer_load_dwordx4 v151, s[40:43], s71 offen lds
	s_mov_b32 m0, s19
	s_nop 0
	buffer_load_dwordx4 v153, s[40:43], s71 offen lds
	s_mov_b32 m0, s15
	s_nop 0
	buffer_load_dwordx4 v150, s[76:79], s70 offen lds
	s_mov_b32 m0, s20
	s_nop 0
	buffer_load_dwordx4 v152, s[76:79], s70 offen lds
	s_waitcnt vmcnt(8)
	s_waitcnt lgkmcnt(0)
	s_setprio 1
	s_barrier
	v_mfma_f32_16x16x32_bf16 v[94:97], v[130:133], v[186:189], v[94:97]
	v_mfma_f32_16x16x32_bf16 v[94:97], v[134:137], v[190:193], v[94:97]
	v_mfma_f32_16x16x32_bf16 v[90:93], v[142:145], v[190:193], v[90:93]
	v_mfma_f32_16x16x32_bf16 v[90:93], v[138:141], v[186:189], v[90:93]
	v_mfma_f32_16x16x32_bf16 v[82:85], v[138:141], v[194:197], v[82:85]
	v_mfma_f32_16x16x32_bf16 v[82:85], v[142:145], v[198:201], v[82:85]
	v_mfma_f32_16x16x32_bf16 v[86:89], v[134:137], v[198:201], v[86:89]
	v_mfma_f32_16x16x32_bf16 v[86:89], v[130:133], v[194:197], v[86:89]
	v_mfma_f32_16x16x32_bf16 v[78:81], v[130:133], v[202:205], v[78:81]
	v_mfma_f32_16x16x32_bf16 v[78:81], v[134:137], v[206:209], v[78:81]
	v_mfma_f32_16x16x32_bf16 v[74:77], v[142:145], v[206:209], v[74:77]
	v_mfma_f32_16x16x32_bf16 v[74:77], v[138:141], v[202:205], v[74:77]
	v_mfma_f32_16x16x32_bf16 v[66:69], v[138:141], v[210:213], v[66:69]
	v_mfma_f32_16x16x32_bf16 v[66:69], v[142:145], v[214:217], v[66:69]
	v_mfma_f32_16x16x32_bf16 v[70:73], v[134:137], v[214:217], v[70:73]
	v_mfma_f32_16x16x32_bf16 v[70:73], v[130:133], v[210:213], v[70:73]
	v_mfma_f32_16x16x32_bf16 v[30:33], v[146:149], v[186:189], v[30:33]
	v_mfma_f32_16x16x32_bf16 v[30:33], v[164:167], v[190:193], v[30:33]
	v_mfma_f32_16x16x32_bf16 v[26:29], v[182:185], v[190:193], v[26:29]
	v_mfma_f32_16x16x32_bf16 v[26:29], v[168:171], v[186:189], v[26:29]
	v_mfma_f32_16x16x32_bf16 v[18:21], v[168:171], v[194:197], v[18:21]
	v_mfma_f32_16x16x32_bf16 v[18:21], v[182:185], v[198:201], v[18:21]
	v_mfma_f32_16x16x32_bf16 v[22:25], v[164:167], v[198:201], v[22:25]
	v_mfma_f32_16x16x32_bf16 v[22:25], v[146:149], v[194:197], v[22:25]
	v_mfma_f32_16x16x32_bf16 v[14:17], v[146:149], v[202:205], v[14:17]
	v_mfma_f32_16x16x32_bf16 v[14:17], v[164:167], v[206:209], v[14:17]
	v_mfma_f32_16x16x32_bf16 v[10:13], v[182:185], v[206:209], v[10:13]
	v_mfma_f32_16x16x32_bf16 v[10:13], v[168:171], v[202:205], v[10:13]
	v_mfma_f32_16x16x32_bf16 v[2:5], v[168:171], v[210:213], v[2:5]
	v_mfma_f32_16x16x32_bf16 v[2:5], v[182:185], v[214:217], v[2:5]
	v_mfma_f32_16x16x32_bf16 v[6:9], v[164:167], v[214:217], v[6:9]
	v_mfma_f32_16x16x32_bf16 v[6:9], v[146:149], v[210:213], v[6:9]
	s_barrier
; #define PG8_STAGEX(rs, bufoff, soff, voff) do { _Pragma("unroll") for (int _i = 0; _i < 2; ++_i) \
;         __builtin_amdgcn_raw_ptr_buffer_load_lds(rs, (LAS unsigned*)(lds + (bufoff) + ldsw + _i * 8192), 16, (voff)[_i], (soff), 0, 0); } while (0)
; #define PG8_LDA(dst, b, h) do { _Pragma("unroll") for (int m = 0; m < 4; ++m) _Pragma("unroll") for (int k = 0; k < 2; ++k) dst[m][k] = *(const LAS bf16x8*)(lds + PG8_SA(b, h) + aoff + m * 2048 + k * 1024); } while (0)
; #define PG8_LDB(dst, b, h) do { _Pragma("unroll") for (int n = 0; n < 2; ++n) _Pragma("unroll") for (int k = 0; k < 2; ++k) dst[n][k] = *(const LAS bf16x8*)(lds + PG8_SB(b, h) + boff + n * 2048 + k * 1024); } while (0)
; #define PG8_WAIT_V(n) asm volatile("s_waitcnt vmcnt(" #n ")" ::: "memory")
; #define PG8_WAIT_L(n) asm volatile("s_waitcnt lgkmcnt(" #n ")" ::: "memory")
; #define PG8_BAR __builtin_amdgcn_s_barrier()
; #define PG8_SCHED __builtin_amdgcn_sched_barrier(0)
;     ...
;             PG8_LDB(B0, 1, 0); PG8_LDB(B1, 1, 1); PG8_SCHED; PG8_LDA(At, 1, 0); PG8_STAGEX(rsA, PG8_SA(0, 1), a2 + hstepA, voffA);
;             PG8_WAIT_V(8); PG8_WAIT_L(0); PG8_BAR; PG8_MMA(0, 0, At, B0); PG8_MMA(0, 1, At, B1); PG8_BAR; PG8_SCHED;
;             PG8_LDA(At, 1, 1); PG8_STAGEX(rsB, PG8_SB(1, 0), b3, voffB); PG8_STAGEX(rsB, PG8_SB(1, 1), b3 + hstepB, voffB); PG8_STAGEX(rsA, PG8_SA(1, 0), a3, voffA);
;             PG8_WAIT_V(8); PG8_WAIT_L(0); PG8_BAR; PG8_MMA(1, 0, At, B0); PG8_MMA(1, 1, At, B1); PG8_BAR; PG8_SCHED;
;     ...
;         }
;         if (wr == 0) PG8_BAR;
	s_setprio 0
	v_add_u32_e32 v142, 0x18000, v157
	v_add_u32_e32 v159, 0x1c000, v157
	ds_read_b128 v[130:133], v142
	ds_read_b128 v[134:137], v142 offset:1024
	ds_read_b128 v[138:141], v142 offset:2048
	ds_read_b128 v[142:145], v142 offset:3072
	ds_read_b128 v[146:149], v159
	ds_read_b128 v[164:167], v159 offset:1024
	ds_read_b128 v[168:171], v159 offset:2048
	ds_read_b128 v[182:185], v159 offset:3072
	s_add_i32 s70, s70, 0x80000
	s_mov_b32 m0, s21
	ds_read_b128 v[186:189], v158 offset:32768
	ds_read_b128 v[190:193], v158 offset:33792
	ds_read_b128 v[194:197], v158 offset:34816
	ds_read_b128 v[198:201], v158 offset:35840
	ds_read_b128 v[202:205], v158 offset:36864
	ds_read_b128 v[206:209], v158 offset:37888
	ds_read_b128 v[210:213], v158 offset:38912
	ds_read_b128 v[214:217], v158 offset:39936
	buffer_load_dwordx4 v150, s[76:79], s70 offen lds
	s_mov_b32 m0, s22
	s_nop 0
	buffer_load_dwordx4 v152, s[76:79], s70 offen lds
	s_waitcnt vmcnt(8)
	s_waitcnt lgkmcnt(0)
	s_setprio 1
	s_barrier
	v_mfma_f32_16x16x32_bf16 v[126:129], v[130:133], v[186:189], v[126:129]
	v_mfma_f32_16x16x32_bf16 v[126:129], v[134:137], v[190:193], v[126:129]
	v_mfma_f32_16x16x32_bf16 v[122:125], v[142:145], v[190:193], v[122:125]
	v_mfma_f32_16x16x32_bf16 v[122:125], v[138:141], v[186:189], v[122:125]
	v_mfma_f32_16x16x32_bf16 v[114:117], v[138:141], v[194:197], v[114:117]
	v_mfma_f32_16x16x32_bf16 v[114:117], v[142:145], v[198:201], v[114:117]
	v_mfma_f32_16x16x32_bf16 v[118:121], v[134:137], v[198:201], v[118:121]
	v_mfma_f32_16x16x32_bf16 v[118:121], v[130:133], v[194:197], v[118:121]
	v_mfma_f32_16x16x32_bf16 v[110:113], v[130:133], v[202:205], v[110:113]
	v_mfma_f32_16x16x32_bf16 v[110:113], v[134:137], v[206:209], v[110:113]
	v_mfma_f32_16x16x32_bf16 v[106:109], v[142:145], v[206:209], v[106:109]
	v_mfma_f32_16x16x32_bf16 v[106:109], v[138:141], v[202:205], v[106:109]
	v_mfma_f32_16x16x32_bf16 v[98:101], v[138:141], v[210:213], v[98:101]
	v_mfma_f32_16x16x32_bf16 v[98:101], v[142:145], v[214:217], v[98:101]
	v_mfma_f32_16x16x32_bf16 v[102:105], v[134:137], v[214:217], v[102:105]
	v_mfma_f32_16x16x32_bf16 v[102:105], v[130:133], v[210:213], v[102:105]
	v_mfma_f32_16x16x32_bf16 v[62:65], v[146:149], v[186:189], v[62:65]
	v_mfma_f32_16x16x32_bf16 v[62:65], v[164:167], v[190:193], v[62:65]
	v_mfma_f32_16x16x32_bf16 v[58:61], v[182:185], v[190:193], v[58:61]
	v_mfma_f32_16x16x32_bf16 v[58:61], v[168:171], v[186:189], v[58:61]
	v_mfma_f32_16x16x32_bf16 v[50:53], v[168:171], v[194:197], v[50:53]
	v_mfma_f32_16x16x32_bf16 v[50:53], v[182:185], v[198:201], v[50:53]
	v_mfma_f32_16x16x32_bf16 v[54:57], v[164:167], v[198:201], v[54:57]
	v_mfma_f32_16x16x32_bf16 v[54:57], v[146:149], v[194:197], v[54:57]
	v_mfma_f32_16x16x32_bf16 v[46:49], v[146:149], v[202:205], v[46:49]
	v_mfma_f32_16x16x32_bf16 v[46:49], v[164:167], v[206:209], v[46:49]
	v_mfma_f32_16x16x32_bf16 v[42:45], v[182:185], v[206:209], v[42:45]
	v_mfma_f32_16x16x32_bf16 v[42:45], v[168:171], v[202:205], v[42:45]
	v_mfma_f32_16x16x32_bf16 v[34:37], v[168:171], v[210:213], v[34:37]
	v_mfma_f32_16x16x32_bf16 v[34:37], v[182:185], v[214:217], v[34:37]
	v_mfma_f32_16x16x32_bf16 v[38:41], v[164:167], v[214:217], v[38:41]
	v_mfma_f32_16x16x32_bf16 v[38:41], v[146:149], v[210:213], v[38:41]
	s_barrier
	s_setprio 0
	s_mov_b32 m0, s23
	s_or_b32 s70, s69, 0x80
	ds_read_b128 v[186:189], v158 offset:49152
	ds_read_b128 v[190:193], v158 offset:50176
	ds_read_b128 v[194:197], v158 offset:51200
	ds_read_b128 v[198:201], v158 offset:52224
	ds_read_b128 v[202:205], v158 offset:53248
	ds_read_b128 v[206:209], v158 offset:54272
	ds_read_b128 v[210:213], v158 offset:55296
	ds_read_b128 v[214:217], v158 offset:56320
	buffer_load_dwordx4 v151, s[40:43], s70 offen lds
	s_mov_b32 m0, s24
	s_add_i32 s69, s69, 0x80080
	buffer_load_dwordx4 v153, s[40:43], s70 offen lds
	s_mov_b32 m0, s27
	s_nop 0
	buffer_load_dwordx4 v151, s[40:43], s69 offen lds
	s_mov_b32 m0, s28
	s_nop 0
	buffer_load_dwordx4 v153, s[40:43], s69 offen lds
	s_mov_b32 m0, s25
	s_nop 0
	buffer_load_dwordx4 v150, s[76:79], s68 offen lds
	s_mov_b32 m0, s26
	s_nop 0
	buffer_load_dwordx4 v152, s[76:79], s68 offen lds
	s_waitcnt vmcnt(8)
	s_waitcnt lgkmcnt(0)
	s_setprio 1
	s_barrier
	v_mfma_f32_16x16x32_bf16 v[94:97], v[130:133], v[186:189], v[94:97]
	v_mfma_f32_16x16x32_bf16 v[94:97], v[134:137], v[190:193], v[94:97]
	v_mfma_f32_16x16x32_bf16 v[90:93], v[142:145], v[190:193], v[90:93]
	v_mfma_f32_16x16x32_bf16 v[90:93], v[138:141], v[186:189], v[90:93]
	v_mfma_f32_16x16x32_bf16 v[82:85], v[138:141], v[194:197], v[82:85]
	v_mfma_f32_16x16x32_bf16 v[82:85], v[142:145], v[198:201], v[82:85]
	v_mfma_f32_16x16x32_bf16 v[86:89], v[134:137], v[198:201], v[86:89]
	v_mfma_f32_16x16x32_bf16 v[86:89], v[130:133], v[194:197], v[86:89]
	v_mfma_f32_16x16x32_bf16 v[78:81], v[130:133], v[202:205], v[78:81]
	v_mfma_f32_16x16x32_bf16 v[78:81], v[134:137], v[206:209], v[78:81]
	v_mfma_f32_16x16x32_bf16 v[74:77], v[142:145], v[206:209], v[74:77]
	v_mfma_f32_16x16x32_bf16 v[74:77], v[138:141], v[202:205], v[74:77]
	v_mfma_f32_16x16x32_bf16 v[66:69], v[138:141], v[210:213], v[66:69]
	v_mfma_f32_16x16x32_bf16 v[66:69], v[142:145], v[214:217], v[66:69]
	v_mfma_f32_16x16x32_bf16 v[70:73], v[134:137], v[214:217], v[70:73]
	v_mfma_f32_16x16x32_bf16 v[70:73], v[130:133], v[210:213], v[70:73]
	v_mfma_f32_16x16x32_bf16 v[30:33], v[146:149], v[186:189], v[30:33]
	v_mfma_f32_16x16x32_bf16 v[30:33], v[164:167], v[190:193], v[30:33]
	v_mfma_f32_16x16x32_bf16 v[26:29], v[182:185], v[190:193], v[26:29]
	v_mfma_f32_16x16x32_bf16 v[26:29], v[168:171], v[186:189], v[26:29]
	v_mfma_f32_16x16x32_bf16 v[18:21], v[168:171], v[194:197], v[18:21]
	v_mfma_f32_16x16x32_bf16 v[18:21], v[182:185], v[198:201], v[18:21]
	v_mfma_f32_16x16x32_bf16 v[22:25], v[164:167], v[198:201], v[22:25]
	v_mfma_f32_16x16x32_bf16 v[22:25], v[146:149], v[194:197], v[22:25]
	v_mfma_f32_16x16x32_bf16 v[14:17], v[146:149], v[202:205], v[14:17]
	v_mfma_f32_16x16x32_bf16 v[14:17], v[164:167], v[206:209], v[14:17]
	v_mfma_f32_16x16x32_bf16 v[10:13], v[182:185], v[206:209], v[10:13]
	v_mfma_f32_16x16x32_bf16 v[10:13], v[168:171], v[202:205], v[10:13]
	v_mfma_f32_16x16x32_bf16 v[2:5], v[168:171], v[210:213], v[2:5]
	v_mfma_f32_16x16x32_bf16 v[2:5], v[182:185], v[214:217], v[2:5]
	v_mfma_f32_16x16x32_bf16 v[6:9], v[164:167], v[214:217], v[6:9]
	v_mfma_f32_16x16x32_bf16 v[6:9], v[146:149], v[210:213], v[6:9]
	s_barrier
	s_setprio 0
	s_add_i32 s67, s67, 2
	s_addk_i32 s62, 0x100
	s_addk_i32 s63, 0x100
	s_cmp_gt_u32 s67, 29
	s_cbranch_scc0 .LBB0_1274
	s_and_b64 vcc, exec, s[50:51]
	s_cbranch_vccz .LBB0_1277
	s_barrier

; #define PG8_STAGEX(rs, bufoff, soff, voff) do { _Pragma("unroll") for (int _i = 0; _i < 2; ++_i) \
;         __builtin_amdgcn_raw_ptr_buffer_load_lds(rs, (LAS unsigned*)(lds + (bufoff) + ldsw + _i * 8192), 16, (voff)[_i], (soff), 0, 0); } while (0)
; #define PG8_LDA(dst, b, h) do { _Pragma("unroll") for (int m = 0; m < 4; ++m) _Pragma("unroll") for (int k = 0; k < 2; ++k) dst[m][k] = *(const LAS bf16x8*)(lds + PG8_SA(b, h) + aoff + m * 2048 + k * 1024); } while (0)
; #define PG8_LDB(dst, b, h) do { _Pragma("unroll") for (int n = 0; n < 2; ++n) _Pragma("unroll") for (int k = 0; k < 2; ++k) dst[n][k] = *(const LAS bf16x8*)(lds + PG8_SB(b, h) + boff + n * 2048 + k * 1024); } while (0)
; #define PG8_WAIT_V(n) asm volatile("s_waitcnt vmcnt(" #n ")" ::: "memory")
; #define PG8_WAIT_L(n) asm volatile("s_waitcnt lgkmcnt(" #n ")" ::: "memory")
; #define PG8_BAR __builtin_amdgcn_s_barrier()
; #define PG8_SCHED __builtin_amdgcn_sched_barrier(0)
;     ...
;                 if (w0) { PG8_LDB(B0, 0, 0); PG8_LDB(B1, 0, 1); PG8_SCHED; PG8_LDA(At, 0, 0); }
;                 PG8_WAIT_L(0); PG8_BAR; if (w0) { PG8_MMA(0, 0, At, B0); PG8_MMA(0, 1, At, B1); } PG8_BAR; PG8_SCHED;
;                 PG8_STAGEX(rsB, PG8_SB(0, 0), b2, voffB); PG8_STAGEX(rsB, PG8_SB(0, 1), b2 + hstepB, voffB); PG8_STAGEX(rsA, PG8_SA(0, 0), a2, voffA);
;                 PG8_WAIT_V(6); PG8_BAR; PG8_BAR; PG8_SCHED;
.LBB0_1287:
	v_add_u32_e32 v86, 0x10000, v72
	v_add_u32_e32 v102, 0x14000, v72
	ds_read_b128 v[74:77], v86
	ds_read_b128 v[78:81], v86 offset:1024
	ds_read_b128 v[82:85], v86 offset:2048
	ds_read_b128 v[86:89], v86 offset:3072
	ds_read_b128 v[90:93], v102
	ds_read_b128 v[94:97], v102 offset:1024
	ds_read_b128 v[98:101], v102 offset:2048
	ds_read_b128 v[102:105], v102 offset:3072
	s_cmp_lg_u32 s29, 28
	s_cselect_b32 s30, s28, 0
	s_add_i32 s31, s30, s19
	s_or_b32 s35, s31, 0x80
	s_add_i32 s30, s30, s13
	ds_read_b128 v[106:109], v73
	ds_read_b128 v[110:113], v73 offset:1024
	ds_read_b128 v[114:117], v73 offset:2048
	ds_read_b128 v[118:121], v73 offset:3072
	ds_read_b128 v[122:125], v73 offset:4096
	ds_read_b128 v[126:129], v73 offset:5120
	ds_read_b128 v[130:133], v73 offset:6144
	ds_read_b128 v[134:137], v73 offset:7168
	s_waitcnt lgkmcnt(0)
	s_setprio 1
	s_barrier
	v_mfma_f32_16x16x32_bf16 v[62:65], v[74:77], v[106:109], v[62:65]
	v_mfma_f32_16x16x32_bf16 v[62:65], v[78:81], v[110:113], v[62:65]
	v_mfma_f32_16x16x32_bf16 v[58:61], v[86:89], v[110:113], v[58:61]
	v_mfma_f32_16x16x32_bf16 v[58:61], v[82:85], v[106:109], v[58:61]
	v_mfma_f32_16x16x32_bf16 v[50:53], v[82:85], v[114:117], v[50:53]
	v_mfma_f32_16x16x32_bf16 v[50:53], v[86:89], v[118:121], v[50:53]
	v_mfma_f32_16x16x32_bf16 v[54:57], v[78:81], v[118:121], v[54:57]
	v_mfma_f32_16x16x32_bf16 v[54:57], v[74:77], v[114:117], v[54:57]
	v_mfma_f32_16x16x32_bf16 v[46:49], v[74:77], v[122:125], v[46:49]
	v_mfma_f32_16x16x32_bf16 v[46:49], v[78:81], v[126:129], v[46:49]
	v_mfma_f32_16x16x32_bf16 v[42:45], v[86:89], v[126:129], v[42:45]
	v_mfma_f32_16x16x32_bf16 v[42:45], v[82:85], v[122:125], v[42:45]
	v_mfma_f32_16x16x32_bf16 v[34:37], v[82:85], v[130:133], v[34:37]
	v_mfma_f32_16x16x32_bf16 v[34:37], v[86:89], v[134:137], v[34:37]
	v_mfma_f32_16x16x32_bf16 v[38:41], v[78:81], v[134:137], v[38:41]
	v_mfma_f32_16x16x32_bf16 v[38:41], v[74:77], v[130:133], v[38:41]
	v_mfma_f32_16x16x32_bf16 v[30:33], v[90:93], v[106:109], v[30:33]
	v_mfma_f32_16x16x32_bf16 v[30:33], v[94:97], v[110:113], v[30:33]
	v_mfma_f32_16x16x32_bf16 v[26:29], v[102:105], v[110:113], v[26:29]
	v_mfma_f32_16x16x32_bf16 v[26:29], v[98:101], v[106:109], v[26:29]
	v_mfma_f32_16x16x32_bf16 v[18:21], v[98:101], v[114:117], v[18:21]
	v_mfma_f32_16x16x32_bf16 v[18:21], v[102:105], v[118:121], v[18:21]
	v_mfma_f32_16x16x32_bf16 v[22:25], v[94:97], v[118:121], v[22:25]
	v_mfma_f32_16x16x32_bf16 v[22:25], v[90:93], v[114:117], v[22:25]
	v_mfma_f32_16x16x32_bf16 v[14:17], v[90:93], v[122:125], v[14:17]
	v_mfma_f32_16x16x32_bf16 v[14:17], v[94:97], v[126:129], v[14:17]
	v_mfma_f32_16x16x32_bf16 v[10:13], v[102:105], v[126:129], v[10:13]
	v_mfma_f32_16x16x32_bf16 v[10:13], v[98:101], v[122:125], v[10:13]
	v_mfma_f32_16x16x32_bf16 v[2:5], v[98:101], v[130:133], v[2:5]
	v_mfma_f32_16x16x32_bf16 v[2:5], v[102:105], v[134:137], v[2:5]
	v_mfma_f32_16x16x32_bf16 v[6:9], v[94:97], v[134:137], v[6:9]
	v_mfma_f32_16x16x32_bf16 v[6:9], v[90:93], v[130:133], v[6:9]
	s_barrier
	s_setprio 0
	s_mov_b32 m0, s15
	s_mov_b32 s42, s78
	s_mov_b32 s43, s79
	buffer_load_dwordx4 v67, s[40:43], s30 offen lds
	s_mov_b32 m0, s16
	s_add_i32 s38, s30, 0x80000
	buffer_load_dwordx4 v69, s[40:43], s30 offen lds
	s_mov_b32 m0, s17
	s_nop 0
	buffer_load_dwordx4 v67, s[40:43], s38 offen lds
	s_mov_b32 m0, s18
	s_nop 0
	buffer_load_dwordx4 v69, s[40:43], s38 offen lds
	s_mov_b32 m0, s14
	s_nop 0
	buffer_load_dwordx4 v66, s[76:79], s31 offen lds
	s_mov_b32 m0, s20
	s_nop 0
	buffer_load_dwordx4 v68, s[76:79], s31 offen lds
	s_waitcnt vmcnt(6)
	s_barrier
	s_barrier
; #define PG8_STAGEX(rs, bufoff, soff, voff) do { _Pragma("unroll") for (int _i = 0; _i < 2; ++_i) \
;         __builtin_amdgcn_raw_ptr_buffer_load_lds(rs, (LAS unsigned*)(lds + (bufoff) + ldsw + _i * 8192), 16, (voff)[_i], (soff), 0, 0); } while (0)
; #define PG8_LDA(dst, b, h) do { _Pragma("unroll") for (int m = 0; m < 4; ++m) _Pragma("unroll") for (int k = 0; k < 2; ++k) dst[m][k] = *(const LAS bf16x8*)(lds + PG8_SA(b, h) + aoff + m * 2048 + k * 1024); } while (0)
; #define PG8_LDB(dst, b, h) do { _Pragma("unroll") for (int n = 0; n < 2; ++n) _Pragma("unroll") for (int k = 0; k < 2; ++k) dst[n][k] = *(const LAS bf16x8*)(lds + PG8_SB(b, h) + boff + n * 2048 + k * 1024); } while (0)
; #define PG8_WAIT_V(n) asm volatile("s_waitcnt vmcnt(" #n ")" ::: "memory")
; #define PG8_WAIT_L(n) asm volatile("s_waitcnt lgkmcnt(" #n ")" ::: "memory")
; #define PG8_BAR __builtin_amdgcn_s_barrier()
; #define PG8_SCHED __builtin_amdgcn_sched_barrier(0)
;     ...
;                 if (w0) { PG8_LDB(B0, 1, 0); PG8_LDB(B1, 1, 1); PG8_SCHED; PG8_LDA(At, 1, 0); }
;                 PG8_WAIT_L(0); PG8_BAR; if (w0) { PG8_MMA(0, 0, At, B0); PG8_MMA(0, 1, At, B1); } PG8_BAR; PG8_SCHED;
;                 PG8_STAGEX(rsB, PG8_SB(1, 0), b3, voffB); PG8_STAGEX(rsB, PG8_SB(1, 1), b3 + hstepB, voffB); PG8_STAGEX(rsA, PG8_SA(1, 0), a3, voffA);
;                 PG8_WAIT_V(6); PG8_BAR; PG8_BAR; PG8_SCHED;
	v_add_u32_e32 v86, 0x18000, v72
	v_add_u32_e32 v102, 0x1c000, v72
	ds_read_b128 v[74:77], v86
	ds_read_b128 v[78:81], v86 offset:1024
	ds_read_b128 v[82:85], v86 offset:2048
	ds_read_b128 v[86:89], v86 offset:3072
	ds_read_b128 v[90:93], v102
	ds_read_b128 v[94:97], v102 offset:1024
	ds_read_b128 v[98:101], v102 offset:2048
	ds_read_b128 v[102:105], v102 offset:3072
	ds_read_b128 v[106:109], v73 offset:32768
	ds_read_b128 v[110:113], v73 offset:33792
	ds_read_b128 v[114:117], v73 offset:34816
	ds_read_b128 v[118:121], v73 offset:35840
	ds_read_b128 v[122:125], v73 offset:36864
	ds_read_b128 v[126:129], v73 offset:37888
	ds_read_b128 v[130:133], v73 offset:38912
	ds_read_b128 v[134:137], v73 offset:39936
	s_waitcnt lgkmcnt(0)
	s_setprio 1
	s_barrier
	v_mfma_f32_16x16x32_bf16 v[62:65], v[74:77], v[106:109], v[62:65]
	v_mfma_f32_16x16x32_bf16 v[58:61], v[82:85], v[106:109], v[58:61]
	v_mfma_f32_16x16x32_bf16 v[54:57], v[74:77], v[114:117], v[54:57]
	v_mfma_f32_16x16x32_bf16 v[50:53], v[82:85], v[114:117], v[50:53]
	v_mfma_f32_16x16x32_bf16 v[46:49], v[74:77], v[122:125], v[46:49]
	v_mfma_f32_16x16x32_bf16 v[42:45], v[82:85], v[122:125], v[42:45]
	v_mfma_f32_16x16x32_bf16 v[38:41], v[74:77], v[130:133], v[38:41]
	v_mfma_f32_16x16x32_bf16 v[34:37], v[82:85], v[130:133], v[34:37]
	v_mfma_f32_16x16x32_bf16 v[62:65], v[78:81], v[110:113], v[62:65]
	v_mfma_f32_16x16x32_bf16 v[58:61], v[86:89], v[110:113], v[58:61]
	v_mfma_f32_16x16x32_bf16 v[54:57], v[78:81], v[118:121], v[54:57]
	v_mfma_f32_16x16x32_bf16 v[50:53], v[86:89], v[118:121], v[50:53]
	v_mfma_f32_16x16x32_bf16 v[46:49], v[78:81], v[126:129], v[46:49]
	v_mfma_f32_16x16x32_bf16 v[42:45], v[86:89], v[126:129], v[42:45]
	v_mfma_f32_16x16x32_bf16 v[38:41], v[78:81], v[134:137], v[38:41]
	v_mfma_f32_16x16x32_bf16 v[34:37], v[86:89], v[134:137], v[34:37]
	v_mfma_f32_16x16x32_bf16 v[30:33], v[90:93], v[106:109], v[30:33]
	s_or_b32 s31, s30, 0x80
	v_mfma_f32_16x16x32_bf16 v[26:29], v[98:101], v[106:109], v[26:29]
	v_mfma_f32_16x16x32_bf16 v[22:25], v[90:93], v[114:117], v[22:25]
	v_mfma_f32_16x16x32_bf16 v[18:21], v[98:101], v[114:117], v[18:21]
	v_mfma_f32_16x16x32_bf16 v[14:17], v[90:93], v[122:125], v[14:17]
	v_mfma_f32_16x16x32_bf16 v[10:13], v[98:101], v[122:125], v[10:13]
	v_mfma_f32_16x16x32_bf16 v[6:9], v[90:93], v[130:133], v[6:9]
	v_mfma_f32_16x16x32_bf16 v[2:5], v[98:101], v[130:133], v[2:5]
	v_mfma_f32_16x16x32_bf16 v[30:33], v[94:97], v[110:113], v[30:33]
	v_mfma_f32_16x16x32_bf16 v[26:29], v[102:105], v[110:113], v[26:29]
	v_mfma_f32_16x16x32_bf16 v[22:25], v[94:97], v[118:121], v[22:25]
	v_mfma_f32_16x16x32_bf16 v[18:21], v[102:105], v[118:121], v[18:21]
	v_mfma_f32_16x16x32_bf16 v[14:17], v[94:97], v[126:129], v[14:17]
	v_mfma_f32_16x16x32_bf16 v[10:13], v[102:105], v[126:129], v[10:13]
	v_mfma_f32_16x16x32_bf16 v[6:9], v[94:97], v[134:137], v[6:9]
	v_mfma_f32_16x16x32_bf16 v[2:5], v[102:105], v[134:137], v[2:5]
	s_barrier
	s_setprio 0
	s_mov_b32 m0, s22
	s_add_i32 s30, s30, 0x80080
	buffer_load_dwordx4 v67, s[40:43], s31 offen lds
	s_mov_b32 m0, s23
	s_nop 0
	buffer_load_dwordx4 v69, s[40:43], s31 offen lds
	s_mov_b32 m0, s26
	s_nop 0
	buffer_load_dwordx4 v67, s[40:43], s30 offen lds
	s_mov_b32 m0, s27
	s_nop 0
	buffer_load_dwordx4 v69, s[40:43], s30 offen lds
	s_mov_b32 m0, s24
	s_nop 0
	buffer_load_dwordx4 v66, s[76:79], s35 offen lds
	s_mov_b32 m0, s25
	s_nop 0
	buffer_load_dwordx4 v68, s[76:79], s35 offen lds
	s_waitcnt vmcnt(6)
	s_barrier
	s_barrier
	s_addk_i32 s28, 0x100
	s_add_i32 s29, s29, 2
	s_cmp_gt_u32 s29, 29
	s_cbranch_scc0 .LBB0_1287
	s_cmpk_lt_u32 s12, 0x100
	s_cbranch_scc0 .LBB0_1290
	s_barrier

; #define PG8_STAGEX(rs, bufoff, soff, voff) do { _Pragma("unroll") for (int _i = 0; _i < 2; ++_i) \
;         __builtin_amdgcn_raw_ptr_buffer_load_lds(rs, (LAS unsigned*)(lds + (bufoff) + ldsw + _i * 8192), 16, (voff)[_i], (soff), 0, 0); } while (0)
; #define PG8_LDA(dst, b, h) do { _Pragma("unroll") for (int m = 0; m < 4; ++m) _Pragma("unroll") for (int k = 0; k < 2; ++k) dst[m][k] = *(const LAS bf16x8*)(lds + PG8_SA(b, h) + aoff + m * 2048 + k * 1024); } while (0)
; #define PG8_LDB(dst, b, h) do { _Pragma("unroll") for (int n = 0; n < 2; ++n) _Pragma("unroll") for (int k = 0; k < 2; ++k) dst[n][k] = *(const LAS bf16x8*)(lds + PG8_SB(b, h) + boff + n * 2048 + k * 1024); } while (0)
; #define PG8_WAIT_V(n) asm volatile("s_waitcnt vmcnt(" #n ")" ::: "memory")
; #define PG8_WAIT_L(n) asm volatile("s_waitcnt lgkmcnt(" #n ")" ::: "memory")
; #define PG8_BAR __builtin_amdgcn_s_barrier()
; #define PG8_SCHED __builtin_amdgcn_sched_barrier(0)
;     ...
;             const unsigned a1 = cA + (unsigned)(t + 1) * kstep;
;             const unsigned a2 = last ? nA : cA + (unsigned)(t + 2) * kstep, b2 = last ? nB : cB + (unsigned)(t + 2) * kstep;
;             const unsigned a3 = a2 + kstep, b3 = b2 + kstep;
;             PG8_LDB(B0, 0, 0); PG8_LDB(B1, 0, 1); PG8_SCHED; PG8_LDA(At, 0, 0); PG8_STAGEX(rsA, PG8_SA(1, 1), a1 + hstepA, voffA);
;             PG8_WAIT_V(8); PG8_WAIT_L(0); PG8_BAR; PG8_MMA(0, 0, At, B0); PG8_MMA(0, 1, At, B1); PG8_BAR; PG8_SCHED;
;             PG8_LDA(At, 0, 1); PG8_STAGEX(rsB, PG8_SB(0, 0), b2, voffB); PG8_STAGEX(rsB, PG8_SB(0, 1), b2 + hstepB, voffB); PG8_STAGEX(rsA, PG8_SA(0, 0), a2, voffA);
;             PG8_WAIT_V(8); PG8_WAIT_L(0); PG8_BAR; PG8_MMA(1, 0, At, B0); PG8_MMA(1, 1, At, B1); PG8_BAR; PG8_SCHED;
.LBB0_1377:
	v_add_u32_e32 v142, 0x10000, v185
	v_add_u32_e32 v158, 0x14000, v185
	ds_read_b128 v[130:133], v142
	ds_read_b128 v[134:137], v142 offset:1024
	ds_read_b128 v[138:141], v142 offset:2048
	ds_read_b128 v[142:145], v142 offset:3072
	ds_read_b128 v[146:149], v158
	ds_read_b128 v[150:153], v158 offset:1024
	ds_read_b128 v[154:157], v158 offset:2048
	ds_read_b128 v[158:161], v158 offset:3072
	s_add_i32 s50, s43, 0xfff40080
	s_cmp_eq_u32 s60, 12
	s_cselect_b32 s63, s30, s50
	s_cselect_b32 s62, s31, s59
	s_add_i32 s61, s63, 0x80
	s_mov_b32 m0, s23
	ds_read_b128 v[162:165], v186
	ds_read_b128 v[166:169], v186 offset:1024
	ds_read_b128 v[190:193], v186 offset:2048
	ds_read_b128 v[194:197], v186 offset:3072
	ds_read_b128 v[198:201], v186 offset:4096
	ds_read_b128 v[202:205], v186 offset:5120
	ds_read_b128 v[206:209], v186 offset:6144
	ds_read_b128 v[210:213], v186 offset:7168
	buffer_load_dwordx4 v173, s[76:79], s43 offen lds
	s_mov_b32 m0, s24
	s_nop 0
	buffer_load_dwordx4 v178, s[76:79], s43 offen lds
	s_waitcnt vmcnt(8)
	s_waitcnt lgkmcnt(0)
	s_setprio 1
	s_barrier
	v_mfma_f32_16x16x32_bf16 v[126:129], v[130:133], v[162:165], v[126:129]
	v_mfma_f32_16x16x32_bf16 v[126:129], v[134:137], v[166:169], v[126:129]
	v_mfma_f32_16x16x32_bf16 v[122:125], v[142:145], v[166:169], v[122:125]
	v_mfma_f32_16x16x32_bf16 v[122:125], v[138:141], v[162:165], v[122:125]
	v_mfma_f32_16x16x32_bf16 v[114:117], v[138:141], v[190:193], v[114:117]
	v_mfma_f32_16x16x32_bf16 v[114:117], v[142:145], v[194:197], v[114:117]
	v_mfma_f32_16x16x32_bf16 v[118:121], v[134:137], v[194:197], v[118:121]
	v_mfma_f32_16x16x32_bf16 v[118:121], v[130:133], v[190:193], v[118:121]
	v_mfma_f32_16x16x32_bf16 v[110:113], v[130:133], v[198:201], v[110:113]
	v_mfma_f32_16x16x32_bf16 v[110:113], v[134:137], v[202:205], v[110:113]
	v_mfma_f32_16x16x32_bf16 v[106:109], v[142:145], v[202:205], v[106:109]
	v_mfma_f32_16x16x32_bf16 v[106:109], v[138:141], v[198:201], v[106:109]
	v_mfma_f32_16x16x32_bf16 v[98:101], v[138:141], v[206:209], v[98:101]
	v_mfma_f32_16x16x32_bf16 v[98:101], v[142:145], v[210:213], v[98:101]
	v_mfma_f32_16x16x32_bf16 v[102:105], v[134:137], v[210:213], v[102:105]
	v_mfma_f32_16x16x32_bf16 v[102:105], v[130:133], v[206:209], v[102:105]
	v_mfma_f32_16x16x32_bf16 v[94:97], v[146:149], v[162:165], v[94:97]
	v_mfma_f32_16x16x32_bf16 v[94:97], v[150:153], v[166:169], v[94:97]
	v_mfma_f32_16x16x32_bf16 v[90:93], v[158:161], v[166:169], v[90:93]
	v_mfma_f32_16x16x32_bf16 v[90:93], v[154:157], v[162:165], v[90:93]
	v_mfma_f32_16x16x32_bf16 v[82:85], v[154:157], v[190:193], v[82:85]
	v_mfma_f32_16x16x32_bf16 v[82:85], v[158:161], v[194:197], v[82:85]
	v_mfma_f32_16x16x32_bf16 v[86:89], v[150:153], v[194:197], v[86:89]
	v_mfma_f32_16x16x32_bf16 v[86:89], v[146:149], v[190:193], v[86:89]
	v_mfma_f32_16x16x32_bf16 v[78:81], v[146:149], v[198:201], v[78:81]
	v_mfma_f32_16x16x32_bf16 v[78:81], v[150:153], v[202:205], v[78:81]
	v_mfma_f32_16x16x32_bf16 v[74:77], v[158:161], v[202:205], v[74:77]
	v_mfma_f32_16x16x32_bf16 v[74:77], v[154:157], v[198:201], v[74:77]
	v_mfma_f32_16x16x32_bf16 v[66:69], v[154:157], v[206:209], v[66:69]
	v_mfma_f32_16x16x32_bf16 v[66:69], v[158:161], v[210:213], v[66:69]
	v_mfma_f32_16x16x32_bf16 v[70:73], v[150:153], v[210:213], v[70:73]
	v_mfma_f32_16x16x32_bf16 v[70:73], v[146:149], v[206:209], v[70:73]
	s_barrier
	s_setprio 0
	s_mov_b32 m0, s7
	s_mov_b32 s50, s78
	s_mov_b32 s51, s79
	ds_read_b128 v[162:165], v186 offset:16384
	ds_read_b128 v[166:169], v186 offset:17408
	ds_read_b128 v[190:193], v186 offset:18432
	ds_read_b128 v[194:197], v186 offset:19456
	ds_read_b128 v[198:201], v186 offset:20480
	ds_read_b128 v[202:205], v186 offset:21504
	ds_read_b128 v[206:209], v186 offset:22528
	ds_read_b128 v[210:213], v186 offset:23552
	buffer_load_dwordx4 v177, s[48:51], s62 offen lds
	s_mov_b32 m0, s11
	s_add_i32 s64, s62, 0x40000
	buffer_load_dwordx4 v179, s[48:51], s62 offen lds
	s_mov_b32 m0, s12
	s_nop 0
	buffer_load_dwordx4 v177, s[48:51], s64 offen lds
	s_mov_b32 m0, s13
	s_nop 0
	buffer_load_dwordx4 v179, s[48:51], s64 offen lds
	s_mov_b32 m0, s5
	s_nop 0
	buffer_load_dwordx4 v173, s[76:79], s63 offen lds
	s_mov_b32 m0, s14
	s_nop 0
	buffer_load_dwordx4 v178, s[76:79], s63 offen lds
	s_waitcnt vmcnt(8)
	s_waitcnt lgkmcnt(0)
	s_setprio 1
	s_barrier
	v_mfma_f32_16x16x32_bf16 v[62:65], v[130:133], v[162:165], v[62:65]
	v_mfma_f32_16x16x32_bf16 v[62:65], v[134:137], v[166:169], v[62:65]
	v_mfma_f32_16x16x32_bf16 v[58:61], v[142:145], v[166:169], v[58:61]
	v_mfma_f32_16x16x32_bf16 v[58:61], v[138:141], v[162:165], v[58:61]
	v_mfma_f32_16x16x32_bf16 v[50:53], v[138:141], v[190:193], v[50:53]
	v_mfma_f32_16x16x32_bf16 v[50:53], v[142:145], v[194:197], v[50:53]
	v_mfma_f32_16x16x32_bf16 v[54:57], v[134:137], v[194:197], v[54:57]
	v_mfma_f32_16x16x32_bf16 v[54:57], v[130:133], v[190:193], v[54:57]
	v_mfma_f32_16x16x32_bf16 v[46:49], v[130:133], v[198:201], v[46:49]
	v_mfma_f32_16x16x32_bf16 v[46:49], v[134:137], v[202:205], v[46:49]
	v_mfma_f32_16x16x32_bf16 v[42:45], v[142:145], v[202:205], v[42:45]
	v_mfma_f32_16x16x32_bf16 v[42:45], v[138:141], v[198:201], v[42:45]
	v_mfma_f32_16x16x32_bf16 v[34:37], v[138:141], v[206:209], v[34:37]
	v_mfma_f32_16x16x32_bf16 v[34:37], v[142:145], v[210:213], v[34:37]
	v_mfma_f32_16x16x32_bf16 v[38:41], v[134:137], v[210:213], v[38:41]
	v_mfma_f32_16x16x32_bf16 v[38:41], v[130:133], v[206:209], v[38:41]
	v_mfma_f32_16x16x32_bf16 v[30:33], v[146:149], v[162:165], v[30:33]
	v_mfma_f32_16x16x32_bf16 v[30:33], v[150:153], v[166:169], v[30:33]
	v_mfma_f32_16x16x32_bf16 v[26:29], v[158:161], v[166:169], v[26:29]
	v_mfma_f32_16x16x32_bf16 v[26:29], v[154:157], v[162:165], v[26:29]
	v_mfma_f32_16x16x32_bf16 v[18:21], v[154:157], v[190:193], v[18:21]
	v_mfma_f32_16x16x32_bf16 v[18:21], v[158:161], v[194:197], v[18:21]
	v_mfma_f32_16x16x32_bf16 v[22:25], v[150:153], v[194:197], v[22:25]
	v_mfma_f32_16x16x32_bf16 v[22:25], v[146:149], v[190:193], v[22:25]
	v_mfma_f32_16x16x32_bf16 v[14:17], v[146:149], v[198:201], v[14:17]
	v_mfma_f32_16x16x32_bf16 v[14:17], v[150:153], v[202:205], v[14:17]
	v_mfma_f32_16x16x32_bf16 v[10:13], v[158:161], v[202:205], v[10:13]
	v_mfma_f32_16x16x32_bf16 v[10:13], v[154:157], v[198:201], v[10:13]
	v_mfma_f32_16x16x32_bf16 v[2:5], v[154:157], v[206:209], v[2:5]
	v_mfma_f32_16x16x32_bf16 v[2:5], v[158:161], v[210:213], v[2:5]
	v_mfma_f32_16x16x32_bf16 v[6:9], v[150:153], v[210:213], v[6:9]
	v_mfma_f32_16x16x32_bf16 v[6:9], v[146:149], v[206:209], v[6:9]
	s_barrier
; #define PG8_STAGEX(rs, bufoff, soff, voff) do { _Pragma("unroll") for (int _i = 0; _i < 2; ++_i) \
;         __builtin_amdgcn_raw_ptr_buffer_load_lds(rs, (LAS unsigned*)(lds + (bufoff) + ldsw + _i * 8192), 16, (voff)[_i], (soff), 0, 0); } while (0)
; #define PG8_LDA(dst, b, h) do { _Pragma("unroll") for (int m = 0; m < 4; ++m) _Pragma("unroll") for (int k = 0; k < 2; ++k) dst[m][k] = *(const LAS bf16x8*)(lds + PG8_SA(b, h) + aoff + m * 2048 + k * 1024); } while (0)
; #define PG8_LDB(dst, b, h) do { _Pragma("unroll") for (int n = 0; n < 2; ++n) _Pragma("unroll") for (int k = 0; k < 2; ++k) dst[n][k] = *(const LAS bf16x8*)(lds + PG8_SB(b, h) + boff + n * 2048 + k * 1024); } while (0)
; #define PG8_WAIT_V(n) asm volatile("s_waitcnt vmcnt(" #n ")" ::: "memory")
; #define PG8_WAIT_L(n) asm volatile("s_waitcnt lgkmcnt(" #n ")" ::: "memory")
; #define PG8_BAR __builtin_amdgcn_s_barrier()
; #define PG8_SCHED __builtin_amdgcn_sched_barrier(0)
;     ...
;             PG8_LDB(B0, 1, 0); PG8_LDB(B1, 1, 1); PG8_SCHED; PG8_LDA(At, 1, 0); PG8_STAGEX(rsA, PG8_SA(0, 1), a2 + hstepA, voffA);
;             PG8_WAIT_V(8); PG8_WAIT_L(0); PG8_BAR; PG8_MMA(0, 0, At, B0); PG8_MMA(0, 1, At, B1); PG8_BAR; PG8_SCHED;
;             PG8_LDA(At, 1, 1); PG8_STAGEX(rsB, PG8_SB(1, 0), b3, voffB); PG8_STAGEX(rsB, PG8_SB(1, 1), b3 + hstepB, voffB); PG8_STAGEX(rsA, PG8_SA(1, 0), a3, voffA);
;             PG8_WAIT_V(8); PG8_WAIT_L(0); PG8_BAR; PG8_MMA(1, 0, At, B0); PG8_MMA(1, 1, At, B1); PG8_BAR; PG8_SCHED;
;     ...
;         }
;         if (wr == 0) PG8_BAR;
	s_setprio 0
	v_add_u32_e32 v142, 0x18000, v185
	v_add_u32_e32 v158, 0x1c000, v185
	ds_read_b128 v[130:133], v142
	ds_read_b128 v[134:137], v142 offset:1024
	ds_read_b128 v[138:141], v142 offset:2048
	ds_read_b128 v[142:145], v142 offset:3072
	ds_read_b128 v[146:149], v158
	ds_read_b128 v[150:153], v158 offset:1024
	ds_read_b128 v[154:157], v158 offset:2048
	ds_read_b128 v[158:161], v158 offset:3072
	s_add_i32 s63, s63, 0xc0000
	s_mov_b32 m0, s15
	ds_read_b128 v[162:165], v186 offset:32768
	ds_read_b128 v[166:169], v186 offset:33792
	ds_read_b128 v[190:193], v186 offset:34816
	ds_read_b128 v[194:197], v186 offset:35840
	ds_read_b128 v[198:201], v186 offset:36864
	ds_read_b128 v[202:205], v186 offset:37888
	ds_read_b128 v[206:209], v186 offset:38912
	ds_read_b128 v[210:213], v186 offset:39936
	buffer_load_dwordx4 v173, s[76:79], s63 offen lds
	s_mov_b32 m0, s16
	s_nop 0
	buffer_load_dwordx4 v178, s[76:79], s63 offen lds
	s_waitcnt vmcnt(8)
	s_waitcnt lgkmcnt(0)
	s_setprio 1
	s_barrier
	v_mfma_f32_16x16x32_bf16 v[126:129], v[130:133], v[162:165], v[126:129]
	v_mfma_f32_16x16x32_bf16 v[126:129], v[134:137], v[166:169], v[126:129]
	v_mfma_f32_16x16x32_bf16 v[122:125], v[142:145], v[166:169], v[122:125]
	v_mfma_f32_16x16x32_bf16 v[122:125], v[138:141], v[162:165], v[122:125]
	v_mfma_f32_16x16x32_bf16 v[114:117], v[138:141], v[190:193], v[114:117]
	v_mfma_f32_16x16x32_bf16 v[114:117], v[142:145], v[194:197], v[114:117]
	v_mfma_f32_16x16x32_bf16 v[118:121], v[134:137], v[194:197], v[118:121]
	v_mfma_f32_16x16x32_bf16 v[118:121], v[130:133], v[190:193], v[118:121]
	v_mfma_f32_16x16x32_bf16 v[110:113], v[130:133], v[198:201], v[110:113]
	v_mfma_f32_16x16x32_bf16 v[110:113], v[134:137], v[202:205], v[110:113]
	v_mfma_f32_16x16x32_bf16 v[106:109], v[142:145], v[202:205], v[106:109]
	v_mfma_f32_16x16x32_bf16 v[106:109], v[138:141], v[198:201], v[106:109]
	v_mfma_f32_16x16x32_bf16 v[98:101], v[138:141], v[206:209], v[98:101]
	v_mfma_f32_16x16x32_bf16 v[98:101], v[142:145], v[210:213], v[98:101]
	v_mfma_f32_16x16x32_bf16 v[102:105], v[134:137], v[210:213], v[102:105]
	v_mfma_f32_16x16x32_bf16 v[102:105], v[130:133], v[206:209], v[102:105]
	v_mfma_f32_16x16x32_bf16 v[94:97], v[146:149], v[162:165], v[94:97]
	v_mfma_f32_16x16x32_bf16 v[94:97], v[150:153], v[166:169], v[94:97]
	v_mfma_f32_16x16x32_bf16 v[90:93], v[158:161], v[166:169], v[90:93]
	v_mfma_f32_16x16x32_bf16 v[90:93], v[154:157], v[162:165], v[90:93]
	v_mfma_f32_16x16x32_bf16 v[82:85], v[154:157], v[190:193], v[82:85]
	v_mfma_f32_16x16x32_bf16 v[82:85], v[158:161], v[194:197], v[82:85]
	v_mfma_f32_16x16x32_bf16 v[86:89], v[150:153], v[194:197], v[86:89]
	v_mfma_f32_16x16x32_bf16 v[86:89], v[146:149], v[190:193], v[86:89]
	v_mfma_f32_16x16x32_bf16 v[78:81], v[146:149], v[198:201], v[78:81]
	v_mfma_f32_16x16x32_bf16 v[78:81], v[150:153], v[202:205], v[78:81]
	v_mfma_f32_16x16x32_bf16 v[74:77], v[158:161], v[202:205], v[74:77]
	v_mfma_f32_16x16x32_bf16 v[74:77], v[154:157], v[198:201], v[74:77]
	v_mfma_f32_16x16x32_bf16 v[66:69], v[154:157], v[206:209], v[66:69]
	v_mfma_f32_16x16x32_bf16 v[66:69], v[158:161], v[210:213], v[66:69]
	v_mfma_f32_16x16x32_bf16 v[70:73], v[150:153], v[210:213], v[70:73]
	v_mfma_f32_16x16x32_bf16 v[70:73], v[146:149], v[206:209], v[70:73]
	s_barrier
	s_setprio 0
	s_mov_b32 m0, s17
	s_add_i32 s63, s62, 0x80
	ds_read_b128 v[162:165], v186 offset:49152
	ds_read_b128 v[166:169], v186 offset:50176
	ds_read_b128 v[190:193], v186 offset:51200
	ds_read_b128 v[194:197], v186 offset:52224
	ds_read_b128 v[198:201], v186 offset:53248
	ds_read_b128 v[202:205], v186 offset:54272
	ds_read_b128 v[206:209], v186 offset:55296
	ds_read_b128 v[210:213], v186 offset:56320
	buffer_load_dwordx4 v177, s[48:51], s63 offen lds
	s_mov_b32 m0, s18
	s_add_i32 s62, s62, 0x40080
	buffer_load_dwordx4 v179, s[48:51], s63 offen lds
	s_mov_b32 m0, s21
	s_nop 0
	buffer_load_dwordx4 v177, s[48:51], s62 offen lds
	s_mov_b32 m0, s22
	s_nop 0
	buffer_load_dwordx4 v179, s[48:51], s62 offen lds
	s_mov_b32 m0, s19
	s_nop 0
	buffer_load_dwordx4 v173, s[76:79], s61 offen lds
	s_mov_b32 m0, s20
	s_nop 0
	buffer_load_dwordx4 v178, s[76:79], s61 offen lds
	s_waitcnt vmcnt(8)
	s_waitcnt lgkmcnt(0)
	s_setprio 1
	s_barrier
	v_mfma_f32_16x16x32_bf16 v[62:65], v[130:133], v[162:165], v[62:65]
	v_mfma_f32_16x16x32_bf16 v[62:65], v[134:137], v[166:169], v[62:65]
	v_mfma_f32_16x16x32_bf16 v[58:61], v[142:145], v[166:169], v[58:61]
	v_mfma_f32_16x16x32_bf16 v[58:61], v[138:141], v[162:165], v[58:61]
	v_mfma_f32_16x16x32_bf16 v[50:53], v[138:141], v[190:193], v[50:53]
	v_mfma_f32_16x16x32_bf16 v[50:53], v[142:145], v[194:197], v[50:53]
	v_mfma_f32_16x16x32_bf16 v[54:57], v[134:137], v[194:197], v[54:57]
	v_mfma_f32_16x16x32_bf16 v[54:57], v[130:133], v[190:193], v[54:57]
	v_mfma_f32_16x16x32_bf16 v[46:49], v[130:133], v[198:201], v[46:49]
	v_mfma_f32_16x16x32_bf16 v[46:49], v[134:137], v[202:205], v[46:49]
	v_mfma_f32_16x16x32_bf16 v[42:45], v[142:145], v[202:205], v[42:45]
	v_mfma_f32_16x16x32_bf16 v[42:45], v[138:141], v[198:201], v[42:45]
	v_mfma_f32_16x16x32_bf16 v[34:37], v[138:141], v[206:209], v[34:37]
	v_mfma_f32_16x16x32_bf16 v[34:37], v[142:145], v[210:213], v[34:37]
	v_mfma_f32_16x16x32_bf16 v[38:41], v[134:137], v[210:213], v[38:41]
	v_mfma_f32_16x16x32_bf16 v[38:41], v[130:133], v[206:209], v[38:41]
	v_mfma_f32_16x16x32_bf16 v[30:33], v[146:149], v[162:165], v[30:33]
	v_mfma_f32_16x16x32_bf16 v[30:33], v[150:153], v[166:169], v[30:33]
	v_mfma_f32_16x16x32_bf16 v[26:29], v[158:161], v[166:169], v[26:29]
	v_mfma_f32_16x16x32_bf16 v[26:29], v[154:157], v[162:165], v[26:29]
	v_mfma_f32_16x16x32_bf16 v[18:21], v[154:157], v[190:193], v[18:21]
	v_mfma_f32_16x16x32_bf16 v[18:21], v[158:161], v[194:197], v[18:21]
	v_mfma_f32_16x16x32_bf16 v[22:25], v[150:153], v[194:197], v[22:25]
	v_mfma_f32_16x16x32_bf16 v[22:25], v[146:149], v[190:193], v[22:25]
	v_mfma_f32_16x16x32_bf16 v[14:17], v[146:149], v[198:201], v[14:17]
	v_mfma_f32_16x16x32_bf16 v[14:17], v[150:153], v[202:205], v[14:17]
	v_mfma_f32_16x16x32_bf16 v[10:13], v[158:161], v[202:205], v[10:13]
	v_mfma_f32_16x16x32_bf16 v[10:13], v[154:157], v[198:201], v[10:13]
	v_mfma_f32_16x16x32_bf16 v[2:5], v[154:157], v[206:209], v[2:5]
	v_mfma_f32_16x16x32_bf16 v[2:5], v[158:161], v[210:213], v[2:5]
	v_mfma_f32_16x16x32_bf16 v[6:9], v[150:153], v[210:213], v[6:9]
	v_mfma_f32_16x16x32_bf16 v[6:9], v[146:149], v[206:209], v[6:9]
	s_barrier
	s_setprio 0
	s_add_i32 s60, s60, 2
	s_addk_i32 s43, 0x100
	s_addk_i32 s59, 0x100
	s_cmp_gt_u32 s60, 13
	s_cbranch_scc0 .LBB0_1377
	s_and_b64 vcc, exec, s[52:53]
	s_cbranch_vccz .LBB0_1380
	s_barrier

; #define PG8_STAGEX(rs, bufoff, soff, voff) do { _Pragma("unroll") for (int _i = 0; _i < 2; ++_i) \
;         __builtin_amdgcn_raw_ptr_buffer_load_lds(rs, (LAS unsigned*)(lds + (bufoff) + ldsw + _i * 8192), 16, (voff)[_i], (soff), 0, 0); } while (0)
; #define PG8_LDA(dst, b, h) do { _Pragma("unroll") for (int m = 0; m < 4; ++m) _Pragma("unroll") for (int k = 0; k < 2; ++k) dst[m][k] = *(const LAS bf16x8*)(lds + PG8_SA(b, h) + aoff + m * 2048 + k * 1024); } while (0)
; #define PG8_LDB(dst, b, h) do { _Pragma("unroll") for (int n = 0; n < 2; ++n) _Pragma("unroll") for (int k = 0; k < 2; ++k) dst[n][k] = *(const LAS bf16x8*)(lds + PG8_SB(b, h) + boff + n * 2048 + k * 1024); } while (0)
; #define PG8_WAIT_V(n) asm volatile("s_waitcnt vmcnt(" #n ")" ::: "memory")
; #define PG8_WAIT_L(n) asm volatile("s_waitcnt lgkmcnt(" #n ")" ::: "memory")
; #define PG8_BAR __builtin_amdgcn_s_barrier()
; #define PG8_SCHED __builtin_amdgcn_sched_barrier(0)
;     ...
;                 if (w0) { PG8_LDB(B0, 0, 0); PG8_LDB(B1, 0, 1); PG8_SCHED; PG8_LDA(At, 0, 0); }
;                 PG8_WAIT_L(0); PG8_BAR; if (w0) { PG8_MMA(0, 0, At, B0); PG8_MMA(0, 1, At, B1); } PG8_BAR; PG8_SCHED;
;                 PG8_STAGEX(rsB, PG8_SB(0, 0), b2, voffB); PG8_STAGEX(rsB, PG8_SB(0, 1), b2 + hstepB, voffB); PG8_STAGEX(rsA, PG8_SA(0, 0), a2, voffA);
;                 PG8_WAIT_V(6); PG8_BAR; PG8_BAR; PG8_SCHED;
.LBB0_1429:
	v_add_u32_e32 v78, 0x10000, v95
	v_add_u32_e32 v86, 0x14000, v95
	ds_read_b128 v[66:69], v78
	ds_read_b128 v[70:73], v78 offset:1024
	ds_read_b128 v[74:77], v78 offset:2048
	ds_read_b128 v[78:81], v78 offset:3072
	ds_read_b128 v[82:85], v86
	ds_read_b128 v[100:103], v86 offset:1024
	ds_read_b128 v[104:107], v86 offset:2048
	ds_read_b128 v[108:111], v86 offset:3072
	s_cmp_eq_u32 s40, 12
	s_cselect_b32 s41, s38, s39
	s_cselect_b32 s46, s30, s31
	s_add_i32 s47, s41, 0x80
	ds_read_b128 v[112:115], v96
	ds_read_b128 v[116:119], v96 offset:1024
	ds_read_b128 v[120:123], v96 offset:2048
	ds_read_b128 v[124:127], v96 offset:3072
	ds_read_b128 v[128:131], v96 offset:4096
	ds_read_b128 v[132:135], v96 offset:5120
	ds_read_b128 v[136:139], v96 offset:6144
	ds_read_b128 v[140:143], v96 offset:7168
	s_waitcnt lgkmcnt(0)
	s_setprio 1
	s_barrier
	v_mfma_f32_16x16x32_bf16 v[62:65], v[66:69], v[112:115], v[62:65]
	v_mfma_f32_16x16x32_bf16 v[62:65], v[70:73], v[116:119], v[62:65]
	v_mfma_f32_16x16x32_bf16 v[58:61], v[78:81], v[116:119], v[58:61]
	v_mfma_f32_16x16x32_bf16 v[58:61], v[74:77], v[112:115], v[58:61]
	v_mfma_f32_16x16x32_bf16 v[50:53], v[74:77], v[120:123], v[50:53]
	v_mfma_f32_16x16x32_bf16 v[50:53], v[78:81], v[124:127], v[50:53]
	v_mfma_f32_16x16x32_bf16 v[54:57], v[70:73], v[124:127], v[54:57]
	v_mfma_f32_16x16x32_bf16 v[54:57], v[66:69], v[120:123], v[54:57]
	v_mfma_f32_16x16x32_bf16 v[46:49], v[66:69], v[128:131], v[46:49]
	v_mfma_f32_16x16x32_bf16 v[46:49], v[70:73], v[132:135], v[46:49]
	v_mfma_f32_16x16x32_bf16 v[42:45], v[78:81], v[132:135], v[42:45]
	v_mfma_f32_16x16x32_bf16 v[42:45], v[74:77], v[128:131], v[42:45]
	v_mfma_f32_16x16x32_bf16 v[34:37], v[74:77], v[136:139], v[34:37]
	v_mfma_f32_16x16x32_bf16 v[34:37], v[78:81], v[140:143], v[34:37]
	v_mfma_f32_16x16x32_bf16 v[38:41], v[70:73], v[140:143], v[38:41]
	v_mfma_f32_16x16x32_bf16 v[38:41], v[66:69], v[136:139], v[38:41]
	v_mfma_f32_16x16x32_bf16 v[30:33], v[82:85], v[112:115], v[30:33]
	v_mfma_f32_16x16x32_bf16 v[30:33], v[100:103], v[116:119], v[30:33]
	v_mfma_f32_16x16x32_bf16 v[26:29], v[108:111], v[116:119], v[26:29]
	v_mfma_f32_16x16x32_bf16 v[26:29], v[104:107], v[112:115], v[26:29]
	v_mfma_f32_16x16x32_bf16 v[18:21], v[104:107], v[120:123], v[18:21]
	v_mfma_f32_16x16x32_bf16 v[18:21], v[108:111], v[124:127], v[18:21]
	v_mfma_f32_16x16x32_bf16 v[22:25], v[100:103], v[124:127], v[22:25]
	v_mfma_f32_16x16x32_bf16 v[22:25], v[82:85], v[120:123], v[22:25]
	v_mfma_f32_16x16x32_bf16 v[14:17], v[82:85], v[128:131], v[14:17]
	v_mfma_f32_16x16x32_bf16 v[14:17], v[100:103], v[132:135], v[14:17]
	v_mfma_f32_16x16x32_bf16 v[10:13], v[108:111], v[132:135], v[10:13]
	v_mfma_f32_16x16x32_bf16 v[10:13], v[104:107], v[128:131], v[10:13]
	v_mfma_f32_16x16x32_bf16 v[2:5], v[104:107], v[136:139], v[2:5]
	v_mfma_f32_16x16x32_bf16 v[2:5], v[108:111], v[140:143], v[2:5]
	v_mfma_f32_16x16x32_bf16 v[6:9], v[100:103], v[140:143], v[6:9]
	v_mfma_f32_16x16x32_bf16 v[6:9], v[82:85], v[136:139], v[6:9]
	s_barrier
	s_setprio 0
	s_mov_b32 m0, s5
	s_mov_b32 s50, s78
	s_mov_b32 s51, s79
	buffer_load_dwordx4 v89, s[48:51], s46 offen lds
	s_mov_b32 m0, s7
	s_add_i32 s52, s46, 0x40000
	buffer_load_dwordx4 v91, s[48:51], s46 offen lds
	s_mov_b32 m0, s11
	s_nop 0
	buffer_load_dwordx4 v89, s[48:51], s52 offen lds
	s_mov_b32 m0, s12
	s_nop 0
	buffer_load_dwordx4 v91, s[48:51], s52 offen lds
	s_mov_b32 m0, s3
	s_nop 0
	buffer_load_dwordx4 v88, s[76:79], s41 offen lds
	s_mov_b32 m0, s13
	s_nop 0
	buffer_load_dwordx4 v90, s[76:79], s41 offen lds
	s_waitcnt vmcnt(6)
	s_barrier
	s_barrier
; #define PG8_STAGEX(rs, bufoff, soff, voff) do { _Pragma("unroll") for (int _i = 0; _i < 2; ++_i) \
;         __builtin_amdgcn_raw_ptr_buffer_load_lds(rs, (LAS unsigned*)(lds + (bufoff) + ldsw + _i * 8192), 16, (voff)[_i], (soff), 0, 0); } while (0)
; #define PG8_LDA(dst, b, h) do { _Pragma("unroll") for (int m = 0; m < 4; ++m) _Pragma("unroll") for (int k = 0; k < 2; ++k) dst[m][k] = *(const LAS bf16x8*)(lds + PG8_SA(b, h) + aoff + m * 2048 + k * 1024); } while (0)
; #define PG8_LDB(dst, b, h) do { _Pragma("unroll") for (int n = 0; n < 2; ++n) _Pragma("unroll") for (int k = 0; k < 2; ++k) dst[n][k] = *(const LAS bf16x8*)(lds + PG8_SB(b, h) + boff + n * 2048 + k * 1024); } while (0)
; #define PG8_WAIT_V(n) asm volatile("s_waitcnt vmcnt(" #n ")" ::: "memory")
; #define PG8_WAIT_L(n) asm volatile("s_waitcnt lgkmcnt(" #n ")" ::: "memory")
; #define PG8_BAR __builtin_amdgcn_s_barrier()
; #define PG8_SCHED __builtin_amdgcn_sched_barrier(0)
;     ...
;                 if (w0) { PG8_LDB(B0, 1, 0); PG8_LDB(B1, 1, 1); PG8_SCHED; PG8_LDA(At, 1, 0); }
;                 PG8_WAIT_L(0); PG8_BAR; if (w0) { PG8_MMA(0, 0, At, B0); PG8_MMA(0, 1, At, B1); } PG8_BAR; PG8_SCHED;
;                 PG8_STAGEX(rsB, PG8_SB(1, 0), b3, voffB); PG8_STAGEX(rsB, PG8_SB(1, 1), b3 + hstepB, voffB); PG8_STAGEX(rsA, PG8_SA(1, 0), a3, voffA);
;                 PG8_WAIT_V(6); PG8_BAR; PG8_BAR; PG8_SCHED;
;             }
;         }
;         if (wr == 0) PG8_BAR;
	v_add_u32_e32 v78, 0x18000, v95
	v_add_u32_e32 v86, 0x1c000, v95
	ds_read_b128 v[66:69], v78
	ds_read_b128 v[70:73], v78 offset:1024
	ds_read_b128 v[74:77], v78 offset:2048
	ds_read_b128 v[78:81], v78 offset:3072
	ds_read_b128 v[82:85], v86
	ds_read_b128 v[100:103], v86 offset:1024
	ds_read_b128 v[104:107], v86 offset:2048
	ds_read_b128 v[108:111], v86 offset:3072
	ds_read_b128 v[112:115], v96 offset:32768
	ds_read_b128 v[116:119], v96 offset:33792
	ds_read_b128 v[120:123], v96 offset:34816
	ds_read_b128 v[124:127], v96 offset:35840
	ds_read_b128 v[128:131], v96 offset:36864
	ds_read_b128 v[132:135], v96 offset:37888
	ds_read_b128 v[136:139], v96 offset:38912
	ds_read_b128 v[140:143], v96 offset:39936
	s_waitcnt lgkmcnt(0)
	s_setprio 1
	s_barrier
	v_mfma_f32_16x16x32_bf16 v[62:65], v[66:69], v[112:115], v[62:65]
	v_mfma_f32_16x16x32_bf16 v[58:61], v[74:77], v[112:115], v[58:61]
	v_mfma_f32_16x16x32_bf16 v[54:57], v[66:69], v[120:123], v[54:57]
	v_mfma_f32_16x16x32_bf16 v[50:53], v[74:77], v[120:123], v[50:53]
	v_mfma_f32_16x16x32_bf16 v[46:49], v[66:69], v[128:131], v[46:49]
	v_mfma_f32_16x16x32_bf16 v[42:45], v[74:77], v[128:131], v[42:45]
	v_mfma_f32_16x16x32_bf16 v[38:41], v[66:69], v[136:139], v[38:41]
	v_mfma_f32_16x16x32_bf16 v[34:37], v[74:77], v[136:139], v[34:37]
	v_mfma_f32_16x16x32_bf16 v[62:65], v[70:73], v[116:119], v[62:65]
	v_mfma_f32_16x16x32_bf16 v[58:61], v[78:81], v[116:119], v[58:61]
	v_mfma_f32_16x16x32_bf16 v[54:57], v[70:73], v[124:127], v[54:57]
	v_mfma_f32_16x16x32_bf16 v[50:53], v[78:81], v[124:127], v[50:53]
	v_mfma_f32_16x16x32_bf16 v[46:49], v[70:73], v[132:135], v[46:49]
	v_mfma_f32_16x16x32_bf16 v[42:45], v[78:81], v[132:135], v[42:45]
	v_mfma_f32_16x16x32_bf16 v[38:41], v[70:73], v[140:143], v[38:41]
	v_mfma_f32_16x16x32_bf16 v[34:37], v[78:81], v[140:143], v[34:37]
	v_mfma_f32_16x16x32_bf16 v[30:33], v[82:85], v[112:115], v[30:33]
	s_add_i32 s41, s46, 0x80
	v_mfma_f32_16x16x32_bf16 v[26:29], v[104:107], v[112:115], v[26:29]
	v_mfma_f32_16x16x32_bf16 v[22:25], v[82:85], v[120:123], v[22:25]
	v_mfma_f32_16x16x32_bf16 v[18:21], v[104:107], v[120:123], v[18:21]
	v_mfma_f32_16x16x32_bf16 v[14:17], v[82:85], v[128:131], v[14:17]
	v_mfma_f32_16x16x32_bf16 v[10:13], v[104:107], v[128:131], v[10:13]
	v_mfma_f32_16x16x32_bf16 v[6:9], v[82:85], v[136:139], v[6:9]
	v_mfma_f32_16x16x32_bf16 v[2:5], v[104:107], v[136:139], v[2:5]
	v_mfma_f32_16x16x32_bf16 v[30:33], v[100:103], v[116:119], v[30:33]
	v_mfma_f32_16x16x32_bf16 v[26:29], v[108:111], v[116:119], v[26:29]
	v_mfma_f32_16x16x32_bf16 v[22:25], v[100:103], v[124:127], v[22:25]
	v_mfma_f32_16x16x32_bf16 v[18:21], v[108:111], v[124:127], v[18:21]
	v_mfma_f32_16x16x32_bf16 v[14:17], v[100:103], v[132:135], v[14:17]
	v_mfma_f32_16x16x32_bf16 v[10:13], v[108:111], v[132:135], v[10:13]
	v_mfma_f32_16x16x32_bf16 v[6:9], v[100:103], v[140:143], v[6:9]
	v_mfma_f32_16x16x32_bf16 v[2:5], v[108:111], v[140:143], v[2:5]
	s_barrier
	s_setprio 0
	s_mov_b32 m0, s14
	s_add_i32 s46, s46, 0x40080
	buffer_load_dwordx4 v89, s[48:51], s41 offen lds
	s_mov_b32 m0, s15
	s_nop 0
	buffer_load_dwordx4 v91, s[48:51], s41 offen lds
	s_mov_b32 m0, s18
	s_nop 0
	buffer_load_dwordx4 v89, s[48:51], s46 offen lds
	s_mov_b32 m0, s19
	s_nop 0
	buffer_load_dwordx4 v91, s[48:51], s46 offen lds
	s_mov_b32 m0, s16
	s_nop 0
	buffer_load_dwordx4 v88, s[76:79], s47 offen lds
	s_mov_b32 m0, s17
	s_nop 0
	buffer_load_dwordx4 v90, s[76:79], s47 offen lds
	s_waitcnt vmcnt(6)
	s_barrier
	s_barrier
	s_add_i32 s40, s40, 2
	s_addk_i32 s31, 0x100
	s_addk_i32 s39, 0x100
	s_cmp_gt_u32 s40, 13
	s_cbranch_scc0 .LBB0_1429
	s_and_b64 vcc, exec, s[42:43]
	s_cbranch_vccz .LBB0_1432
	s_barrier

; #define PG8_STAGEX(rs, bufoff, soff, voff) do { _Pragma("unroll") for (int _i = 0; _i < 2; ++_i) \
;         __builtin_amdgcn_raw_ptr_buffer_load_lds(rs, (LAS unsigned*)(lds + (bufoff) + ldsw + _i * 8192), 16, (voff)[_i], (soff), 0, 0); } while (0)
; #define PG8_LDA(dst, b, h) do { _Pragma("unroll") for (int m = 0; m < 4; ++m) _Pragma("unroll") for (int k = 0; k < 2; ++k) dst[m][k] = *(const LAS bf16x8*)(lds + PG8_SA(b, h) + aoff + m * 2048 + k * 1024); } while (0)
; #define PG8_LDB(dst, b, h) do { _Pragma("unroll") for (int n = 0; n < 2; ++n) _Pragma("unroll") for (int k = 0; k < 2; ++k) dst[n][k] = *(const LAS bf16x8*)(lds + PG8_SB(b, h) + boff + n * 2048 + k * 1024); } while (0)
; #define PG8_WAIT_V(n) asm volatile("s_waitcnt vmcnt(" #n ")" ::: "memory")
; #define PG8_WAIT_L(n) asm volatile("s_waitcnt lgkmcnt(" #n ")" ::: "memory")
; #define PG8_BAR __builtin_amdgcn_s_barrier()
; #define PG8_SCHED __builtin_amdgcn_sched_barrier(0)
;     ...
;             const unsigned a1 = cA + (unsigned)(t + 1) * kstep;
;             const unsigned a2 = last ? nA : cA + (unsigned)(t + 2) * kstep, b2 = last ? nB : cB + (unsigned)(t + 2) * kstep;
;             const unsigned a3 = a2 + kstep, b3 = b2 + kstep;
;             PG8_LDB(B0, 0, 0); PG8_LDB(B1, 0, 1); PG8_SCHED; PG8_LDA(At, 0, 0); PG8_STAGEX(rsA, PG8_SA(1, 1), a1 + hstepA, voffA);
;             PG8_WAIT_V(8); PG8_WAIT_L(0); PG8_BAR; PG8_MMA(0, 0, At, B0); PG8_MMA(0, 1, At, B1); PG8_BAR; PG8_SCHED;
;             PG8_LDA(At, 0, 1); PG8_STAGEX(rsB, PG8_SB(0, 0), b2, voffB); PG8_STAGEX(rsB, PG8_SB(0, 1), b2 + hstepB, voffB); PG8_STAGEX(rsA, PG8_SA(0, 0), a2, voffA);
;             PG8_WAIT_V(8); PG8_WAIT_L(0); PG8_BAR; PG8_MMA(1, 0, At, B0); PG8_MMA(1, 1, At, B1); PG8_BAR; PG8_SCHED;
.LBB0_1529:
	v_add_u32_e32 v118, 0x10000, v210
	v_add_u32_e32 v142, 0x14000, v210
	ds_read_b128 v[106:109], v118
	ds_read_b128 v[110:113], v118 offset:1024
	ds_read_b128 v[114:117], v118 offset:2048
	ds_read_b128 v[118:121], v118 offset:3072
	ds_read_b128 v[122:125], v142
	ds_read_b128 v[126:129], v142 offset:1024
	ds_read_b128 v[130:133], v142 offset:2048
	ds_read_b128 v[142:145], v142 offset:3072
	s_add_i32 s46, s59, 0xfff80080
	s_cmp_eq_u32 s64, 28
	s_cselect_b32 s67, s30, s46
	s_cselect_b32 s66, s31, s63
	s_or_b32 s65, s67, 0x80
	s_mov_b32 m0, s76
	ds_read_b128 v[164:167], v211
	ds_read_b128 v[168:171], v211 offset:1024
	ds_read_b128 v[182:185], v211 offset:2048
	ds_read_b128 v[186:189], v211 offset:3072
	ds_read_b128 v[190:193], v211 offset:4096
	ds_read_b128 v[194:197], v211 offset:5120
	ds_read_b128 v[198:201], v211 offset:6144
	ds_read_b128 v[202:205], v211 offset:7168
	buffer_load_dwordx4 v178, s[40:43], s59 offen lds
	s_mov_b32 m0, s77
	s_nop 0
	buffer_load_dwordx4 v206, s[40:43], s59 offen lds
	s_waitcnt vmcnt(8)
	s_waitcnt lgkmcnt(0)
	s_setprio 1
	s_barrier
	v_mfma_f32_16x16x32_bf16 v[158:161], v[106:109], v[164:167], v[158:161]
	v_mfma_f32_16x16x32_bf16 v[158:161], v[110:113], v[168:171], v[158:161]
	v_mfma_f32_16x16x32_bf16 v[154:157], v[118:121], v[168:171], v[154:157]
	v_mfma_f32_16x16x32_bf16 v[154:157], v[114:117], v[164:167], v[154:157]
	v_mfma_f32_16x16x32_bf16 v[146:149], v[114:117], v[182:185], v[146:149]
	v_mfma_f32_16x16x32_bf16 v[146:149], v[118:121], v[186:189], v[146:149]
	v_mfma_f32_16x16x32_bf16 v[150:153], v[110:113], v[186:189], v[150:153]
	v_mfma_f32_16x16x32_bf16 v[150:153], v[106:109], v[182:185], v[150:153]
	v_mfma_f32_16x16x32_bf16 v[138:141], v[106:109], v[190:193], v[138:141]
	v_mfma_f32_16x16x32_bf16 v[138:141], v[110:113], v[194:197], v[138:141]
	v_mfma_f32_16x16x32_bf16 v[134:137], v[118:121], v[194:197], v[134:137]
	v_mfma_f32_16x16x32_bf16 v[134:137], v[114:117], v[190:193], v[134:137]
	v_mfma_f32_16x16x32_bf16 v[98:101], v[114:117], v[198:201], v[98:101]
	v_mfma_f32_16x16x32_bf16 v[98:101], v[118:121], v[202:205], v[98:101]
	v_mfma_f32_16x16x32_bf16 v[102:105], v[110:113], v[202:205], v[102:105]
	v_mfma_f32_16x16x32_bf16 v[102:105], v[106:109], v[198:201], v[102:105]
	v_mfma_f32_16x16x32_bf16 v[62:65], v[122:125], v[164:167], v[62:65]
	v_mfma_f32_16x16x32_bf16 v[62:65], v[126:129], v[168:171], v[62:65]
	v_mfma_f32_16x16x32_bf16 v[58:61], v[142:145], v[168:171], v[58:61]
	v_mfma_f32_16x16x32_bf16 v[58:61], v[130:133], v[164:167], v[58:61]
	v_mfma_f32_16x16x32_bf16 v[50:53], v[130:133], v[182:185], v[50:53]
	v_mfma_f32_16x16x32_bf16 v[50:53], v[142:145], v[186:189], v[50:53]
	v_mfma_f32_16x16x32_bf16 v[54:57], v[126:129], v[186:189], v[54:57]
	v_mfma_f32_16x16x32_bf16 v[54:57], v[122:125], v[182:185], v[54:57]
	v_mfma_f32_16x16x32_bf16 v[46:49], v[122:125], v[190:193], v[46:49]
	v_mfma_f32_16x16x32_bf16 v[46:49], v[126:129], v[194:197], v[46:49]
	v_mfma_f32_16x16x32_bf16 v[42:45], v[142:145], v[194:197], v[42:45]
	v_mfma_f32_16x16x32_bf16 v[42:45], v[130:133], v[190:193], v[42:45]
	v_mfma_f32_16x16x32_bf16 v[34:37], v[130:133], v[198:201], v[34:37]
	v_mfma_f32_16x16x32_bf16 v[34:37], v[142:145], v[202:205], v[34:37]
	v_mfma_f32_16x16x32_bf16 v[38:41], v[126:129], v[202:205], v[38:41]
	v_mfma_f32_16x16x32_bf16 v[38:41], v[122:125], v[198:201], v[38:41]
	s_barrier
	s_setprio 0
	s_mov_b32 m0, s17
	s_mov_b32 s46, s42
	s_mov_b32 s47, s43
	ds_read_b128 v[164:167], v211 offset:16384
	ds_read_b128 v[168:171], v211 offset:17408
	ds_read_b128 v[182:185], v211 offset:18432
	ds_read_b128 v[186:189], v211 offset:19456
	ds_read_b128 v[190:193], v211 offset:20480
	ds_read_b128 v[194:197], v211 offset:21504
	ds_read_b128 v[198:201], v211 offset:22528
	ds_read_b128 v[202:205], v211 offset:23552
	buffer_load_dwordx4 v179, s[44:47], s66 offen lds
	s_mov_b32 m0, s18
	s_add_i32 s68, s66, 0x80000
	buffer_load_dwordx4 v207, s[44:47], s66 offen lds
	s_mov_b32 m0, s19
	s_nop 0
	buffer_load_dwordx4 v179, s[44:47], s68 offen lds
	s_mov_b32 m0, s20
	s_nop 0
	buffer_load_dwordx4 v207, s[44:47], s68 offen lds
	s_mov_b32 m0, s16
	s_nop 0
	buffer_load_dwordx4 v178, s[40:43], s67 offen lds
	s_mov_b32 m0, s21
	s_nop 0
	buffer_load_dwordx4 v206, s[40:43], s67 offen lds
	s_waitcnt vmcnt(8)
	s_waitcnt lgkmcnt(0)
	s_setprio 1
	s_barrier
	v_mfma_f32_16x16x32_bf16 v[94:97], v[106:109], v[164:167], v[94:97]
	v_mfma_f32_16x16x32_bf16 v[94:97], v[110:113], v[168:171], v[94:97]
	v_mfma_f32_16x16x32_bf16 v[90:93], v[118:121], v[168:171], v[90:93]
	v_mfma_f32_16x16x32_bf16 v[90:93], v[114:117], v[164:167], v[90:93]
	v_mfma_f32_16x16x32_bf16 v[82:85], v[114:117], v[182:185], v[82:85]
	v_mfma_f32_16x16x32_bf16 v[82:85], v[118:121], v[186:189], v[82:85]
	v_mfma_f32_16x16x32_bf16 v[86:89], v[110:113], v[186:189], v[86:89]
	v_mfma_f32_16x16x32_bf16 v[86:89], v[106:109], v[182:185], v[86:89]
	v_mfma_f32_16x16x32_bf16 v[78:81], v[106:109], v[190:193], v[78:81]
	v_mfma_f32_16x16x32_bf16 v[78:81], v[110:113], v[194:197], v[78:81]
	v_mfma_f32_16x16x32_bf16 v[74:77], v[118:121], v[194:197], v[74:77]
	v_mfma_f32_16x16x32_bf16 v[74:77], v[114:117], v[190:193], v[74:77]
	v_mfma_f32_16x16x32_bf16 v[66:69], v[114:117], v[198:201], v[66:69]
	v_mfma_f32_16x16x32_bf16 v[66:69], v[118:121], v[202:205], v[66:69]
	v_mfma_f32_16x16x32_bf16 v[70:73], v[110:113], v[202:205], v[70:73]
	v_mfma_f32_16x16x32_bf16 v[70:73], v[106:109], v[198:201], v[70:73]
	v_mfma_f32_16x16x32_bf16 v[30:33], v[122:125], v[164:167], v[30:33]
	v_mfma_f32_16x16x32_bf16 v[30:33], v[126:129], v[168:171], v[30:33]
	v_mfma_f32_16x16x32_bf16 v[26:29], v[142:145], v[168:171], v[26:29]
	v_mfma_f32_16x16x32_bf16 v[26:29], v[130:133], v[164:167], v[26:29]
	v_mfma_f32_16x16x32_bf16 v[18:21], v[130:133], v[182:185], v[18:21]
	v_mfma_f32_16x16x32_bf16 v[18:21], v[142:145], v[186:189], v[18:21]
	v_mfma_f32_16x16x32_bf16 v[22:25], v[126:129], v[186:189], v[22:25]
	v_mfma_f32_16x16x32_bf16 v[22:25], v[122:125], v[182:185], v[22:25]
	v_mfma_f32_16x16x32_bf16 v[14:17], v[122:125], v[190:193], v[14:17]
	v_mfma_f32_16x16x32_bf16 v[14:17], v[126:129], v[194:197], v[14:17]
	v_mfma_f32_16x16x32_bf16 v[10:13], v[142:145], v[194:197], v[10:13]
	v_mfma_f32_16x16x32_bf16 v[10:13], v[130:133], v[190:193], v[10:13]
	v_mfma_f32_16x16x32_bf16 v[2:5], v[130:133], v[198:201], v[2:5]
	v_mfma_f32_16x16x32_bf16 v[2:5], v[142:145], v[202:205], v[2:5]
	v_mfma_f32_16x16x32_bf16 v[6:9], v[126:129], v[202:205], v[6:9]
	v_mfma_f32_16x16x32_bf16 v[6:9], v[122:125], v[198:201], v[6:9]
	s_barrier
; #define PG8_STAGEX(rs, bufoff, soff, voff) do { _Pragma("unroll") for (int _i = 0; _i < 2; ++_i) \
;         __builtin_amdgcn_raw_ptr_buffer_load_lds(rs, (LAS unsigned*)(lds + (bufoff) + ldsw + _i * 8192), 16, (voff)[_i], (soff), 0, 0); } while (0)
; #define PG8_LDA(dst, b, h) do { _Pragma("unroll") for (int m = 0; m < 4; ++m) _Pragma("unroll") for (int k = 0; k < 2; ++k) dst[m][k] = *(const LAS bf16x8*)(lds + PG8_SA(b, h) + aoff + m * 2048 + k * 1024); } while (0)
; #define PG8_LDB(dst, b, h) do { _Pragma("unroll") for (int n = 0; n < 2; ++n) _Pragma("unroll") for (int k = 0; k < 2; ++k) dst[n][k] = *(const LAS bf16x8*)(lds + PG8_SB(b, h) + boff + n * 2048 + k * 1024); } while (0)
; #define PG8_WAIT_V(n) asm volatile("s_waitcnt vmcnt(" #n ")" ::: "memory")
; #define PG8_WAIT_L(n) asm volatile("s_waitcnt lgkmcnt(" #n ")" ::: "memory")
; #define PG8_BAR __builtin_amdgcn_s_barrier()
; #define PG8_SCHED __builtin_amdgcn_sched_barrier(0)
;     ...
;             PG8_LDB(B0, 1, 0); PG8_LDB(B1, 1, 1); PG8_SCHED; PG8_LDA(At, 1, 0); PG8_STAGEX(rsA, PG8_SA(0, 1), a2 + hstepA, voffA);
;             PG8_WAIT_V(8); PG8_WAIT_L(0); PG8_BAR; PG8_MMA(0, 0, At, B0); PG8_MMA(0, 1, At, B1); PG8_BAR; PG8_SCHED;
;             PG8_LDA(At, 1, 1); PG8_STAGEX(rsB, PG8_SB(1, 0), b3, voffB); PG8_STAGEX(rsB, PG8_SB(1, 1), b3 + hstepB, voffB); PG8_STAGEX(rsA, PG8_SA(1, 0), a3, voffA);
;             PG8_WAIT_V(8); PG8_WAIT_L(0); PG8_BAR; PG8_MMA(1, 0, At, B0); PG8_MMA(1, 1, At, B1); PG8_BAR; PG8_SCHED;
;     ...
;         }
;         if (wr == 0) PG8_BAR;
	s_setprio 0
	v_add_u32_e32 v118, 0x18000, v210
	v_add_u32_e32 v142, 0x1c000, v210
	ds_read_b128 v[106:109], v118
	ds_read_b128 v[110:113], v118 offset:1024
	ds_read_b128 v[114:117], v118 offset:2048
	ds_read_b128 v[118:121], v118 offset:3072
	ds_read_b128 v[122:125], v142
	ds_read_b128 v[126:129], v142 offset:1024
	ds_read_b128 v[130:133], v142 offset:2048
	ds_read_b128 v[142:145], v142 offset:3072
	s_add_i32 s67, s67, 0x80000
	s_mov_b32 m0, s22
	ds_read_b128 v[164:167], v211 offset:32768
	ds_read_b128 v[168:171], v211 offset:33792
	ds_read_b128 v[182:185], v211 offset:34816
	ds_read_b128 v[186:189], v211 offset:35840
	ds_read_b128 v[190:193], v211 offset:36864
	ds_read_b128 v[194:197], v211 offset:37888
	ds_read_b128 v[198:201], v211 offset:38912
	ds_read_b128 v[202:205], v211 offset:39936
	buffer_load_dwordx4 v178, s[40:43], s67 offen lds
	s_mov_b32 m0, s23
	s_nop 0
	buffer_load_dwordx4 v206, s[40:43], s67 offen lds
	s_waitcnt vmcnt(8)
	s_waitcnt lgkmcnt(0)
	s_setprio 1
	s_barrier
	v_mfma_f32_16x16x32_bf16 v[158:161], v[106:109], v[164:167], v[158:161]
	v_mfma_f32_16x16x32_bf16 v[158:161], v[110:113], v[168:171], v[158:161]
	v_mfma_f32_16x16x32_bf16 v[154:157], v[118:121], v[168:171], v[154:157]
	v_mfma_f32_16x16x32_bf16 v[154:157], v[114:117], v[164:167], v[154:157]
	v_mfma_f32_16x16x32_bf16 v[146:149], v[114:117], v[182:185], v[146:149]
	v_mfma_f32_16x16x32_bf16 v[146:149], v[118:121], v[186:189], v[146:149]
	v_mfma_f32_16x16x32_bf16 v[150:153], v[110:113], v[186:189], v[150:153]
	v_mfma_f32_16x16x32_bf16 v[150:153], v[106:109], v[182:185], v[150:153]
	v_mfma_f32_16x16x32_bf16 v[138:141], v[106:109], v[190:193], v[138:141]
	v_mfma_f32_16x16x32_bf16 v[138:141], v[110:113], v[194:197], v[138:141]
	v_mfma_f32_16x16x32_bf16 v[134:137], v[118:121], v[194:197], v[134:137]
	v_mfma_f32_16x16x32_bf16 v[134:137], v[114:117], v[190:193], v[134:137]
	v_mfma_f32_16x16x32_bf16 v[98:101], v[114:117], v[198:201], v[98:101]
	v_mfma_f32_16x16x32_bf16 v[98:101], v[118:121], v[202:205], v[98:101]
	v_mfma_f32_16x16x32_bf16 v[102:105], v[110:113], v[202:205], v[102:105]
	v_mfma_f32_16x16x32_bf16 v[102:105], v[106:109], v[198:201], v[102:105]
	v_mfma_f32_16x16x32_bf16 v[62:65], v[122:125], v[164:167], v[62:65]
	v_mfma_f32_16x16x32_bf16 v[62:65], v[126:129], v[168:171], v[62:65]
	v_mfma_f32_16x16x32_bf16 v[58:61], v[142:145], v[168:171], v[58:61]
	v_mfma_f32_16x16x32_bf16 v[58:61], v[130:133], v[164:167], v[58:61]
	v_mfma_f32_16x16x32_bf16 v[50:53], v[130:133], v[182:185], v[50:53]
	v_mfma_f32_16x16x32_bf16 v[50:53], v[142:145], v[186:189], v[50:53]
	v_mfma_f32_16x16x32_bf16 v[54:57], v[126:129], v[186:189], v[54:57]
	v_mfma_f32_16x16x32_bf16 v[54:57], v[122:125], v[182:185], v[54:57]
	v_mfma_f32_16x16x32_bf16 v[46:49], v[122:125], v[190:193], v[46:49]
	v_mfma_f32_16x16x32_bf16 v[46:49], v[126:129], v[194:197], v[46:49]
	v_mfma_f32_16x16x32_bf16 v[42:45], v[142:145], v[194:197], v[42:45]
	v_mfma_f32_16x16x32_bf16 v[42:45], v[130:133], v[190:193], v[42:45]
	v_mfma_f32_16x16x32_bf16 v[34:37], v[130:133], v[198:201], v[34:37]
	v_mfma_f32_16x16x32_bf16 v[34:37], v[142:145], v[202:205], v[34:37]
	v_mfma_f32_16x16x32_bf16 v[38:41], v[126:129], v[202:205], v[38:41]
	v_mfma_f32_16x16x32_bf16 v[38:41], v[122:125], v[198:201], v[38:41]
	s_barrier
	s_setprio 0
	s_mov_b32 m0, s54
	s_or_b32 s67, s66, 0x80
	ds_read_b128 v[164:167], v211 offset:49152
	ds_read_b128 v[168:171], v211 offset:50176
	ds_read_b128 v[182:185], v211 offset:51200
	ds_read_b128 v[186:189], v211 offset:52224
	ds_read_b128 v[190:193], v211 offset:53248
	ds_read_b128 v[194:197], v211 offset:54272
	ds_read_b128 v[198:201], v211 offset:55296
	ds_read_b128 v[202:205], v211 offset:56320
	buffer_load_dwordx4 v179, s[44:47], s67 offen lds
	s_mov_b32 m0, s55
	s_add_i32 s66, s66, 0x80080
	buffer_load_dwordx4 v207, s[44:47], s67 offen lds
	s_mov_b32 m0, s74
	s_nop 0
	buffer_load_dwordx4 v179, s[44:47], s66 offen lds
	s_mov_b32 m0, s75
	s_nop 0
	buffer_load_dwordx4 v207, s[44:47], s66 offen lds
	s_mov_b32 m0, s72
	s_nop 0
	buffer_load_dwordx4 v178, s[40:43], s65 offen lds
	s_mov_b32 m0, s73
	s_nop 0
	buffer_load_dwordx4 v206, s[40:43], s65 offen lds
	s_waitcnt vmcnt(8)
	s_waitcnt lgkmcnt(0)
	s_setprio 1
	s_barrier
	v_mfma_f32_16x16x32_bf16 v[94:97], v[106:109], v[164:167], v[94:97]
	v_mfma_f32_16x16x32_bf16 v[94:97], v[110:113], v[168:171], v[94:97]
	v_mfma_f32_16x16x32_bf16 v[90:93], v[118:121], v[168:171], v[90:93]
	v_mfma_f32_16x16x32_bf16 v[90:93], v[114:117], v[164:167], v[90:93]
	v_mfma_f32_16x16x32_bf16 v[82:85], v[114:117], v[182:185], v[82:85]
	v_mfma_f32_16x16x32_bf16 v[82:85], v[118:121], v[186:189], v[82:85]
	v_mfma_f32_16x16x32_bf16 v[86:89], v[110:113], v[186:189], v[86:89]
	v_mfma_f32_16x16x32_bf16 v[86:89], v[106:109], v[182:185], v[86:89]
	v_mfma_f32_16x16x32_bf16 v[78:81], v[106:109], v[190:193], v[78:81]
	v_mfma_f32_16x16x32_bf16 v[78:81], v[110:113], v[194:197], v[78:81]
	v_mfma_f32_16x16x32_bf16 v[74:77], v[118:121], v[194:197], v[74:77]
	v_mfma_f32_16x16x32_bf16 v[74:77], v[114:117], v[190:193], v[74:77]
	v_mfma_f32_16x16x32_bf16 v[66:69], v[114:117], v[198:201], v[66:69]
	v_mfma_f32_16x16x32_bf16 v[66:69], v[118:121], v[202:205], v[66:69]
	v_mfma_f32_16x16x32_bf16 v[70:73], v[110:113], v[202:205], v[70:73]
	v_mfma_f32_16x16x32_bf16 v[70:73], v[106:109], v[198:201], v[70:73]
	v_mfma_f32_16x16x32_bf16 v[30:33], v[122:125], v[164:167], v[30:33]
	v_mfma_f32_16x16x32_bf16 v[30:33], v[126:129], v[168:171], v[30:33]
	v_mfma_f32_16x16x32_bf16 v[26:29], v[142:145], v[168:171], v[26:29]
	v_mfma_f32_16x16x32_bf16 v[26:29], v[130:133], v[164:167], v[26:29]
	v_mfma_f32_16x16x32_bf16 v[18:21], v[130:133], v[182:185], v[18:21]
	v_mfma_f32_16x16x32_bf16 v[18:21], v[142:145], v[186:189], v[18:21]
	v_mfma_f32_16x16x32_bf16 v[22:25], v[126:129], v[186:189], v[22:25]
	v_mfma_f32_16x16x32_bf16 v[22:25], v[122:125], v[182:185], v[22:25]
	v_mfma_f32_16x16x32_bf16 v[14:17], v[122:125], v[190:193], v[14:17]
	v_mfma_f32_16x16x32_bf16 v[14:17], v[126:129], v[194:197], v[14:17]
	v_mfma_f32_16x16x32_bf16 v[10:13], v[142:145], v[194:197], v[10:13]
	v_mfma_f32_16x16x32_bf16 v[10:13], v[130:133], v[190:193], v[10:13]
	v_mfma_f32_16x16x32_bf16 v[2:5], v[130:133], v[198:201], v[2:5]
	v_mfma_f32_16x16x32_bf16 v[2:5], v[142:145], v[202:205], v[2:5]
	v_mfma_f32_16x16x32_bf16 v[6:9], v[126:129], v[202:205], v[6:9]
	v_mfma_f32_16x16x32_bf16 v[6:9], v[122:125], v[198:201], v[6:9]
	s_barrier
	s_setprio 0
	s_add_i32 s64, s64, 2
	s_addk_i32 s59, 0x100
	s_addk_i32 s63, 0x100
	s_cmp_gt_u32 s64, 29
	s_cbranch_scc0 .LBB0_1529
	s_and_b64 vcc, exec, s[52:53]
	s_cbranch_vccz .LBB0_1532
	s_barrier

; #define PG8_STAGEX(rs, bufoff, soff, voff) do { _Pragma("unroll") for (int _i = 0; _i < 2; ++_i) \
;         __builtin_amdgcn_raw_ptr_buffer_load_lds(rs, (LAS unsigned*)(lds + (bufoff) + ldsw + _i * 8192), 16, (voff)[_i], (soff), 0, 0); } while (0)
; #define PG8_LDA(dst, b, h) do { _Pragma("unroll") for (int m = 0; m < 4; ++m) _Pragma("unroll") for (int k = 0; k < 2; ++k) dst[m][k] = *(const LAS bf16x8*)(lds + PG8_SA(b, h) + aoff + m * 2048 + k * 1024); } while (0)
; #define PG8_LDB(dst, b, h) do { _Pragma("unroll") for (int n = 0; n < 2; ++n) _Pragma("unroll") for (int k = 0; k < 2; ++k) dst[n][k] = *(const LAS bf16x8*)(lds + PG8_SB(b, h) + boff + n * 2048 + k * 1024); } while (0)
; #define PG8_WAIT_V(n) asm volatile("s_waitcnt vmcnt(" #n ")" ::: "memory")
; #define PG8_WAIT_L(n) asm volatile("s_waitcnt lgkmcnt(" #n ")" ::: "memory")
; #define PG8_BAR __builtin_amdgcn_s_barrier()
; #define PG8_SCHED __builtin_amdgcn_sched_barrier(0)
;     ...
;             const unsigned a1 = cA + (unsigned)(t + 1) * kstep;
;             const unsigned a2 = last ? nA : cA + (unsigned)(t + 2) * kstep, b2 = last ? nB : cB + (unsigned)(t + 2) * kstep;
;             const unsigned a3 = a2 + kstep, b3 = b2 + kstep;
;             PG8_LDB(B0, 0, 0); PG8_LDB(B1, 0, 1); PG8_SCHED; PG8_LDA(At, 0, 0); PG8_STAGEX(rsA, PG8_SA(1, 1), a1 + hstepA, voffA);
;             PG8_WAIT_V(8); PG8_WAIT_L(0); PG8_BAR; PG8_MMA(0, 0, At, B0); PG8_MMA(0, 1, At, B1); PG8_BAR; PG8_SCHED;
;             PG8_LDA(At, 0, 1); PG8_STAGEX(rsB, PG8_SB(0, 0), b2, voffB); PG8_STAGEX(rsB, PG8_SB(0, 1), b2 + hstepB, voffB); PG8_STAGEX(rsA, PG8_SA(0, 0), a2, voffA);
;             PG8_WAIT_V(8); PG8_WAIT_L(0); PG8_BAR; PG8_MMA(1, 0, At, B0); PG8_MMA(1, 1, At, B1); PG8_BAR; PG8_SCHED;
.LBB0_1651:
	v_add_u32_e32 v102, 0x10000, v172
	v_add_u32_e32 v146, 0x14000, v172
	ds_read_b128 v[82:85], v102
	ds_read_b128 v[86:89], v102 offset:1024
	ds_read_b128 v[98:101], v102 offset:2048
	ds_read_b128 v[102:105], v102 offset:3072
	ds_read_b128 v[150:153], v146
	ds_read_b128 v[154:157], v146 offset:1024
	ds_read_b128 v[182:185], v146 offset:2048
	ds_read_b128 v[186:189], v146 offset:3072
	s_add_i32 s42, s61, 0xfff80080
	s_cmp_eq_u32 s63, 28
	s_cselect_b32 s66, s30, s42
	s_cselect_b32 s65, s31, s62
	s_or_b32 s64, s66, 0x80
	s_mov_b32 m0, s29
	ds_read_b128 v[190:193], v173
	ds_read_b128 v[194:197], v173 offset:1024
	ds_read_b128 v[198:201], v173 offset:2048
	ds_read_b128 v[202:205], v173 offset:3072
	ds_read_b128 v[206:209], v173 offset:4096
	ds_read_b128 v[210:213], v173 offset:5120
	ds_read_b128 v[214:217], v173 offset:6144
	ds_read_b128 v[218:221], v173 offset:7168
	buffer_load_dwordx4 v159, s[76:79], s61 offen lds
	s_mov_b32 m0, s50
	s_nop 0
	buffer_load_dwordx4 v163, s[76:79], s61 offen lds
	s_waitcnt vmcnt(8)
	s_waitcnt lgkmcnt(0)
	s_setprio 1
	s_barrier
	v_mfma_f32_16x16x32_bf16 v[142:145], v[82:85], v[190:193], v[142:145]
	v_mfma_f32_16x16x32_bf16 v[142:145], v[86:89], v[194:197], v[142:145]
	v_mfma_f32_16x16x32_bf16 v[134:137], v[102:105], v[194:197], v[134:137]
	v_mfma_f32_16x16x32_bf16 v[134:137], v[98:101], v[190:193], v[134:137]
	v_mfma_f32_16x16x32_bf16 v[118:121], v[98:101], v[198:201], v[118:121]
	v_mfma_f32_16x16x32_bf16 v[118:121], v[102:105], v[202:205], v[118:121]
	v_mfma_f32_16x16x32_bf16 v[126:129], v[86:89], v[202:205], v[126:129]
	v_mfma_f32_16x16x32_bf16 v[126:129], v[82:85], v[198:201], v[126:129]
	v_mfma_f32_16x16x32_bf16 v[110:113], v[82:85], v[206:209], v[110:113]
	v_mfma_f32_16x16x32_bf16 v[110:113], v[86:89], v[210:213], v[110:113]
	v_mfma_f32_16x16x32_bf16 v[94:97], v[102:105], v[210:213], v[94:97]
	v_mfma_f32_16x16x32_bf16 v[94:97], v[98:101], v[206:209], v[94:97]
	v_mfma_f32_16x16x32_bf16 v[70:73], v[98:101], v[214:217], v[70:73]
	v_mfma_f32_16x16x32_bf16 v[70:73], v[102:105], v[218:221], v[70:73]
	v_mfma_f32_16x16x32_bf16 v[78:81], v[86:89], v[218:221], v[78:81]
	v_mfma_f32_16x16x32_bf16 v[78:81], v[82:85], v[214:217], v[78:81]
	v_mfma_f32_16x16x32_bf16 v[138:141], v[150:153], v[190:193], v[138:141]
	v_mfma_f32_16x16x32_bf16 v[138:141], v[154:157], v[194:197], v[138:141]
	v_mfma_f32_16x16x32_bf16 v[130:133], v[186:189], v[194:197], v[130:133]
	v_mfma_f32_16x16x32_bf16 v[130:133], v[182:185], v[190:193], v[130:133]
	v_mfma_f32_16x16x32_bf16 v[114:117], v[182:185], v[198:201], v[114:117]
	v_mfma_f32_16x16x32_bf16 v[114:117], v[186:189], v[202:205], v[114:117]
	v_mfma_f32_16x16x32_bf16 v[122:125], v[154:157], v[202:205], v[122:125]
	v_mfma_f32_16x16x32_bf16 v[122:125], v[150:153], v[198:201], v[122:125]
	v_mfma_f32_16x16x32_bf16 v[106:109], v[150:153], v[206:209], v[106:109]
	v_mfma_f32_16x16x32_bf16 v[106:109], v[154:157], v[210:213], v[106:109]
	v_mfma_f32_16x16x32_bf16 v[90:93], v[186:189], v[210:213], v[90:93]
	v_mfma_f32_16x16x32_bf16 v[90:93], v[182:185], v[206:209], v[90:93]
	v_mfma_f32_16x16x32_bf16 v[66:69], v[182:185], v[214:217], v[66:69]
	v_mfma_f32_16x16x32_bf16 v[66:69], v[186:189], v[218:221], v[66:69]
	v_mfma_f32_16x16x32_bf16 v[74:77], v[154:157], v[218:221], v[74:77]
	v_mfma_f32_16x16x32_bf16 v[74:77], v[150:153], v[214:217], v[74:77]
	s_barrier
	s_setprio 0
	s_mov_b32 m0, s16
	s_mov_b32 s42, s78
	s_mov_b32 s43, s79
	ds_read_b128 v[190:193], v173 offset:16384
	ds_read_b128 v[194:197], v173 offset:17408
	ds_read_b128 v[198:201], v173 offset:18432
	ds_read_b128 v[202:205], v173 offset:19456
	ds_read_b128 v[206:209], v173 offset:20480
	ds_read_b128 v[210:213], v173 offset:21504
	ds_read_b128 v[214:217], v173 offset:22528
	ds_read_b128 v[218:221], v173 offset:23552
	buffer_load_dwordx4 v161, s[40:43], s65 offen lds
	s_mov_b32 m0, s17
	s_add_i32 s67, s65, 0x80000
	buffer_load_dwordx4 v165, s[40:43], s65 offen lds
	s_mov_b32 m0, s18
	s_nop 0
	buffer_load_dwordx4 v161, s[40:43], s67 offen lds
	s_mov_b32 m0, s19
	s_nop 0
	buffer_load_dwordx4 v165, s[40:43], s67 offen lds
	s_mov_b32 m0, s15
	s_nop 0
	buffer_load_dwordx4 v159, s[76:79], s66 offen lds
	s_mov_b32 m0, s20
	s_nop 0
	buffer_load_dwordx4 v163, s[76:79], s66 offen lds
	s_waitcnt vmcnt(8)
	s_waitcnt lgkmcnt(0)
	s_setprio 1
	s_barrier
	v_mfma_f32_16x16x32_bf16 v[62:65], v[82:85], v[190:193], v[62:65]
	v_mfma_f32_16x16x32_bf16 v[62:65], v[86:89], v[194:197], v[62:65]
	v_mfma_f32_16x16x32_bf16 v[54:57], v[102:105], v[194:197], v[54:57]
	v_mfma_f32_16x16x32_bf16 v[54:57], v[98:101], v[190:193], v[54:57]
	v_mfma_f32_16x16x32_bf16 v[38:41], v[98:101], v[198:201], v[38:41]
	v_mfma_f32_16x16x32_bf16 v[38:41], v[102:105], v[202:205], v[38:41]
	v_mfma_f32_16x16x32_bf16 v[46:49], v[86:89], v[202:205], v[46:49]
	v_mfma_f32_16x16x32_bf16 v[46:49], v[82:85], v[198:201], v[46:49]
	v_mfma_f32_16x16x32_bf16 v[30:33], v[82:85], v[206:209], v[30:33]
	v_mfma_f32_16x16x32_bf16 v[30:33], v[86:89], v[210:213], v[30:33]
	v_mfma_f32_16x16x32_bf16 v[22:25], v[102:105], v[210:213], v[22:25]
	v_mfma_f32_16x16x32_bf16 v[22:25], v[98:101], v[206:209], v[22:25]
	v_mfma_f32_16x16x32_bf16 v[6:9], v[98:101], v[214:217], v[6:9]
	v_mfma_f32_16x16x32_bf16 v[6:9], v[102:105], v[218:221], v[6:9]
	v_mfma_f32_16x16x32_bf16 v[14:17], v[86:89], v[218:221], v[14:17]
	v_mfma_f32_16x16x32_bf16 v[14:17], v[82:85], v[214:217], v[14:17]
	v_mfma_f32_16x16x32_bf16 v[58:61], v[150:153], v[190:193], v[58:61]
	v_mfma_f32_16x16x32_bf16 v[58:61], v[154:157], v[194:197], v[58:61]
	v_mfma_f32_16x16x32_bf16 v[50:53], v[186:189], v[194:197], v[50:53]
	v_mfma_f32_16x16x32_bf16 v[50:53], v[182:185], v[190:193], v[50:53]
	v_mfma_f32_16x16x32_bf16 v[34:37], v[182:185], v[198:201], v[34:37]
	v_mfma_f32_16x16x32_bf16 v[34:37], v[186:189], v[202:205], v[34:37]
	v_mfma_f32_16x16x32_bf16 v[42:45], v[154:157], v[202:205], v[42:45]
	v_mfma_f32_16x16x32_bf16 v[42:45], v[150:153], v[198:201], v[42:45]
	v_mfma_f32_16x16x32_bf16 v[26:29], v[150:153], v[206:209], v[26:29]
	v_mfma_f32_16x16x32_bf16 v[26:29], v[154:157], v[210:213], v[26:29]
	v_mfma_f32_16x16x32_bf16 v[18:21], v[186:189], v[210:213], v[18:21]
	v_mfma_f32_16x16x32_bf16 v[18:21], v[182:185], v[206:209], v[18:21]
	v_mfma_f32_16x16x32_bf16 v[2:5], v[182:185], v[214:217], v[2:5]
	v_mfma_f32_16x16x32_bf16 v[2:5], v[186:189], v[218:221], v[2:5]
	v_mfma_f32_16x16x32_bf16 v[10:13], v[154:157], v[218:221], v[10:13]
	v_mfma_f32_16x16x32_bf16 v[10:13], v[150:153], v[214:217], v[10:13]
	s_barrier
; #define PG8_STAGEX(rs, bufoff, soff, voff) do { _Pragma("unroll") for (int _i = 0; _i < 2; ++_i) \
;         __builtin_amdgcn_raw_ptr_buffer_load_lds(rs, (LAS unsigned*)(lds + (bufoff) + ldsw + _i * 8192), 16, (voff)[_i], (soff), 0, 0); } while (0)
; #define PG8_LDA(dst, b, h) do { _Pragma("unroll") for (int m = 0; m < 4; ++m) _Pragma("unroll") for (int k = 0; k < 2; ++k) dst[m][k] = *(const LAS bf16x8*)(lds + PG8_SA(b, h) + aoff + m * 2048 + k * 1024); } while (0)
; #define PG8_LDB(dst, b, h) do { _Pragma("unroll") for (int n = 0; n < 2; ++n) _Pragma("unroll") for (int k = 0; k < 2; ++k) dst[n][k] = *(const LAS bf16x8*)(lds + PG8_SB(b, h) + boff + n * 2048 + k * 1024); } while (0)
; #define PG8_WAIT_V(n) asm volatile("s_waitcnt vmcnt(" #n ")" ::: "memory")
; #define PG8_WAIT_L(n) asm volatile("s_waitcnt lgkmcnt(" #n ")" ::: "memory")
; #define PG8_BAR __builtin_amdgcn_s_barrier()
; #define PG8_SCHED __builtin_amdgcn_sched_barrier(0)
;     ...
;             PG8_LDB(B0, 1, 0); PG8_LDB(B1, 1, 1); PG8_SCHED; PG8_LDA(At, 1, 0); PG8_STAGEX(rsA, PG8_SA(0, 1), a2 + hstepA, voffA);
;             PG8_WAIT_V(8); PG8_WAIT_L(0); PG8_BAR; PG8_MMA(0, 0, At, B0); PG8_MMA(0, 1, At, B1); PG8_BAR; PG8_SCHED;
;             PG8_LDA(At, 1, 1); PG8_STAGEX(rsB, PG8_SB(1, 0), b3, voffB); PG8_STAGEX(rsB, PG8_SB(1, 1), b3 + hstepB, voffB); PG8_STAGEX(rsA, PG8_SA(1, 0), a3, voffA);
;             PG8_WAIT_V(8); PG8_WAIT_L(0); PG8_BAR; PG8_MMA(1, 0, At, B0); PG8_MMA(1, 1, At, B1); PG8_BAR; PG8_SCHED;
;     ...
;         }
;         if (wr == 0) PG8_BAR;
	s_setprio 0
	v_add_u32_e32 v102, 0x18000, v172
	v_add_u32_e32 v146, 0x1c000, v172
	ds_read_b128 v[82:85], v102
	ds_read_b128 v[86:89], v102 offset:1024
	ds_read_b128 v[98:101], v102 offset:2048
	ds_read_b128 v[102:105], v102 offset:3072
	ds_read_b128 v[150:153], v146
	ds_read_b128 v[154:157], v146 offset:1024
	ds_read_b128 v[182:185], v146 offset:2048
	ds_read_b128 v[186:189], v146 offset:3072
	s_add_i32 s66, s66, 0x80000
	s_mov_b32 m0, s21
	ds_read_b128 v[190:193], v173 offset:32768
	ds_read_b128 v[194:197], v173 offset:33792
	ds_read_b128 v[198:201], v173 offset:34816
	ds_read_b128 v[202:205], v173 offset:35840
	ds_read_b128 v[206:209], v173 offset:36864
	ds_read_b128 v[210:213], v173 offset:37888
	ds_read_b128 v[214:217], v173 offset:38912
	ds_read_b128 v[218:221], v173 offset:39936
	buffer_load_dwordx4 v159, s[76:79], s66 offen lds
	s_mov_b32 m0, s22
	s_nop 0
	buffer_load_dwordx4 v163, s[76:79], s66 offen lds
	s_waitcnt vmcnt(8)
	s_waitcnt lgkmcnt(0)
	s_setprio 1
	s_barrier
	v_mfma_f32_16x16x32_bf16 v[142:145], v[82:85], v[190:193], v[142:145]
	v_mfma_f32_16x16x32_bf16 v[142:145], v[86:89], v[194:197], v[142:145]
	v_mfma_f32_16x16x32_bf16 v[134:137], v[102:105], v[194:197], v[134:137]
	v_mfma_f32_16x16x32_bf16 v[134:137], v[98:101], v[190:193], v[134:137]
	v_mfma_f32_16x16x32_bf16 v[118:121], v[98:101], v[198:201], v[118:121]
	v_mfma_f32_16x16x32_bf16 v[118:121], v[102:105], v[202:205], v[118:121]
	v_mfma_f32_16x16x32_bf16 v[126:129], v[86:89], v[202:205], v[126:129]
	v_mfma_f32_16x16x32_bf16 v[126:129], v[82:85], v[198:201], v[126:129]
	v_mfma_f32_16x16x32_bf16 v[110:113], v[82:85], v[206:209], v[110:113]
	v_mfma_f32_16x16x32_bf16 v[110:113], v[86:89], v[210:213], v[110:113]
	v_mfma_f32_16x16x32_bf16 v[94:97], v[102:105], v[210:213], v[94:97]
	v_mfma_f32_16x16x32_bf16 v[94:97], v[98:101], v[206:209], v[94:97]
	v_mfma_f32_16x16x32_bf16 v[70:73], v[98:101], v[214:217], v[70:73]
	v_mfma_f32_16x16x32_bf16 v[70:73], v[102:105], v[218:221], v[70:73]
	v_mfma_f32_16x16x32_bf16 v[78:81], v[86:89], v[218:221], v[78:81]
	v_mfma_f32_16x16x32_bf16 v[78:81], v[82:85], v[214:217], v[78:81]
	v_mfma_f32_16x16x32_bf16 v[138:141], v[150:153], v[190:193], v[138:141]
	v_mfma_f32_16x16x32_bf16 v[138:141], v[154:157], v[194:197], v[138:141]
	v_mfma_f32_16x16x32_bf16 v[130:133], v[186:189], v[194:197], v[130:133]
	v_mfma_f32_16x16x32_bf16 v[130:133], v[182:185], v[190:193], v[130:133]
	v_mfma_f32_16x16x32_bf16 v[114:117], v[182:185], v[198:201], v[114:117]
	v_mfma_f32_16x16x32_bf16 v[114:117], v[186:189], v[202:205], v[114:117]
	v_mfma_f32_16x16x32_bf16 v[122:125], v[154:157], v[202:205], v[122:125]
	v_mfma_f32_16x16x32_bf16 v[122:125], v[150:153], v[198:201], v[122:125]
	v_mfma_f32_16x16x32_bf16 v[106:109], v[150:153], v[206:209], v[106:109]
	v_mfma_f32_16x16x32_bf16 v[106:109], v[154:157], v[210:213], v[106:109]
	v_mfma_f32_16x16x32_bf16 v[90:93], v[186:189], v[210:213], v[90:93]
	v_mfma_f32_16x16x32_bf16 v[90:93], v[182:185], v[206:209], v[90:93]
	v_mfma_f32_16x16x32_bf16 v[66:69], v[182:185], v[214:217], v[66:69]
	v_mfma_f32_16x16x32_bf16 v[66:69], v[186:189], v[218:221], v[66:69]
	v_mfma_f32_16x16x32_bf16 v[74:77], v[154:157], v[218:221], v[74:77]
	v_mfma_f32_16x16x32_bf16 v[74:77], v[150:153], v[214:217], v[74:77]
	s_barrier
	s_setprio 0
	s_mov_b32 m0, s23
	s_or_b32 s66, s65, 0x80
	ds_read_b128 v[190:193], v173 offset:49152
	ds_read_b128 v[194:197], v173 offset:50176
	ds_read_b128 v[198:201], v173 offset:51200
	ds_read_b128 v[202:205], v173 offset:52224
	ds_read_b128 v[206:209], v173 offset:53248
	ds_read_b128 v[210:213], v173 offset:54272
	ds_read_b128 v[214:217], v173 offset:55296
	ds_read_b128 v[218:221], v173 offset:56320
	buffer_load_dwordx4 v161, s[40:43], s66 offen lds
	s_mov_b32 m0, s24
	s_add_i32 s65, s65, 0x80080
	buffer_load_dwordx4 v165, s[40:43], s66 offen lds
	s_mov_b32 m0, s27
	s_nop 0
	buffer_load_dwordx4 v161, s[40:43], s65 offen lds
	s_mov_b32 m0, s28
	s_nop 0
	buffer_load_dwordx4 v165, s[40:43], s65 offen lds
	s_mov_b32 m0, s25
	s_nop 0
	buffer_load_dwordx4 v159, s[76:79], s64 offen lds
	s_mov_b32 m0, s26
	s_nop 0
	buffer_load_dwordx4 v163, s[76:79], s64 offen lds
	s_waitcnt vmcnt(8)
	s_waitcnt lgkmcnt(0)
	s_setprio 1
	s_barrier
	v_mfma_f32_16x16x32_bf16 v[62:65], v[82:85], v[190:193], v[62:65]
	v_mfma_f32_16x16x32_bf16 v[62:65], v[86:89], v[194:197], v[62:65]
	v_mfma_f32_16x16x32_bf16 v[54:57], v[102:105], v[194:197], v[54:57]
	v_mfma_f32_16x16x32_bf16 v[54:57], v[98:101], v[190:193], v[54:57]
	v_mfma_f32_16x16x32_bf16 v[38:41], v[98:101], v[198:201], v[38:41]
	v_mfma_f32_16x16x32_bf16 v[38:41], v[102:105], v[202:205], v[38:41]
	v_mfma_f32_16x16x32_bf16 v[46:49], v[86:89], v[202:205], v[46:49]
	v_mfma_f32_16x16x32_bf16 v[46:49], v[82:85], v[198:201], v[46:49]
	v_mfma_f32_16x16x32_bf16 v[30:33], v[82:85], v[206:209], v[30:33]
	v_mfma_f32_16x16x32_bf16 v[30:33], v[86:89], v[210:213], v[30:33]
	v_mfma_f32_16x16x32_bf16 v[22:25], v[102:105], v[210:213], v[22:25]
	v_mfma_f32_16x16x32_bf16 v[22:25], v[98:101], v[206:209], v[22:25]
	v_mfma_f32_16x16x32_bf16 v[6:9], v[98:101], v[214:217], v[6:9]
	v_mfma_f32_16x16x32_bf16 v[6:9], v[102:105], v[218:221], v[6:9]
	v_mfma_f32_16x16x32_bf16 v[14:17], v[86:89], v[218:221], v[14:17]
	v_mfma_f32_16x16x32_bf16 v[14:17], v[82:85], v[214:217], v[14:17]
	v_mfma_f32_16x16x32_bf16 v[58:61], v[150:153], v[190:193], v[58:61]
	v_mfma_f32_16x16x32_bf16 v[58:61], v[154:157], v[194:197], v[58:61]
	v_mfma_f32_16x16x32_bf16 v[50:53], v[186:189], v[194:197], v[50:53]
	v_mfma_f32_16x16x32_bf16 v[50:53], v[182:185], v[190:193], v[50:53]
	v_mfma_f32_16x16x32_bf16 v[34:37], v[182:185], v[198:201], v[34:37]
	v_mfma_f32_16x16x32_bf16 v[34:37], v[186:189], v[202:205], v[34:37]
	v_mfma_f32_16x16x32_bf16 v[42:45], v[154:157], v[202:205], v[42:45]
	v_mfma_f32_16x16x32_bf16 v[42:45], v[150:153], v[198:201], v[42:45]
	v_mfma_f32_16x16x32_bf16 v[26:29], v[150:153], v[206:209], v[26:29]
	v_mfma_f32_16x16x32_bf16 v[26:29], v[154:157], v[210:213], v[26:29]
	v_mfma_f32_16x16x32_bf16 v[18:21], v[186:189], v[210:213], v[18:21]
	v_mfma_f32_16x16x32_bf16 v[18:21], v[182:185], v[206:209], v[18:21]
	v_mfma_f32_16x16x32_bf16 v[2:5], v[182:185], v[214:217], v[2:5]
	v_mfma_f32_16x16x32_bf16 v[2:5], v[186:189], v[218:221], v[2:5]
	v_mfma_f32_16x16x32_bf16 v[10:13], v[154:157], v[218:221], v[10:13]
	v_mfma_f32_16x16x32_bf16 v[10:13], v[150:153], v[214:217], v[10:13]
	s_barrier
	s_setprio 0
	s_add_i32 s63, s63, 2
	s_addk_i32 s61, 0x100
	s_addk_i32 s62, 0x100
	s_cmp_gt_u32 s63, 29
	s_cbranch_scc0 .LBB0_1651
	s_and_b64 vcc, exec, s[48:49]
	s_cbranch_vccz .LBB0_1654
	s_barrier

; #define PG8_STAGEX(rs, bufoff, soff, voff) do { _Pragma("unroll") for (int _i = 0; _i < 2; ++_i) \
;         __builtin_amdgcn_raw_ptr_buffer_load_lds(rs, (LAS unsigned*)(lds + (bufoff) + ldsw + _i * 8192), 16, (voff)[_i], (soff), 0, 0); } while (0)
; #define PG8_LDA(dst, b, h) do { _Pragma("unroll") for (int m = 0; m < 4; ++m) _Pragma("unroll") for (int k = 0; k < 2; ++k) dst[m][k] = *(const LAS bf16x8*)(lds + PG8_SA(b, h) + aoff + m * 2048 + k * 1024); } while (0)
; #define PG8_LDB(dst, b, h) do { _Pragma("unroll") for (int n = 0; n < 2; ++n) _Pragma("unroll") for (int k = 0; k < 2; ++k) dst[n][k] = *(const LAS bf16x8*)(lds + PG8_SB(b, h) + boff + n * 2048 + k * 1024); } while (0)
; #define PG8_WAIT_V(n) asm volatile("s_waitcnt vmcnt(" #n ")" ::: "memory")
; #define PG8_WAIT_L(n) asm volatile("s_waitcnt lgkmcnt(" #n ")" ::: "memory")
; #define PG8_BAR __builtin_amdgcn_s_barrier()
; #define PG8_SCHED __builtin_amdgcn_sched_barrier(0)
;     ...
;                 if (w0) { PG8_LDB(B0, 0, 0); PG8_LDB(B1, 0, 1); PG8_SCHED; PG8_LDA(At, 0, 0); }
;                 PG8_WAIT_L(0); PG8_BAR; if (w0) { PG8_MMA(0, 0, At, B0); PG8_MMA(0, 1, At, B1); } PG8_BAR; PG8_SCHED;
;                 PG8_STAGEX(rsB, PG8_SB(0, 0), b2, voffB); PG8_STAGEX(rsB, PG8_SB(0, 1), b2 + hstepB, voffB); PG8_STAGEX(rsA, PG8_SA(0, 0), a2, voffA);
;                 PG8_WAIT_V(6); PG8_BAR; PG8_BAR; PG8_SCHED;
.LBB0_1668:
	v_add_u32_e32 v86, 0x10000, v72
	v_add_u32_e32 v102, 0x14000, v72
	ds_read_b128 v[74:77], v86
	ds_read_b128 v[78:81], v86 offset:1024
	ds_read_b128 v[82:85], v86 offset:2048
	ds_read_b128 v[86:89], v86 offset:3072
	ds_read_b128 v[90:93], v102
	ds_read_b128 v[94:97], v102 offset:1024
	ds_read_b128 v[98:101], v102 offset:2048
	ds_read_b128 v[102:105], v102 offset:3072
	s_cmp_lg_u32 s27, 28
	s_cselect_b32 s28, s26, 0
	s_add_i32 s29, s28, s17
	s_or_b32 s30, s29, 0x80
	s_add_i32 s28, s28, s10
	ds_read_b128 v[106:109], v73
	ds_read_b128 v[110:113], v73 offset:1024
	ds_read_b128 v[114:117], v73 offset:2048
	ds_read_b128 v[118:121], v73 offset:3072
	ds_read_b128 v[122:125], v73 offset:4096
	ds_read_b128 v[126:129], v73 offset:5120
	ds_read_b128 v[130:133], v73 offset:6144
	ds_read_b128 v[134:137], v73 offset:7168
	s_waitcnt lgkmcnt(0)
	s_setprio 1
	s_barrier
	v_mfma_f32_16x16x32_bf16 v[62:65], v[74:77], v[106:109], v[62:65]
	v_mfma_f32_16x16x32_bf16 v[62:65], v[78:81], v[110:113], v[62:65]
	v_mfma_f32_16x16x32_bf16 v[58:61], v[86:89], v[110:113], v[58:61]
	v_mfma_f32_16x16x32_bf16 v[58:61], v[82:85], v[106:109], v[58:61]
	v_mfma_f32_16x16x32_bf16 v[38:41], v[82:85], v[114:117], v[38:41]
	v_mfma_f32_16x16x32_bf16 v[38:41], v[86:89], v[118:121], v[38:41]
	v_mfma_f32_16x16x32_bf16 v[54:57], v[78:81], v[118:121], v[54:57]
	v_mfma_f32_16x16x32_bf16 v[54:57], v[74:77], v[114:117], v[54:57]
	v_mfma_f32_16x16x32_bf16 v[30:33], v[74:77], v[122:125], v[30:33]
	v_mfma_f32_16x16x32_bf16 v[30:33], v[78:81], v[126:129], v[30:33]
	v_mfma_f32_16x16x32_bf16 v[22:25], v[86:89], v[126:129], v[22:25]
	v_mfma_f32_16x16x32_bf16 v[22:25], v[82:85], v[122:125], v[22:25]
	v_mfma_f32_16x16x32_bf16 v[6:9], v[82:85], v[130:133], v[6:9]
	v_mfma_f32_16x16x32_bf16 v[6:9], v[86:89], v[134:137], v[6:9]
	v_mfma_f32_16x16x32_bf16 v[14:17], v[78:81], v[134:137], v[14:17]
	v_mfma_f32_16x16x32_bf16 v[14:17], v[74:77], v[130:133], v[14:17]
	v_mfma_f32_16x16x32_bf16 v[50:53], v[90:93], v[106:109], v[50:53]
	v_mfma_f32_16x16x32_bf16 v[50:53], v[94:97], v[110:113], v[50:53]
	v_mfma_f32_16x16x32_bf16 v[46:49], v[102:105], v[110:113], v[46:49]
	v_mfma_f32_16x16x32_bf16 v[46:49], v[98:101], v[106:109], v[46:49]
	v_mfma_f32_16x16x32_bf16 v[34:37], v[98:101], v[114:117], v[34:37]
	v_mfma_f32_16x16x32_bf16 v[34:37], v[102:105], v[118:121], v[34:37]
	v_mfma_f32_16x16x32_bf16 v[42:45], v[94:97], v[118:121], v[42:45]
	v_mfma_f32_16x16x32_bf16 v[42:45], v[90:93], v[114:117], v[42:45]
	v_mfma_f32_16x16x32_bf16 v[26:29], v[90:93], v[122:125], v[26:29]
	v_mfma_f32_16x16x32_bf16 v[26:29], v[94:97], v[126:129], v[26:29]
	v_mfma_f32_16x16x32_bf16 v[18:21], v[102:105], v[126:129], v[18:21]
	v_mfma_f32_16x16x32_bf16 v[18:21], v[98:101], v[122:125], v[18:21]
	v_mfma_f32_16x16x32_bf16 v[2:5], v[98:101], v[130:133], v[2:5]
	v_mfma_f32_16x16x32_bf16 v[2:5], v[102:105], v[134:137], v[2:5]
	v_mfma_f32_16x16x32_bf16 v[10:13], v[94:97], v[134:137], v[10:13]
	v_mfma_f32_16x16x32_bf16 v[10:13], v[90:93], v[130:133], v[10:13]
	s_barrier
	s_setprio 0
	s_mov_b32 m0, s13
	s_mov_b32 s42, s78
	s_mov_b32 s43, s79
	buffer_load_dwordx4 v67, s[40:43], s28 offen lds
	s_mov_b32 m0, s14
	s_add_i32 s31, s28, 0x80000
	buffer_load_dwordx4 v69, s[40:43], s28 offen lds
	s_mov_b32 m0, s15
	s_nop 0
	buffer_load_dwordx4 v67, s[40:43], s31 offen lds
	s_mov_b32 m0, s16
	s_nop 0
	buffer_load_dwordx4 v69, s[40:43], s31 offen lds
	s_mov_b32 m0, s12
	s_nop 0
	buffer_load_dwordx4 v66, s[76:79], s29 offen lds
	s_mov_b32 m0, s18
	s_nop 0
	buffer_load_dwordx4 v68, s[76:79], s29 offen lds
	s_waitcnt vmcnt(6)
	s_barrier
	s_barrier
; #define PG8_STAGEX(rs, bufoff, soff, voff) do { _Pragma("unroll") for (int _i = 0; _i < 2; ++_i) \
;         __builtin_amdgcn_raw_ptr_buffer_load_lds(rs, (LAS unsigned*)(lds + (bufoff) + ldsw + _i * 8192), 16, (voff)[_i], (soff), 0, 0); } while (0)
; #define PG8_LDA(dst, b, h) do { _Pragma("unroll") for (int m = 0; m < 4; ++m) _Pragma("unroll") for (int k = 0; k < 2; ++k) dst[m][k] = *(const LAS bf16x8*)(lds + PG8_SA(b, h) + aoff + m * 2048 + k * 1024); } while (0)
; #define PG8_LDB(dst, b, h) do { _Pragma("unroll") for (int n = 0; n < 2; ++n) _Pragma("unroll") for (int k = 0; k < 2; ++k) dst[n][k] = *(const LAS bf16x8*)(lds + PG8_SB(b, h) + boff + n * 2048 + k * 1024); } while (0)
; #define PG8_WAIT_V(n) asm volatile("s_waitcnt vmcnt(" #n ")" ::: "memory")
; #define PG8_WAIT_L(n) asm volatile("s_waitcnt lgkmcnt(" #n ")" ::: "memory")
; #define PG8_BAR __builtin_amdgcn_s_barrier()
; #define PG8_SCHED __builtin_amdgcn_sched_barrier(0)
;     ...
;                 if (w0) { PG8_LDB(B0, 1, 0); PG8_LDB(B1, 1, 1); PG8_SCHED; PG8_LDA(At, 1, 0); }
;                 PG8_WAIT_L(0); PG8_BAR; if (w0) { PG8_MMA(0, 0, At, B0); PG8_MMA(0, 1, At, B1); } PG8_BAR; PG8_SCHED;
;                 PG8_STAGEX(rsB, PG8_SB(1, 0), b3, voffB); PG8_STAGEX(rsB, PG8_SB(1, 1), b3 + hstepB, voffB); PG8_STAGEX(rsA, PG8_SA(1, 0), a3, voffA);
;                 PG8_WAIT_V(6); PG8_BAR; PG8_BAR; PG8_SCHED;
	v_add_u32_e32 v86, 0x18000, v72
	v_add_u32_e32 v102, 0x1c000, v72
	ds_read_b128 v[74:77], v86
	ds_read_b128 v[78:81], v86 offset:1024
	ds_read_b128 v[82:85], v86 offset:2048
	ds_read_b128 v[86:89], v86 offset:3072
	ds_read_b128 v[90:93], v102
	ds_read_b128 v[94:97], v102 offset:1024
	ds_read_b128 v[98:101], v102 offset:2048
	ds_read_b128 v[102:105], v102 offset:3072
	ds_read_b128 v[106:109], v73 offset:32768
	ds_read_b128 v[110:113], v73 offset:33792
	ds_read_b128 v[114:117], v73 offset:34816
	ds_read_b128 v[118:121], v73 offset:35840
	ds_read_b128 v[122:125], v73 offset:36864
	ds_read_b128 v[126:129], v73 offset:37888
	ds_read_b128 v[130:133], v73 offset:38912
	ds_read_b128 v[134:137], v73 offset:39936
	s_waitcnt lgkmcnt(0)
	s_setprio 1
	s_barrier
	v_mfma_f32_16x16x32_bf16 v[62:65], v[74:77], v[106:109], v[62:65]
	v_mfma_f32_16x16x32_bf16 v[58:61], v[82:85], v[106:109], v[58:61]
	v_mfma_f32_16x16x32_bf16 v[54:57], v[74:77], v[114:117], v[54:57]
	v_mfma_f32_16x16x32_bf16 v[38:41], v[82:85], v[114:117], v[38:41]
	v_mfma_f32_16x16x32_bf16 v[30:33], v[74:77], v[122:125], v[30:33]
	v_mfma_f32_16x16x32_bf16 v[22:25], v[82:85], v[122:125], v[22:25]
	v_mfma_f32_16x16x32_bf16 v[14:17], v[74:77], v[130:133], v[14:17]
	v_mfma_f32_16x16x32_bf16 v[6:9], v[82:85], v[130:133], v[6:9]
	v_mfma_f32_16x16x32_bf16 v[62:65], v[78:81], v[110:113], v[62:65]
	v_mfma_f32_16x16x32_bf16 v[58:61], v[86:89], v[110:113], v[58:61]
	v_mfma_f32_16x16x32_bf16 v[54:57], v[78:81], v[118:121], v[54:57]
	v_mfma_f32_16x16x32_bf16 v[38:41], v[86:89], v[118:121], v[38:41]
	v_mfma_f32_16x16x32_bf16 v[30:33], v[78:81], v[126:129], v[30:33]
	v_mfma_f32_16x16x32_bf16 v[22:25], v[86:89], v[126:129], v[22:25]
	v_mfma_f32_16x16x32_bf16 v[14:17], v[78:81], v[134:137], v[14:17]
	v_mfma_f32_16x16x32_bf16 v[6:9], v[86:89], v[134:137], v[6:9]
	v_mfma_f32_16x16x32_bf16 v[50:53], v[90:93], v[106:109], v[50:53]
	s_or_b32 s29, s28, 0x80
	v_mfma_f32_16x16x32_bf16 v[46:49], v[98:101], v[106:109], v[46:49]
	v_mfma_f32_16x16x32_bf16 v[42:45], v[90:93], v[114:117], v[42:45]
	v_mfma_f32_16x16x32_bf16 v[34:37], v[98:101], v[114:117], v[34:37]
	v_mfma_f32_16x16x32_bf16 v[26:29], v[90:93], v[122:125], v[26:29]
	v_mfma_f32_16x16x32_bf16 v[18:21], v[98:101], v[122:125], v[18:21]
	v_mfma_f32_16x16x32_bf16 v[10:13], v[90:93], v[130:133], v[10:13]
	v_mfma_f32_16x16x32_bf16 v[2:5], v[98:101], v[130:133], v[2:5]
	v_mfma_f32_16x16x32_bf16 v[50:53], v[94:97], v[110:113], v[50:53]
	v_mfma_f32_16x16x32_bf16 v[46:49], v[102:105], v[110:113], v[46:49]
	v_mfma_f32_16x16x32_bf16 v[42:45], v[94:97], v[118:121], v[42:45]
	v_mfma_f32_16x16x32_bf16 v[34:37], v[102:105], v[118:121], v[34:37]
	v_mfma_f32_16x16x32_bf16 v[26:29], v[94:97], v[126:129], v[26:29]
	v_mfma_f32_16x16x32_bf16 v[18:21], v[102:105], v[126:129], v[18:21]
	v_mfma_f32_16x16x32_bf16 v[10:13], v[94:97], v[134:137], v[10:13]
	v_mfma_f32_16x16x32_bf16 v[2:5], v[102:105], v[134:137], v[2:5]
	s_barrier
	s_setprio 0
	s_mov_b32 m0, s20
	s_add_i32 s28, s28, 0x80080
	buffer_load_dwordx4 v67, s[40:43], s29 offen lds
	s_mov_b32 m0, s21
	s_nop 0
	buffer_load_dwordx4 v69, s[40:43], s29 offen lds
	s_mov_b32 m0, s24
	s_nop 0
	buffer_load_dwordx4 v67, s[40:43], s28 offen lds
	s_mov_b32 m0, s25
	s_nop 0
	buffer_load_dwordx4 v69, s[40:43], s28 offen lds
	s_mov_b32 m0, s22
	s_nop 0
	buffer_load_dwordx4 v66, s[76:79], s30 offen lds
	s_mov_b32 m0, s23
	s_nop 0
	buffer_load_dwordx4 v68, s[76:79], s30 offen lds
	s_waitcnt vmcnt(6)
	s_barrier
	s_barrier
	s_addk_i32 s26, 0x100
	s_add_i32 s27, s27, 2
	s_cmp_gt_u32 s27, 29
	s_cbranch_scc0 .LBB0_1668
	s_cmpk_lt_u32 s11, 0x100
	s_cbranch_scc0 .LBB0_1671
	s_barrier

; #define PG8_STAGEX(rs, bufoff, soff, voff) do { _Pragma("unroll") for (int _i = 0; _i < 2; ++_i) \
;         __builtin_amdgcn_raw_ptr_buffer_load_lds(rs, (LAS unsigned*)(lds + (bufoff) + ldsw + _i * 8192), 16, (voff)[_i], (soff), 0, 0); } while (0)
; #define PG8_LDA(dst, b, h) do { _Pragma("unroll") for (int m = 0; m < 4; ++m) _Pragma("unroll") for (int k = 0; k < 2; ++k) dst[m][k] = *(const LAS bf16x8*)(lds + PG8_SA(b, h) + aoff + m * 2048 + k * 1024); } while (0)
; #define PG8_LDB(dst, b, h) do { _Pragma("unroll") for (int n = 0; n < 2; ++n) _Pragma("unroll") for (int k = 0; k < 2; ++k) dst[n][k] = *(const LAS bf16x8*)(lds + PG8_SB(b, h) + boff + n * 2048 + k * 1024); } while (0)
; #define PG8_WAIT_V(n) asm volatile("s_waitcnt vmcnt(" #n ")" ::: "memory")
; #define PG8_WAIT_L(n) asm volatile("s_waitcnt lgkmcnt(" #n ")" ::: "memory")
; #define PG8_BAR __builtin_amdgcn_s_barrier()
; #define PG8_SCHED __builtin_amdgcn_sched_barrier(0)
;     ...
;             const unsigned a1 = cA + (unsigned)(t + 1) * kstep;
;             const unsigned a2 = last ? nA : cA + (unsigned)(t + 2) * kstep, b2 = last ? nB : cB + (unsigned)(t + 2) * kstep;
;             const unsigned a3 = a2 + kstep, b3 = b2 + kstep;
;             PG8_LDB(B0, 0, 0); PG8_LDB(B1, 0, 1); PG8_SCHED; PG8_LDA(At, 0, 0); PG8_STAGEX(rsA, PG8_SA(1, 1), a1 + hstepA, voffA);
;             PG8_WAIT_V(8); PG8_WAIT_L(0); PG8_BAR; PG8_MMA(0, 0, At, B0); PG8_MMA(0, 1, At, B1); PG8_BAR; PG8_SCHED;
;             PG8_LDA(At, 0, 1); PG8_STAGEX(rsB, PG8_SB(0, 0), b2, voffB); PG8_STAGEX(rsB, PG8_SB(0, 1), b2 + hstepB, voffB); PG8_STAGEX(rsA, PG8_SA(0, 0), a2, voffA);
;             PG8_WAIT_V(8); PG8_WAIT_L(0); PG8_BAR; PG8_MMA(1, 0, At, B0); PG8_MMA(1, 1, At, B1); PG8_BAR; PG8_SCHED;
.LBB0_1750:
	v_add_u32_e32 v70, 0x10000, v241
	ds_read_b128 v[134:137], v70
	ds_read_b128 v[138:141], v70 offset:1024
	ds_read_b128 v[142:145], v70 offset:2048
	ds_read_b128 v[146:149], v70 offset:3072
	v_add_u32_e32 v70, 0x14000, v241
	ds_read_b128 v[150:153], v70
	ds_read_b128 v[154:157], v70 offset:1024
	ds_read_b128 v[158:161], v70 offset:2048
	ds_read_b128 v[162:165], v70 offset:3072
	s_add_i32 s46, s40, 0xffea8080
	s_cmpk_eq_i32 s60, 0x52
	s_cselect_b32 s63, s30, s46
	s_cselect_b32 s62, s31, s41
	s_or_b32 s61, s63, 0x80
	s_mov_b32 m0, s72
	ds_read_b128 v[166:169], v242
	ds_read_b128 v[170:173], v242 offset:1024
	ds_read_b128 v[184:187], v242 offset:2048
	ds_read_b128 v[188:191], v242 offset:3072
	ds_read_b128 v[192:195], v242 offset:4096
	ds_read_b128 v[196:199], v242 offset:5120
	ds_read_b128 v[200:203], v242 offset:6144
	ds_read_b128 v[204:207], v242 offset:7168
	buffer_load_dwordx4 v178, s[76:79], s40 offen lds
	s_mov_b32 m0, s73
	s_nop 0
	buffer_load_dwordx4 v237, s[76:79], s40 offen lds
	s_waitcnt vmcnt(8)
	s_waitcnt lgkmcnt(0)
	s_setprio 1
	s_barrier
	v_mfma_f32_16x16x32_bf16 v[130:133], v[134:137], v[166:169], v[130:133]
	v_mfma_f32_16x16x32_bf16 v[130:133], v[138:141], v[170:173], v[130:133]
	v_mfma_f32_16x16x32_bf16 v[126:129], v[146:149], v[170:173], v[126:129]
	v_mfma_f32_16x16x32_bf16 v[126:129], v[142:145], v[166:169], v[126:129]
	v_mfma_f32_16x16x32_bf16 v[118:121], v[142:145], v[184:187], v[118:121]
	v_mfma_f32_16x16x32_bf16 v[118:121], v[146:149], v[188:191], v[118:121]
	v_mfma_f32_16x16x32_bf16 v[122:125], v[138:141], v[188:191], v[122:125]
	v_mfma_f32_16x16x32_bf16 v[122:125], v[134:137], v[184:187], v[122:125]
	v_mfma_f32_16x16x32_bf16 v[114:117], v[134:137], v[192:195], v[114:117]
	v_mfma_f32_16x16x32_bf16 v[114:117], v[138:141], v[196:199], v[114:117]
	v_mfma_f32_16x16x32_bf16 v[110:113], v[146:149], v[196:199], v[110:113]
	v_mfma_f32_16x16x32_bf16 v[110:113], v[142:145], v[192:195], v[110:113]
	v_mfma_f32_16x16x32_bf16 v[102:105], v[142:145], v[200:203], v[102:105]
	v_mfma_f32_16x16x32_bf16 v[102:105], v[146:149], v[204:207], v[102:105]
	v_mfma_f32_16x16x32_bf16 v[106:109], v[138:141], v[204:207], v[106:109]
	v_mfma_f32_16x16x32_bf16 v[106:109], v[134:137], v[200:203], v[106:109]
	v_mfma_f32_16x16x32_bf16 v[62:65], v[150:153], v[166:169], v[62:65]
	v_mfma_f32_16x16x32_bf16 v[62:65], v[154:157], v[170:173], v[62:65]
	v_mfma_f32_16x16x32_bf16 v[58:61], v[162:165], v[170:173], v[58:61]
	v_mfma_f32_16x16x32_bf16 v[58:61], v[158:161], v[166:169], v[58:61]
	v_mfma_f32_16x16x32_bf16 v[50:53], v[158:161], v[184:187], v[50:53]
	v_mfma_f32_16x16x32_bf16 v[50:53], v[162:165], v[188:191], v[50:53]
	v_mfma_f32_16x16x32_bf16 v[54:57], v[154:157], v[188:191], v[54:57]
	v_mfma_f32_16x16x32_bf16 v[54:57], v[150:153], v[184:187], v[54:57]
	v_mfma_f32_16x16x32_bf16 v[46:49], v[150:153], v[192:195], v[46:49]
	v_mfma_f32_16x16x32_bf16 v[46:49], v[154:157], v[196:199], v[46:49]
	v_mfma_f32_16x16x32_bf16 v[42:45], v[162:165], v[196:199], v[42:45]
	v_mfma_f32_16x16x32_bf16 v[42:45], v[158:161], v[192:195], v[42:45]
	v_mfma_f32_16x16x32_bf16 v[34:37], v[158:161], v[200:203], v[34:37]
	v_mfma_f32_16x16x32_bf16 v[34:37], v[162:165], v[204:207], v[34:37]
	v_mfma_f32_16x16x32_bf16 v[38:41], v[154:157], v[204:207], v[38:41]
	v_mfma_f32_16x16x32_bf16 v[38:41], v[150:153], v[200:203], v[38:41]
	s_barrier
	s_setprio 0
	s_mov_b32 m0, s17
	s_mov_b32 s46, s78
	s_mov_b32 s47, s79
	ds_read_b128 v[166:169], v242 offset:16384
	ds_read_b128 v[170:173], v242 offset:17408
	ds_read_b128 v[184:187], v242 offset:18432
	ds_read_b128 v[188:191], v242 offset:19456
	ds_read_b128 v[192:195], v242 offset:20480
	ds_read_b128 v[196:199], v242 offset:21504
	ds_read_b128 v[200:203], v242 offset:22528
	ds_read_b128 v[204:207], v242 offset:23552
	buffer_load_dwordx4 v179, s[44:47], s62 offen lds
	s_mov_b32 m0, s18
	s_add_i32 s64, s62, 0x158000
	buffer_load_dwordx4 v238, s[44:47], s62 offen lds
	s_mov_b32 m0, s19
	s_nop 0
	buffer_load_dwordx4 v179, s[44:47], s64 offen lds
	s_mov_b32 m0, s20
	s_nop 0
	buffer_load_dwordx4 v238, s[44:47], s64 offen lds
	s_mov_b32 m0, s16
	s_nop 0
	buffer_load_dwordx4 v178, s[76:79], s63 offen lds
	s_mov_b32 m0, s21
	s_nop 0
	buffer_load_dwordx4 v237, s[76:79], s63 offen lds
	s_waitcnt vmcnt(8)
	s_waitcnt lgkmcnt(0)
	s_setprio 1
	s_barrier
	v_mfma_f32_16x16x32_bf16 v[98:101], v[134:137], v[166:169], v[98:101]
	v_mfma_f32_16x16x32_bf16 v[94:97], v[142:145], v[166:169], v[94:97]
	v_mfma_f32_16x16x32_bf16 v[90:93], v[134:137], v[184:187], v[90:93]
	v_mfma_f32_16x16x32_bf16 v[86:89], v[142:145], v[184:187], v[86:89]
	v_mfma_f32_16x16x32_bf16 v[82:85], v[134:137], v[192:195], v[82:85]
	v_mfma_f32_16x16x32_bf16 v[76:79], v[142:145], v[192:195], v[78:81]
	v_mfma_f32_16x16x32_bf16 v[70:73], v[134:137], v[200:203], v[72:75]
	v_mfma_f32_16x16x32_bf16 v[66:69], v[142:145], v[200:203], v[66:69]
	v_mfma_f32_16x16x32_bf16 v[98:101], v[138:141], v[170:173], v[98:101]
	v_mfma_f32_16x16x32_bf16 v[94:97], v[146:149], v[170:173], v[94:97]
	v_mfma_f32_16x16x32_bf16 v[90:93], v[138:141], v[188:191], v[90:93]
	v_mfma_f32_16x16x32_bf16 v[86:89], v[146:149], v[188:191], v[86:89]
	v_mfma_f32_16x16x32_bf16 v[82:85], v[138:141], v[196:199], v[82:85]
	v_mfma_f32_16x16x32_bf16 v[76:79], v[146:149], v[196:199], v[76:79]
	v_mfma_f32_16x16x32_bf16 v[70:73], v[138:141], v[204:207], v[70:73]
	v_mfma_f32_16x16x32_bf16 v[66:69], v[146:149], v[204:207], v[66:69]
	v_mfma_f32_16x16x32_bf16 v[30:33], v[150:153], v[166:169], v[30:33]
	v_mfma_f32_16x16x32_bf16 v[26:29], v[158:161], v[166:169], v[26:29]
	v_mfma_f32_16x16x32_bf16 v[22:25], v[150:153], v[184:187], v[22:25]
	v_mfma_f32_16x16x32_bf16 v[18:21], v[158:161], v[184:187], v[18:21]
	v_mfma_f32_16x16x32_bf16 v[14:17], v[150:153], v[192:195], v[14:17]
	v_mfma_f32_16x16x32_bf16 v[10:13], v[158:161], v[192:195], v[10:13]
	v_mfma_f32_16x16x32_bf16 v[6:9], v[150:153], v[200:203], v[6:9]
	v_mfma_f32_16x16x32_bf16 v[2:5], v[158:161], v[200:203], v[2:5]
	v_mfma_f32_16x16x32_bf16 v[30:33], v[154:157], v[170:173], v[30:33]
	v_mfma_f32_16x16x32_bf16 v[26:29], v[162:165], v[170:173], v[26:29]
	v_mfma_f32_16x16x32_bf16 v[22:25], v[154:157], v[188:191], v[22:25]
	v_mfma_f32_16x16x32_bf16 v[18:21], v[162:165], v[188:191], v[18:21]
	v_mfma_f32_16x16x32_bf16 v[14:17], v[154:157], v[196:199], v[14:17]
	v_mfma_f32_16x16x32_bf16 v[10:13], v[162:165], v[196:199], v[10:13]
	v_mfma_f32_16x16x32_bf16 v[6:9], v[154:157], v[204:207], v[6:9]
	v_mfma_f32_16x16x32_bf16 v[2:5], v[162:165], v[204:207], v[2:5]
	s_barrier
; #define PG8_STAGEX(rs, bufoff, soff, voff) do { _Pragma("unroll") for (int _i = 0; _i < 2; ++_i) \
;         __builtin_amdgcn_raw_ptr_buffer_load_lds(rs, (LAS unsigned*)(lds + (bufoff) + ldsw + _i * 8192), 16, (voff)[_i], (soff), 0, 0); } while (0)
; #define PG8_LDA(dst, b, h) do { _Pragma("unroll") for (int m = 0; m < 4; ++m) _Pragma("unroll") for (int k = 0; k < 2; ++k) dst[m][k] = *(const LAS bf16x8*)(lds + PG8_SA(b, h) + aoff + m * 2048 + k * 1024); } while (0)
; #define PG8_LDB(dst, b, h) do { _Pragma("unroll") for (int n = 0; n < 2; ++n) _Pragma("unroll") for (int k = 0; k < 2; ++k) dst[n][k] = *(const LAS bf16x8*)(lds + PG8_SB(b, h) + boff + n * 2048 + k * 1024); } while (0)
; #define PG8_WAIT_V(n) asm volatile("s_waitcnt vmcnt(" #n ")" ::: "memory")
; #define PG8_WAIT_L(n) asm volatile("s_waitcnt lgkmcnt(" #n ")" ::: "memory")
; #define PG8_BAR __builtin_amdgcn_s_barrier()
; #define PG8_SCHED __builtin_amdgcn_sched_barrier(0)
;     ...
;             PG8_LDB(B0, 1, 0); PG8_LDB(B1, 1, 1); PG8_SCHED; PG8_LDA(At, 1, 0); PG8_STAGEX(rsA, PG8_SA(0, 1), a2 + hstepA, voffA);
;             PG8_WAIT_V(8); PG8_WAIT_L(0); PG8_BAR; PG8_MMA(0, 0, At, B0); PG8_MMA(0, 1, At, B1); PG8_BAR; PG8_SCHED;
;             PG8_LDA(At, 1, 1); PG8_STAGEX(rsB, PG8_SB(1, 0), b3, voffB); PG8_STAGEX(rsB, PG8_SB(1, 1), b3 + hstepB, voffB); PG8_STAGEX(rsA, PG8_SA(1, 0), a3, voffA);
;             PG8_WAIT_V(8); PG8_WAIT_L(0); PG8_BAR; PG8_MMA(1, 0, At, B0); PG8_MMA(1, 1, At, B1); PG8_BAR; PG8_SCHED;
;     ...
;         }
;         if (wr == 0) PG8_BAR;
	s_setprio 0
	v_add_u32_e32 v74, 0x18000, v241
	ds_read_b128 v[134:137], v74
	ds_read_b128 v[138:141], v74 offset:1024
	ds_read_b128 v[142:145], v74 offset:2048
	ds_read_b128 v[146:149], v74 offset:3072
	v_add_u32_e32 v74, 0x1c000, v241
	ds_read_b128 v[150:153], v74
	ds_read_b128 v[154:157], v74 offset:1024
	ds_read_b128 v[158:161], v74 offset:2048
	ds_read_b128 v[162:165], v74 offset:3072
	s_add_i32 s63, s63, 0x158000
	s_mov_b32 m0, s22
	ds_read_b128 v[166:169], v242 offset:32768
	ds_read_b128 v[170:173], v242 offset:33792
	ds_read_b128 v[184:187], v242 offset:34816
	ds_read_b128 v[188:191], v242 offset:35840
	ds_read_b128 v[192:195], v242 offset:36864
	ds_read_b128 v[196:199], v242 offset:37888
	ds_read_b128 v[200:203], v242 offset:38912
	ds_read_b128 v[204:207], v242 offset:39936
	buffer_load_dwordx4 v178, s[76:79], s63 offen lds
	s_mov_b32 m0, s23
	s_nop 0
	buffer_load_dwordx4 v237, s[76:79], s63 offen lds
	s_waitcnt vmcnt(8)
	s_waitcnt lgkmcnt(0)
	s_setprio 1
	s_barrier
	v_mfma_f32_16x16x32_bf16 v[130:133], v[134:137], v[166:169], v[130:133]
	v_mfma_f32_16x16x32_bf16 v[130:133], v[138:141], v[170:173], v[130:133]
	v_mfma_f32_16x16x32_bf16 v[126:129], v[146:149], v[170:173], v[126:129]
	v_mfma_f32_16x16x32_bf16 v[126:129], v[142:145], v[166:169], v[126:129]
	v_mfma_f32_16x16x32_bf16 v[118:121], v[142:145], v[184:187], v[118:121]
	v_mfma_f32_16x16x32_bf16 v[118:121], v[146:149], v[188:191], v[118:121]
	v_mfma_f32_16x16x32_bf16 v[122:125], v[138:141], v[188:191], v[122:125]
	v_mfma_f32_16x16x32_bf16 v[122:125], v[134:137], v[184:187], v[122:125]
	v_mfma_f32_16x16x32_bf16 v[114:117], v[134:137], v[192:195], v[114:117]
	v_mfma_f32_16x16x32_bf16 v[114:117], v[138:141], v[196:199], v[114:117]
	v_mfma_f32_16x16x32_bf16 v[110:113], v[146:149], v[196:199], v[110:113]
	v_mfma_f32_16x16x32_bf16 v[110:113], v[142:145], v[192:195], v[110:113]
	v_mfma_f32_16x16x32_bf16 v[102:105], v[142:145], v[200:203], v[102:105]
	v_mfma_f32_16x16x32_bf16 v[102:105], v[146:149], v[204:207], v[102:105]
	v_mfma_f32_16x16x32_bf16 v[106:109], v[138:141], v[204:207], v[106:109]
	v_mfma_f32_16x16x32_bf16 v[106:109], v[134:137], v[200:203], v[106:109]
	v_mfma_f32_16x16x32_bf16 v[62:65], v[150:153], v[166:169], v[62:65]
	v_mfma_f32_16x16x32_bf16 v[62:65], v[154:157], v[170:173], v[62:65]
	v_mfma_f32_16x16x32_bf16 v[58:61], v[162:165], v[170:173], v[58:61]
	v_mfma_f32_16x16x32_bf16 v[58:61], v[158:161], v[166:169], v[58:61]
	v_mfma_f32_16x16x32_bf16 v[50:53], v[158:161], v[184:187], v[50:53]
	v_mfma_f32_16x16x32_bf16 v[50:53], v[162:165], v[188:191], v[50:53]
	v_mfma_f32_16x16x32_bf16 v[54:57], v[154:157], v[188:191], v[54:57]
	v_mfma_f32_16x16x32_bf16 v[54:57], v[150:153], v[184:187], v[54:57]
	v_mfma_f32_16x16x32_bf16 v[46:49], v[150:153], v[192:195], v[46:49]
	v_mfma_f32_16x16x32_bf16 v[46:49], v[154:157], v[196:199], v[46:49]
	v_mfma_f32_16x16x32_bf16 v[42:45], v[162:165], v[196:199], v[42:45]
	v_mfma_f32_16x16x32_bf16 v[42:45], v[158:161], v[192:195], v[42:45]
	v_mfma_f32_16x16x32_bf16 v[34:37], v[158:161], v[200:203], v[34:37]
	v_mfma_f32_16x16x32_bf16 v[34:37], v[162:165], v[204:207], v[34:37]
	v_mfma_f32_16x16x32_bf16 v[38:41], v[154:157], v[204:207], v[38:41]
	v_mfma_f32_16x16x32_bf16 v[38:41], v[150:153], v[200:203], v[38:41]
	s_barrier
	s_setprio 0
	s_mov_b32 m0, s54
	s_or_b32 s63, s62, 0x80
	ds_read_b128 v[166:169], v242 offset:49152
	ds_read_b128 v[170:173], v242 offset:50176
	ds_read_b128 v[184:187], v242 offset:51200
	ds_read_b128 v[188:191], v242 offset:52224
	ds_read_b128 v[192:195], v242 offset:53248
	ds_read_b128 v[196:199], v242 offset:54272
	ds_read_b128 v[200:203], v242 offset:55296
	ds_read_b128 v[204:207], v242 offset:56320
	buffer_load_dwordx4 v179, s[44:47], s63 offen lds
	s_mov_b32 m0, s55
	s_add_i32 s62, s62, 0x158080
	buffer_load_dwordx4 v238, s[44:47], s63 offen lds
	s_mov_b32 m0, s70
	s_nop 0
	buffer_load_dwordx4 v179, s[44:47], s62 offen lds
	s_mov_b32 m0, s71
	s_nop 0
	buffer_load_dwordx4 v238, s[44:47], s62 offen lds
	s_mov_b32 m0, s68
	s_nop 0
	buffer_load_dwordx4 v178, s[76:79], s61 offen lds
	s_mov_b32 m0, s69
	s_nop 0
	buffer_load_dwordx4 v237, s[76:79], s61 offen lds
	s_waitcnt vmcnt(8)
	s_waitcnt lgkmcnt(0)
	s_setprio 1
	s_barrier
	v_mfma_f32_16x16x32_bf16 v[98:101], v[134:137], v[166:169], v[98:101]
	v_mfma_f32_16x16x32_bf16 v[94:97], v[142:145], v[166:169], v[94:97]
	v_mfma_f32_16x16x32_bf16 v[90:93], v[134:137], v[184:187], v[90:93]
	v_mfma_f32_16x16x32_bf16 v[86:89], v[142:145], v[184:187], v[86:89]
	v_mfma_f32_16x16x32_bf16 v[80:83], v[134:137], v[192:195], v[82:85]
	v_mfma_f32_16x16x32_bf16 v[74:77], v[142:145], v[192:195], v[76:79]
	v_mfma_f32_16x16x32_bf16 v[70:73], v[134:137], v[200:203], v[70:73]
	v_mfma_f32_16x16x32_bf16 v[66:69], v[142:145], v[200:203], v[66:69]
	v_mfma_f32_16x16x32_bf16 v[98:101], v[138:141], v[170:173], v[98:101]
	v_mfma_f32_16x16x32_bf16 v[94:97], v[146:149], v[170:173], v[94:97]
	v_mfma_f32_16x16x32_bf16 v[90:93], v[138:141], v[188:191], v[90:93]
	v_mfma_f32_16x16x32_bf16 v[86:89], v[146:149], v[188:191], v[86:89]
	v_mfma_f32_16x16x32_bf16 v[82:85], v[138:141], v[196:199], v[80:83]
	v_mfma_f32_16x16x32_bf16 v[78:81], v[146:149], v[196:199], v[74:77]
	v_mfma_f32_16x16x32_bf16 v[72:75], v[138:141], v[204:207], v[70:73]
	v_mfma_f32_16x16x32_bf16 v[66:69], v[146:149], v[204:207], v[66:69]
	v_mfma_f32_16x16x32_bf16 v[30:33], v[150:153], v[166:169], v[30:33]
	v_mfma_f32_16x16x32_bf16 v[26:29], v[158:161], v[166:169], v[26:29]
	v_mfma_f32_16x16x32_bf16 v[22:25], v[150:153], v[184:187], v[22:25]
	v_mfma_f32_16x16x32_bf16 v[18:21], v[158:161], v[184:187], v[18:21]
	v_mfma_f32_16x16x32_bf16 v[14:17], v[150:153], v[192:195], v[14:17]
	v_mfma_f32_16x16x32_bf16 v[10:13], v[158:161], v[192:195], v[10:13]
	v_mfma_f32_16x16x32_bf16 v[6:9], v[150:153], v[200:203], v[6:9]
	v_mfma_f32_16x16x32_bf16 v[2:5], v[158:161], v[200:203], v[2:5]
	v_mfma_f32_16x16x32_bf16 v[30:33], v[154:157], v[170:173], v[30:33]
	v_mfma_f32_16x16x32_bf16 v[26:29], v[162:165], v[170:173], v[26:29]
	v_mfma_f32_16x16x32_bf16 v[22:25], v[154:157], v[188:191], v[22:25]
	v_mfma_f32_16x16x32_bf16 v[18:21], v[162:165], v[188:191], v[18:21]
	v_mfma_f32_16x16x32_bf16 v[14:17], v[154:157], v[196:199], v[14:17]
	v_mfma_f32_16x16x32_bf16 v[10:13], v[162:165], v[196:199], v[10:13]
	v_mfma_f32_16x16x32_bf16 v[6:9], v[154:157], v[204:207], v[6:9]
	v_mfma_f32_16x16x32_bf16 v[2:5], v[162:165], v[204:207], v[2:5]
	s_barrier
	s_setprio 0
	s_add_i32 s60, s60, 2
	s_addk_i32 s40, 0x100
	s_addk_i32 s41, 0x100
	s_cmpk_gt_u32 s60, 0x53
	s_cbranch_scc0 .LBB0_1750
	s_and_b64 vcc, exec, s[50:51]
	s_cbranch_vccz .LBB0_1753
	s_barrier
